# combination on top of the previous best: RG-LRU gate math folded (bias/negate/log2e into one fma, clamp modifier instead of max), S5 pass-B inner loop trimmed (ds_write2 pairs, packed gelu cvt, runnin
# speedup vs baseline: 1.0185x; 1.0120x over previous
; #define PG8_STAGE(bufoff, gbase, voff) do { _Pragma("unroll") for (int _i = 0; _i < 2; ++_i) \
;         __builtin_amdgcn_global_load_lds((const unsigned*)((const char*)(gbase) + (voff)[_i]), (LAS unsigned*)(lds + (bufoff) + ldsw + _i * 8192), 16, 0, 0); } while (0)
; #define PG8_LDA(dst, b, h) do { _Pragma("unroll") for (int m = 0; m < 4; ++m) _Pragma("unroll") for (int k = 0; k < 2; ++k) dst[m][k] = *(const LAS bf16x8*)(lds + PG8_SA(b, h) + aoff + m * 2048 + k * 1024); } while (0)
; #define PG8_LDB(dst, b, h) do { _Pragma("unroll") for (int n = 0; n < 2; ++n) _Pragma("unroll") for (int k = 0; k < 2; ++k) dst[n][k] = *(const LAS bf16x8*)(lds + PG8_SB(b, h) + boff + n * 2048 + k * 1024); } while (0)
; #define PG8_MMA(ai, bj, At, Bt) do { __builtin_amdgcn_s_setprio(1); _Pragma("unroll") for (int m = 0; m < 4; ++m) _Pragma("unroll") for (int n = 0; n < 2; ++n) _Pragma("unroll") for (int k = 0; k < 2; ++k) \
;         acc[ai][bj][m][n] = __builtin_amdgcn_mfma_f32_16x16x32_bf16(Bt[n][k], At[m][k], acc[ai][bj][m][n], 0, 0, 0); __builtin_amdgcn_s_setprio(0); } while (0)
; #define PG8_WAIT_V(n) asm volatile("s_waitcnt vmcnt(" #n ")" ::: "memory")
; #define PG8_WAIT_L(n) asm volatile("s_waitcnt lgkmcnt(" #n ")" ::: "memory")
; #define PG8_BAR __builtin_amdgcn_s_barrier()
; #define PG8_SCHED __builtin_amdgcn_sched_barrier(0)
; template <class Epi, bool ALIGN_EPI = true, bool SP2 = true>
; __device__ __forceinline__ void gemm_phase(LAS unsigned char* lds, const Gemm g, const StaticOrder& S, const Epi& E) {
;     ...
;     f32x4 acc[2][2][4][2];
; #pragma unroll
;     for (int a = 0; a < 2; ++a)
; #pragma unroll
;         for (int b = 0; b < 2; ++b)
; #pragma unroll
;             for (int m = 0; m < 4; ++m)
; #pragma unroll
;                 for (int n = 0; n < 2; ++n) acc[a][b][m][n] = (f32x4){0.f, 0.f, 0.f, 0.f};
;     ...
;             PG8_LDB(B0, 0, 0); PG8_LDB(B1, 0, 1); PG8_SCHED; PG8_LDA(At, 0, 0); PG8_STAGE(PG8_SA(1, 1), a1 + hstepA, voffA);
;             PG8_WAIT_V(8); PG8_WAIT_L(0); PG8_BAR; PG8_MMA(0, 0, At, B0); PG8_MMA(0, 1, At, B1); PG8_BAR; PG8_SCHED;
;             PG8_LDA(At, 0, 1); PG8_STAGE(PG8_SB(0, 0), b2, voffB); PG8_STAGE(PG8_SB(0, 1), b2 + hstepB, voffB); PG8_STAGE(PG8_SA(0, 0), a2, voffA);
;             PG8_WAIT_V(8); PG8_WAIT_L(0); PG8_BAR; PG8_MMA(1, 0, At, B0); PG8_MMA(1, 1, At, B1); PG8_BAR; PG8_SCHED;
.LBB0_247:
	s_ashr_i32 s61, s60, 31
	s_lshl_b64 s[62:63], s[60:61], 19
	s_add_u32 s62, s87, s62
	s_addc_u32 s63, s91, s63
	s_and_b64 s[64:65], s[4:5], exec
	s_cselect_b32 s61, s63, s75
	s_cselect_b32 s67, s62, s74
	s_ashr_i32 s71, s70, 31
	s_ashr_i32 s81, s80, 31
	s_lshl_b64 s[64:65], s[70:71], 19
	s_lshl_b64 s[72:73], s[80:81], 19
	s_add_u32 s68, s20, s72
	s_addc_u32 s69, s21, s73
	v_readlane_b32 s8, v248, 14
	s_add_u32 s71, s8, s72
	v_readlane_b32 s8, v248, 15
	s_addc_u32 s72, s8, s73
	s_add_u32 s73, s78, s64
	s_addc_u32 vcc_lo, s79, s65
	s_add_u32 vcc_hi, s74, 0x100
	v_mov_b32_e32 v0, 0
	s_addc_u32 s89, s75, 0
	s_mov_b32 s8, -2
	s_mov_b64 s[74:75], 0
	v_lshl_add_u64 v[148:149], v[140:141], 0, s[64:65]
	v_lshl_add_u64 v[150:151], v[142:143], 0, s[64:65]
	s_add_i32 s93, s8, 2
	s_add_u32 s10, s73, s74
	s_addc_u32 s11, vcc_lo, s75
	s_add_u32 s10, s10, 0x2000100
	s_addc_u32 s11, s11, 0
	s_add_u32 s80, s78, s74
	s_addc_u32 s81, s79, s75
	s_add_u32 s82, s80, 0x2000180
	s_addc_u32 s83, s81, 0
	s_add_i32 s8, s8, -11
	ds_read_b128 v[152:155], v163
	ds_read_b128 v[156:159], v163 offset:1024
	ds_read_b128 v[172:175], v163 offset:2048
	ds_read_b128 v[176:179], v163 offset:3072
	ds_read_b128 v[180:183], v164
	ds_read_b128 v[184:187], v164 offset:1024
	ds_read_b128 v[188:191], v164 offset:2048
	ds_read_b128 v[192:195], v164 offset:3072
	s_lshl_b64 s[80:81], s[8:9], 7
	s_add_u32 s8, s20, s80
	s_addc_u32 s80, s21, s81
	s_cmp_lt_u32 s93, 13
	s_cselect_b32 s8, s82, s8
	s_cselect_b32 s80, s83, s80
	s_add_u32 s8, s8, s64
	s_addc_u32 s80, s80, s65
	s_add_u32 s82, vcc_hi, s74
	s_addc_u32 s83, s89, s75
	s_cmpk_eq_i32 s74, 0x700
	s_cselect_b32 s85, s69, s11
	s_cselect_b32 s84, s68, s10
	s_cselect_b32 s81, s72, s80
	s_cselect_b32 s80, s71, s8
	s_cselect_b32 s83, s61, s83
	s_cselect_b32 s82, s67, s82
	v_lshl_add_u64 v[160:161], v[148:149], 0, s[74:75]
	s_add_i32 m0, s97, 0xc000
	ds_read_b128 v[196:199], v165
	ds_read_b128 v[200:203], v165 offset:1024
	ds_read_b128 v[204:207], v165 offset:2048
	ds_read_b128 v[208:211], v165 offset:3072
	ds_read_b128 v[212:215], v165 offset:4096
	ds_read_b128 v[216:219], v165 offset:5120
	ds_read_b128 v[220:223], v165 offset:6144
	ds_read_b128 v[228:231], v165 offset:7168
	global_load_lds_dwordx4 v[160:161], off
	v_lshl_add_u64 v[160:161], v[150:151], 0, s[74:75]
	s_add_i32 m0, s97, 0xe000
	s_nop 0
	global_load_lds_dwordx4 v[160:161], off
	s_waitcnt vmcnt(8)
	s_waitcnt lgkmcnt(0)
	s_barrier
	s_setprio 1
	s_waitcnt lgkmcnt(0)
	v_mfma_f32_16x16x32_bf16 v[124:127], v[152:155], v[196:199], 0
	v_mfma_f32_16x16x32_bf16 v[120:123], v[172:175], v[196:199], 0
	v_mfma_f32_16x16x32_bf16 v[108:111], v[152:155], v[204:207], 0
	v_mfma_f32_16x16x32_bf16 v[104:107], v[172:175], v[204:207], 0
	v_mfma_f32_16x16x32_bf16 v[92:95], v[152:155], v[212:215], 0
	v_mfma_f32_16x16x32_bf16 v[88:91], v[172:175], v[212:215], 0
	v_mfma_f32_16x16x32_bf16 v[76:79], v[152:155], v[220:223], 0
	v_mfma_f32_16x16x32_bf16 v[72:75], v[172:175], v[220:223], 0
	v_mfma_f32_16x16x32_bf16 v[124:127], v[156:159], v[200:203], v[124:127]
	v_mfma_f32_16x16x32_bf16 v[120:123], v[176:179], v[200:203], v[120:123]
	v_mfma_f32_16x16x32_bf16 v[108:111], v[156:159], v[208:211], v[108:111]
	v_mfma_f32_16x16x32_bf16 v[104:107], v[176:179], v[208:211], v[104:107]
	v_mfma_f32_16x16x32_bf16 v[92:95], v[156:159], v[216:219], v[92:95]
	v_mfma_f32_16x16x32_bf16 v[88:91], v[176:179], v[216:219], v[88:91]
	v_mfma_f32_16x16x32_bf16 v[76:79], v[156:159], v[228:231], v[76:79]
	v_mfma_f32_16x16x32_bf16 v[72:75], v[176:179], v[228:231], v[72:75]
	s_setprio 0
	s_setprio 1
	v_mfma_f32_16x16x32_bf16 v[116:119], v[180:183], v[196:199], 0
	v_mfma_f32_16x16x32_bf16 v[112:115], v[188:191], v[196:199], 0
	v_mfma_f32_16x16x32_bf16 v[100:103], v[180:183], v[204:207], 0
	v_mfma_f32_16x16x32_bf16 v[96:99], v[188:191], v[204:207], 0
	v_mfma_f32_16x16x32_bf16 v[84:87], v[180:183], v[212:215], 0
	v_mfma_f32_16x16x32_bf16 v[80:83], v[188:191], v[212:215], 0
	v_mfma_f32_16x16x32_bf16 v[68:71], v[180:183], v[220:223], 0
	v_mfma_f32_16x16x32_bf16 v[64:67], v[188:191], v[220:223], 0
	v_mfma_f32_16x16x32_bf16 v[116:119], v[184:187], v[200:203], v[116:119]
	v_mfma_f32_16x16x32_bf16 v[112:115], v[192:195], v[200:203], v[112:115]
	v_mfma_f32_16x16x32_bf16 v[100:103], v[184:187], v[208:211], v[100:103]
	v_mfma_f32_16x16x32_bf16 v[96:99], v[192:195], v[208:211], v[96:99]
	v_mfma_f32_16x16x32_bf16 v[84:87], v[184:187], v[216:219], v[84:87]
	v_mfma_f32_16x16x32_bf16 v[80:83], v[192:195], v[216:219], v[80:83]
	v_mfma_f32_16x16x32_bf16 v[68:71], v[184:187], v[228:231], v[68:71]
	v_mfma_f32_16x16x32_bf16 v[64:67], v[192:195], v[228:231], v[64:67]
	s_setprio 0
	s_barrier
	s_add_i32 s8, s96, s92
	v_lshl_add_u64 v[160:161], s[82:83], 0, v[130:131]
	s_mov_b32 m0, s8
	ds_read_b128 v[196:199], v165 offset:16384
	ds_read_b128 v[200:203], v165 offset:17408
	ds_read_b128 v[204:207], v165 offset:18432
	ds_read_b128 v[208:211], v165 offset:19456
	ds_read_b128 v[212:215], v165 offset:20480
	ds_read_b128 v[216:219], v165 offset:21504
	ds_read_b128 v[220:223], v165 offset:22528
	ds_read_b128 v[228:231], v165 offset:23552
	global_load_lds_dwordx4 v[160:161], off
	s_add_i32 m0, s8, 0x2000
	s_add_u32 s10, s82, 0x40000
	v_lshl_add_u64 v[224:225], s[82:83], 0, v[134:135]
	s_addc_u32 s11, s83, 0
	s_add_i32 s8, s95, s92
	global_load_lds_dwordx4 v[224:225], off
	v_lshl_add_u64 v[232:233], s[10:11], 0, v[130:131]
	s_mov_b32 m0, s8
	s_nop 0
	global_load_lds_dwordx4 v[232:233], off
	v_lshl_add_u64 v[232:233], s[10:11], 0, v[134:135]
	s_add_i32 m0, s8, 0x2000
	s_nop 0
	global_load_lds_dwordx4 v[232:233], off
	v_lshl_add_u64 v[232:233], s[84:85], 0, v[128:129]
	s_mov_b32 m0, s97
	s_nop 0
	global_load_lds_dwordx4 v[232:233], off
	v_lshl_add_u64 v[232:233], s[84:85], 0, v[132:133]
	s_mov_b32 m0, s86
	s_nop 0
	global_load_lds_dwordx4 v[232:233], off
	s_waitcnt vmcnt(8)
	s_waitcnt lgkmcnt(0)
	s_barrier
; #define PG8_STAGE(bufoff, gbase, voff) do { _Pragma("unroll") for (int _i = 0; _i < 2; ++_i) \
;         __builtin_amdgcn_global_load_lds((const unsigned*)((const char*)(gbase) + (voff)[_i]), (LAS unsigned*)(lds + (bufoff) + ldsw + _i * 8192), 16, 0, 0); } while (0)
; #define PG8_LDA(dst, b, h) do { _Pragma("unroll") for (int m = 0; m < 4; ++m) _Pragma("unroll") for (int k = 0; k < 2; ++k) dst[m][k] = *(const LAS bf16x8*)(lds + PG8_SA(b, h) + aoff + m * 2048 + k * 1024); } while (0)
; #define PG8_LDB(dst, b, h) do { _Pragma("unroll") for (int n = 0; n < 2; ++n) _Pragma("unroll") for (int k = 0; k < 2; ++k) dst[n][k] = *(const LAS bf16x8*)(lds + PG8_SB(b, h) + boff + n * 2048 + k * 1024); } while (0)
; #define PG8_MMA(ai, bj, At, Bt) do { __builtin_amdgcn_s_setprio(1); _Pragma("unroll") for (int m = 0; m < 4; ++m) _Pragma("unroll") for (int n = 0; n < 2; ++n) _Pragma("unroll") for (int k = 0; k < 2; ++k) \
;         acc[ai][bj][m][n] = __builtin_amdgcn_mfma_f32_16x16x32_bf16(Bt[n][k], At[m][k], acc[ai][bj][m][n], 0, 0, 0); __builtin_amdgcn_s_setprio(0); } while (0)
; #define PG8_WAIT_V(n) asm volatile("s_waitcnt vmcnt(" #n ")" ::: "memory")
; #define PG8_WAIT_L(n) asm volatile("s_waitcnt lgkmcnt(" #n ")" ::: "memory")
; #define PG8_BAR __builtin_amdgcn_s_barrier()
; #define PG8_SCHED __builtin_amdgcn_sched_barrier(0)
; template <class Epi, bool ALIGN_EPI = true, bool SP2 = true>
; __device__ __forceinline__ void gemm_phase(LAS unsigned char* lds, const Gemm g, const StaticOrder& S, const Epi& E) {
;     ...
;             PG8_WAIT_V(8); PG8_WAIT_L(0); PG8_BAR; PG8_MMA(1, 0, At, B0); PG8_MMA(1, 1, At, B1); PG8_BAR; PG8_SCHED;
;             PG8_LDB(B0, 1, 0); PG8_LDB(B1, 1, 1); PG8_SCHED; PG8_LDA(At, 1, 0); PG8_STAGE(PG8_SA(0, 1), a2 + hstepA, voffA);
;             PG8_WAIT_V(8); PG8_WAIT_L(0); PG8_BAR; PG8_MMA(0, 0, At, B0); PG8_MMA(0, 1, At, B1); PG8_BAR; PG8_SCHED;
	s_setprio 1
	s_waitcnt lgkmcnt(0)
	v_mfma_f32_16x16x32_bf16 v[60:63], v[152:155], v[196:199], 0
	v_mfma_f32_16x16x32_bf16 v[56:59], v[172:175], v[196:199], 0
	v_mfma_f32_16x16x32_bf16 v[44:47], v[152:155], v[204:207], 0
	v_mfma_f32_16x16x32_bf16 v[40:43], v[172:175], v[204:207], 0
	v_mfma_f32_16x16x32_bf16 v[28:31], v[152:155], v[212:215], 0
	v_mfma_f32_16x16x32_bf16 v[24:27], v[172:175], v[212:215], 0
	v_mfma_f32_16x16x32_bf16 v[12:15], v[152:155], v[220:223], 0
	v_mfma_f32_16x16x32_bf16 v[8:11], v[172:175], v[220:223], 0
	v_mfma_f32_16x16x32_bf16 v[60:63], v[156:159], v[200:203], v[60:63]
	v_mfma_f32_16x16x32_bf16 v[56:59], v[176:179], v[200:203], v[56:59]
	v_mfma_f32_16x16x32_bf16 v[44:47], v[156:159], v[208:211], v[44:47]
	v_mfma_f32_16x16x32_bf16 v[40:43], v[176:179], v[208:211], v[40:43]
	v_mfma_f32_16x16x32_bf16 v[28:31], v[156:159], v[216:219], v[28:31]
	v_mfma_f32_16x16x32_bf16 v[24:27], v[176:179], v[216:219], v[24:27]
	v_mfma_f32_16x16x32_bf16 v[12:15], v[156:159], v[228:231], v[12:15]
	v_mfma_f32_16x16x32_bf16 v[8:11], v[176:179], v[228:231], v[8:11]
	s_setprio 0
	s_setprio 1
	v_mfma_f32_16x16x32_bf16 v[52:55], v[180:183], v[196:199], 0
	v_mfma_f32_16x16x32_bf16 v[48:51], v[188:191], v[196:199], 0
	v_mfma_f32_16x16x32_bf16 v[36:39], v[180:183], v[204:207], 0
	v_mfma_f32_16x16x32_bf16 v[32:35], v[188:191], v[204:207], 0
	v_mfma_f32_16x16x32_bf16 v[20:23], v[180:183], v[212:215], 0
	v_mfma_f32_16x16x32_bf16 v[16:19], v[188:191], v[212:215], 0
	v_mfma_f32_16x16x32_bf16 v[4:7], v[180:183], v[220:223], 0
	v_mfma_f32_16x16x32_bf16 v[0:3], v[188:191], v[220:223], 0
	v_mfma_f32_16x16x32_bf16 v[52:55], v[184:187], v[200:203], v[52:55]
	v_mfma_f32_16x16x32_bf16 v[48:51], v[192:195], v[200:203], v[48:51]
	v_mfma_f32_16x16x32_bf16 v[36:39], v[184:187], v[208:211], v[36:39]
	v_mfma_f32_16x16x32_bf16 v[32:35], v[192:195], v[208:211], v[32:35]
	v_mfma_f32_16x16x32_bf16 v[20:23], v[184:187], v[216:219], v[20:23]
	v_mfma_f32_16x16x32_bf16 v[16:19], v[192:195], v[216:219], v[16:19]
	v_mfma_f32_16x16x32_bf16 v[4:7], v[184:187], v[228:231], v[4:7]
	v_mfma_f32_16x16x32_bf16 v[0:3], v[192:195], v[228:231], v[0:3]
	s_setprio 0
	s_barrier
	s_add_i32 s8, 0, 0x18000
	v_add_u32_e32 v136, s8, v162
	s_add_i32 s94, 0, 0x1c000
	ds_read_b128 v[152:155], v136
	ds_read_b128 v[156:159], v136 offset:1024
	ds_read_b128 v[172:175], v136 offset:2048
	ds_read_b128 v[176:179], v136 offset:3072
	v_add_u32_e32 v136, s94, v162
	ds_read_b128 v[180:183], v136
	ds_read_b128 v[184:187], v136 offset:1024
	ds_read_b128 v[188:191], v136 offset:2048
	ds_read_b128 v[192:195], v136 offset:3072
	s_add_u32 s10, s84, 0x40000
	s_addc_u32 s11, s85, 0
	s_mov_b32 m0, s88
	v_lshl_add_u64 v[232:233], s[10:11], 0, v[128:129]
	ds_read_b128 v[196:199], v165 offset:32768
	ds_read_b128 v[200:203], v165 offset:33792
	ds_read_b128 v[204:207], v165 offset:34816
	ds_read_b128 v[208:211], v165 offset:35840
	ds_read_b128 v[212:215], v165 offset:36864
	ds_read_b128 v[216:219], v165 offset:37888
	ds_read_b128 v[220:223], v165 offset:38912
	ds_read_b128 v[228:231], v165 offset:39936
	global_load_lds_dwordx4 v[232:233], off
	v_lshl_add_u64 v[232:233], s[10:11], 0, v[132:133]
	s_mov_b32 m0, s38
	s_nop 0
	global_load_lds_dwordx4 v[232:233], off
	s_waitcnt vmcnt(8)
	s_waitcnt lgkmcnt(0)
	s_barrier
	s_setprio 1
	s_waitcnt lgkmcnt(0)
	v_mfma_f32_16x16x32_bf16 v[124:127], v[152:155], v[196:199], v[124:127]
	v_mfma_f32_16x16x32_bf16 v[120:123], v[172:175], v[196:199], v[120:123]
	v_mfma_f32_16x16x32_bf16 v[108:111], v[152:155], v[204:207], v[108:111]
	v_mfma_f32_16x16x32_bf16 v[104:107], v[172:175], v[204:207], v[104:107]
	v_mfma_f32_16x16x32_bf16 v[92:95], v[152:155], v[212:215], v[92:95]
	v_mfma_f32_16x16x32_bf16 v[88:91], v[172:175], v[212:215], v[88:91]
	v_mfma_f32_16x16x32_bf16 v[76:79], v[152:155], v[220:223], v[76:79]
	v_mfma_f32_16x16x32_bf16 v[72:75], v[172:175], v[220:223], v[72:75]
	v_mfma_f32_16x16x32_bf16 v[124:127], v[156:159], v[200:203], v[124:127]
	v_mfma_f32_16x16x32_bf16 v[120:123], v[176:179], v[200:203], v[120:123]
	v_mfma_f32_16x16x32_bf16 v[108:111], v[156:159], v[208:211], v[108:111]
	v_mfma_f32_16x16x32_bf16 v[104:107], v[176:179], v[208:211], v[104:107]
	v_mfma_f32_16x16x32_bf16 v[92:95], v[156:159], v[216:219], v[92:95]
	v_mfma_f32_16x16x32_bf16 v[88:91], v[176:179], v[216:219], v[88:91]
	v_mfma_f32_16x16x32_bf16 v[76:79], v[156:159], v[228:231], v[76:79]
	v_mfma_f32_16x16x32_bf16 v[72:75], v[176:179], v[228:231], v[72:75]
	s_setprio 0
	s_setprio 1
	v_mfma_f32_16x16x32_bf16 v[116:119], v[180:183], v[196:199], v[116:119]
	v_mfma_f32_16x16x32_bf16 v[112:115], v[188:191], v[196:199], v[112:115]
	v_mfma_f32_16x16x32_bf16 v[100:103], v[180:183], v[204:207], v[100:103]
	v_mfma_f32_16x16x32_bf16 v[96:99], v[188:191], v[204:207], v[96:99]
	v_mfma_f32_16x16x32_bf16 v[84:87], v[180:183], v[212:215], v[84:87]
	v_mfma_f32_16x16x32_bf16 v[80:83], v[188:191], v[212:215], v[80:83]
	v_mfma_f32_16x16x32_bf16 v[68:71], v[180:183], v[220:223], v[68:71]
	v_mfma_f32_16x16x32_bf16 v[64:67], v[188:191], v[220:223], v[64:67]
	v_mfma_f32_16x16x32_bf16 v[116:119], v[184:187], v[200:203], v[116:119]
	v_mfma_f32_16x16x32_bf16 v[112:115], v[192:195], v[200:203], v[112:115]
	v_mfma_f32_16x16x32_bf16 v[100:103], v[184:187], v[208:211], v[100:103]
	v_mfma_f32_16x16x32_bf16 v[96:99], v[192:195], v[208:211], v[96:99]
	v_mfma_f32_16x16x32_bf16 v[84:87], v[184:187], v[216:219], v[84:87]
	v_mfma_f32_16x16x32_bf16 v[80:83], v[192:195], v[216:219], v[80:83]
	v_mfma_f32_16x16x32_bf16 v[68:71], v[184:187], v[228:231], v[68:71]
	v_mfma_f32_16x16x32_bf16 v[64:67], v[192:195], v[228:231], v[64:67]
	s_setprio 0
	s_barrier
; #define PG8_STAGE(bufoff, gbase, voff) do { _Pragma("unroll") for (int _i = 0; _i < 2; ++_i) \
;         __builtin_amdgcn_global_load_lds((const unsigned*)((const char*)(gbase) + (voff)[_i]), (LAS unsigned*)(lds + (bufoff) + ldsw + _i * 8192), 16, 0, 0); } while (0)
; #define PG8_LDA(dst, b, h) do { _Pragma("unroll") for (int m = 0; m < 4; ++m) _Pragma("unroll") for (int k = 0; k < 2; ++k) dst[m][k] = *(const LAS bf16x8*)(lds + PG8_SA(b, h) + aoff + m * 2048 + k * 1024); } while (0)
; #define PG8_LDB(dst, b, h) do { _Pragma("unroll") for (int n = 0; n < 2; ++n) _Pragma("unroll") for (int k = 0; k < 2; ++k) dst[n][k] = *(const LAS bf16x8*)(lds + PG8_SB(b, h) + boff + n * 2048 + k * 1024); } while (0)
; #define PG8_MMA(ai, bj, At, Bt) do { __builtin_amdgcn_s_setprio(1); _Pragma("unroll") for (int m = 0; m < 4; ++m) _Pragma("unroll") for (int n = 0; n < 2; ++n) _Pragma("unroll") for (int k = 0; k < 2; ++k) \
;         acc[ai][bj][m][n] = __builtin_amdgcn_mfma_f32_16x16x32_bf16(Bt[n][k], At[m][k], acc[ai][bj][m][n], 0, 0, 0); __builtin_amdgcn_s_setprio(0); } while (0)
; #define PG8_WAIT_V(n) asm volatile("s_waitcnt vmcnt(" #n ")" ::: "memory")
; template <class Epi, bool ALIGN_EPI = true, bool SP2 = true>
; __device__ __forceinline__ void gemm_phase(LAS unsigned char* lds, const Gemm g, const StaticOrder& S, const Epi& E) {
;     ...
;             PG8_LDB(B0, 0, 0); PG8_LDB(B1, 0, 1); PG8_SCHED; PG8_LDA(At, 0, 0); PG8_STAGE(PG8_SA(1, 1), a1 + hstepA, voffA);
;             PG8_WAIT_V(8); PG8_WAIT_L(0); PG8_BAR; PG8_MMA(0, 0, At, B0); PG8_MMA(0, 1, At, B1); PG8_BAR; PG8_SCHED;
;             PG8_LDA(At, 0, 1); PG8_STAGE(PG8_SB(0, 0), b2, voffB); PG8_STAGE(PG8_SB(0, 1), b2 + hstepB, voffB); PG8_STAGE(PG8_SA(0, 0), a2, voffA);
;             PG8_WAIT_V(8); PG8_WAIT_L(0); PG8_BAR; PG8_MMA(1, 0, At, B0); PG8_MMA(1, 1, At, B1); PG8_BAR; PG8_SCHED;
;             PG8_LDB(B0, 1, 0); PG8_LDB(B1, 1, 1); PG8_SCHED; PG8_LDA(At, 1, 0); PG8_STAGE(PG8_SA(0, 1), a2 + hstepA, voffA);
;             PG8_WAIT_V(8); PG8_WAIT_L(0); PG8_BAR; PG8_MMA(0, 0, At, B0); PG8_MMA(0, 1, At, B1); PG8_BAR; PG8_SCHED;
;             PG8_LDA(At, 1, 1); PG8_STAGE(PG8_SB(1, 0), b3, voffB); PG8_STAGE(PG8_SB(1, 1), b3 + hstepB, voffB); PG8_STAGE(PG8_SA(1, 0), a3, voffA);
;             PG8_WAIT_V(8); PG8_WAIT_L(0); PG8_BAR; PG8_MMA(1, 0, At, B0); PG8_MMA(1, 1, At, B1); PG8_BAR; PG8_SCHED;
	s_add_i32 s8, s8, s92
	v_lshl_add_u64 v[160:161], v[160:161], 0, s[14:15]
	s_mov_b32 m0, s8
	ds_read_b128 v[196:199], v165 offset:49152
	ds_read_b128 v[200:203], v165 offset:50176
	ds_read_b128 v[204:207], v165 offset:51200
	ds_read_b128 v[208:211], v165 offset:52224
	ds_read_b128 v[212:215], v165 offset:53248
	ds_read_b128 v[216:219], v165 offset:54272
	ds_read_b128 v[220:223], v165 offset:55296
	ds_read_b128 v[228:231], v165 offset:56320
	global_load_lds_dwordx4 v[160:161], off
	s_add_i32 m0, s8, 0x2000
	s_add_u32 s10, s82, 0x40080
	v_lshl_add_u64 v[160:161], v[224:225], 0, s[14:15]
	s_addc_u32 s11, s83, 0
	s_add_i32 s8, s94, s92
	global_load_lds_dwordx4 v[160:161], off
	v_lshl_add_u64 v[160:161], s[10:11], 0, v[130:131]
	s_mov_b32 m0, s8
	s_nop 0
	global_load_lds_dwordx4 v[160:161], off
	v_lshl_add_u64 v[160:161], s[10:11], 0, v[134:135]
	s_add_i32 m0, s8, 0x2000
	s_nop 0
	global_load_lds_dwordx4 v[160:161], off
	v_lshl_add_u64 v[160:161], s[80:81], 0, v[128:129]
	s_mov_b32 m0, s39
	s_nop 0
	global_load_lds_dwordx4 v[160:161], off
	v_lshl_add_u64 v[160:161], s[80:81], 0, v[132:133]
	s_mov_b32 m0, s90
	s_nop 0
	global_load_lds_dwordx4 v[160:161], off
	s_waitcnt vmcnt(8)
	s_waitcnt lgkmcnt(0)
	s_barrier
	s_setprio 1
	s_waitcnt lgkmcnt(0)
	v_mfma_f32_16x16x32_bf16 v[60:63], v[152:155], v[196:199], v[60:63]
	v_mfma_f32_16x16x32_bf16 v[56:59], v[172:175], v[196:199], v[56:59]
	v_mfma_f32_16x16x32_bf16 v[44:47], v[152:155], v[204:207], v[44:47]
	v_mfma_f32_16x16x32_bf16 v[40:43], v[172:175], v[204:207], v[40:43]
	v_mfma_f32_16x16x32_bf16 v[28:31], v[152:155], v[212:215], v[28:31]
	v_mfma_f32_16x16x32_bf16 v[24:27], v[172:175], v[212:215], v[24:27]
	v_mfma_f32_16x16x32_bf16 v[12:15], v[152:155], v[220:223], v[12:15]
	v_mfma_f32_16x16x32_bf16 v[8:11], v[172:175], v[220:223], v[8:11]
	v_mfma_f32_16x16x32_bf16 v[60:63], v[156:159], v[200:203], v[60:63]
	v_mfma_f32_16x16x32_bf16 v[56:59], v[176:179], v[200:203], v[56:59]
	v_mfma_f32_16x16x32_bf16 v[44:47], v[156:159], v[208:211], v[44:47]
	v_mfma_f32_16x16x32_bf16 v[40:43], v[176:179], v[208:211], v[40:43]
	v_mfma_f32_16x16x32_bf16 v[28:31], v[156:159], v[216:219], v[28:31]
	v_mfma_f32_16x16x32_bf16 v[24:27], v[176:179], v[216:219], v[24:27]
	v_mfma_f32_16x16x32_bf16 v[12:15], v[156:159], v[228:231], v[12:15]
	v_mfma_f32_16x16x32_bf16 v[8:11], v[176:179], v[228:231], v[8:11]
	s_setprio 0
	s_setprio 1
	v_mfma_f32_16x16x32_bf16 v[52:55], v[180:183], v[196:199], v[52:55]
	v_mfma_f32_16x16x32_bf16 v[48:51], v[188:191], v[196:199], v[48:51]
	v_mfma_f32_16x16x32_bf16 v[36:39], v[180:183], v[204:207], v[36:39]
	v_mfma_f32_16x16x32_bf16 v[32:35], v[188:191], v[204:207], v[32:35]
	v_mfma_f32_16x16x32_bf16 v[20:23], v[180:183], v[212:215], v[20:23]
	v_mfma_f32_16x16x32_bf16 v[16:19], v[188:191], v[212:215], v[16:19]
	v_mfma_f32_16x16x32_bf16 v[4:7], v[180:183], v[220:223], v[4:7]
	v_mfma_f32_16x16x32_bf16 v[0:3], v[188:191], v[220:223], v[0:3]
	v_mfma_f32_16x16x32_bf16 v[52:55], v[184:187], v[200:203], v[52:55]
	v_mfma_f32_16x16x32_bf16 v[48:51], v[192:195], v[200:203], v[48:51]
	v_mfma_f32_16x16x32_bf16 v[36:39], v[184:187], v[208:211], v[36:39]
	v_mfma_f32_16x16x32_bf16 v[32:35], v[192:195], v[208:211], v[32:35]
	v_mfma_f32_16x16x32_bf16 v[20:23], v[184:187], v[216:219], v[20:23]
	v_mfma_f32_16x16x32_bf16 v[16:19], v[192:195], v[216:219], v[16:19]
	v_mfma_f32_16x16x32_bf16 v[4:7], v[184:187], v[228:231], v[4:7]
	v_mfma_f32_16x16x32_bf16 v[0:3], v[192:195], v[228:231], v[0:3]
	s_setprio 0
	s_barrier
	s_add_u32 s74, s74, 0x100
	s_addc_u32 s75, s75, 0
	s_cmp_gt_u32 s93, 13
	s_mov_b32 s8, s93

; #define PG8_STAGE(bufoff, gbase, voff) do { _Pragma("unroll") for (int _i = 0; _i < 2; ++_i) \
;         __builtin_amdgcn_global_load_lds((const unsigned*)((const char*)(gbase) + (voff)[_i]), (LAS unsigned*)(lds + (bufoff) + ldsw + _i * 8192), 16, 0, 0); } while (0)
; #define PG8_LDA(dst, b, h) do { _Pragma("unroll") for (int m = 0; m < 4; ++m) _Pragma("unroll") for (int k = 0; k < 2; ++k) dst[m][k] = *(const LAS bf16x8*)(lds + PG8_SA(b, h) + aoff + m * 2048 + k * 1024); } while (0)
; #define PG8_LDB(dst, b, h) do { _Pragma("unroll") for (int n = 0; n < 2; ++n) _Pragma("unroll") for (int k = 0; k < 2; ++k) dst[n][k] = *(const LAS bf16x8*)(lds + PG8_SB(b, h) + boff + n * 2048 + k * 1024); } while (0)
; #define PG8_WAIT_V(n) asm volatile("s_waitcnt vmcnt(" #n ")" ::: "memory")
; #define PG8_WAIT_L(n) asm volatile("s_waitcnt lgkmcnt(" #n ")" ::: "memory")
; #define PG8_BAR __builtin_amdgcn_s_barrier()
; #define PG8_SCHED __builtin_amdgcn_sched_barrier(0)
; template <class Epi, bool ALIGN_EPI = true, bool SP2 = true>
; __device__ __forceinline__ void gemm_phase(LAS unsigned char* lds, const Gemm g, const StaticOrder& S, const Epi& E) {
;     ...
;         const bool has_next = S.next(ui + 1, nxt);
;         const int npm = has_next ? nxt.pm : cur.pm;
;         const char* nB = has_next ? (const char*)g.Bt + (size_t)nxt.pn * tstepB : cB;
;         for (int t = 0; t < nt; t += 2) {
;             const bool last = (t == nt - 2);
;             const char* a1 = PG8_ATILE(cur.pm, t + 1);
;             const char* a2 = last ? PG8_ATILE(npm, 0) : PG8_ATILE(cur.pm, t + 2);
;             const char* a3 = last ? PG8_ATILE(npm, 1) : PG8_ATILE(cur.pm, t + 3);
;             const char* b2 = last ? nB : cB + (size_t)(t + 2) * kstep;
;             const char* b3 = b2 + kstep;
;             if constexpr (SP2) {
;             PG8_LDB(B0, 0, 0); PG8_LDB(B1, 0, 1); PG8_SCHED; PG8_LDA(At, 0, 0); PG8_STAGE(PG8_SA(1, 1), a1 + hstepA, voffA);
;             PG8_WAIT_V(8); PG8_WAIT_L(0); PG8_BAR; PG8_MMA(0, 0, At, B0); PG8_MMA(0, 1, At, B1); PG8_BAR; PG8_SCHED;
;             PG8_LDA(At, 0, 1); PG8_STAGE(PG8_SB(0, 0), b2, voffB); PG8_STAGE(PG8_SB(0, 1), b2 + hstepB, voffB); PG8_STAGE(PG8_SA(0, 0), a2, voffA);
;             PG8_WAIT_V(8); PG8_WAIT_L(0); PG8_BAR; PG8_MMA(1, 0, At, B0); PG8_MMA(1, 1, At, B1); PG8_BAR; PG8_SCHED;
.LBB0_412:
	s_ashr_i32 s15, s14, 31
	s_lshl_b64 s[52:53], s[14:15], 19
	s_add_u32 s52, s20, s52
	s_addc_u32 s53, s21, s53
	s_and_b64 s[56:57], s[0:1], exec
	s_cselect_b32 s15, s53, s59
	s_cselect_b32 s68, s52, s58
	s_ashr_i32 s55, s54, 31
	s_ashr_i32 s61, s60, 31
	s_lshl_b64 s[56:57], s[54:55], 19
	s_lshl_b64 s[60:61], s[60:61], 19
	s_add_u32 s55, s7, s60
	s_addc_u32 s69, s28, s61
	s_add_u32 s72, s67, s60
	s_addc_u32 s73, s70, s61
	s_add_u32 s84, s78, s56
	s_addc_u32 s85, s79, s57
	s_add_u32 s86, s58, 0x100
	v_mov_b32_e32 v0, 0
	v_lshl_add_u64 v[144:145], v[136:137], 0, s[56:57]
	v_lshl_add_u64 v[146:147], v[138:139], 0, s[56:57]
	s_addc_u32 s87, s59, 0
	s_mov_b32 s4, -2
	s_mov_b64 s[58:59], 0
	s_add_i32 s88, s4, 2
	s_add_u32 s60, s84, s58
	s_addc_u32 s61, s85, s59
	s_add_u32 s62, s60, 0x1200100
	s_addc_u32 s63, s61, 0
	s_add_u32 s60, s78, s58
	s_addc_u32 s61, s79, s59
	s_add_u32 s64, s60, 0x1200180
	s_addc_u32 s65, s61, 0
	s_add_i32 s4, s4, -11
	ds_read_b128 v[154:157], v151
	ds_read_b128 v[158:161], v151 offset:1024
	ds_read_b128 v[162:165], v151 offset:2048
	ds_read_b128 v[166:169], v151 offset:3072
	ds_read_b128 v[172:175], v152
	ds_read_b128 v[176:179], v152 offset:1024
	ds_read_b128 v[180:183], v152 offset:2048
	ds_read_b128 v[184:187], v152 offset:3072
	s_lshl_b64 s[60:61], s[4:5], 7
	s_add_u32 s4, s7, s60
	s_addc_u32 s60, s28, s61
	s_cmp_lt_u32 s88, 13
	s_cselect_b32 s4, s64, s4
	s_cselect_b32 s60, s65, s60
	s_add_u32 s4, s4, s56
	s_addc_u32 s60, s60, s57
	s_add_u32 s89, s86, s58
	s_addc_u32 s90, s87, s59
	s_cmpk_eq_i32 s58, 0x700
	s_cselect_b32 s65, s69, s63
	s_cselect_b32 s64, s55, s62
	s_cselect_b32 s61, s73, s60
	s_cselect_b32 s60, s72, s4
	s_cselect_b32 s63, s15, s90
	s_cselect_b32 s62, s68, s89
	v_lshl_add_u64 v[220:221], v[144:145], 0, s[58:59]
	s_add_i32 m0, s29, 0xc000
	ds_read_b128 v[188:191], v153
	ds_read_b128 v[192:195], v153 offset:1024
	ds_read_b128 v[196:199], v153 offset:2048
	ds_read_b128 v[200:203], v153 offset:3072
	ds_read_b128 v[204:207], v153 offset:4096
	ds_read_b128 v[208:211], v153 offset:5120
	ds_read_b128 v[212:215], v153 offset:6144
	ds_read_b128 v[216:219], v153 offset:7168
	global_load_lds_dwordx4 v[220:221], off
	v_lshl_add_u64 v[220:221], v[146:147], 0, s[58:59]
	s_add_i32 m0, s29, 0xe000
	s_nop 0
	global_load_lds_dwordx4 v[220:221], off
	s_waitcnt vmcnt(8)
	s_waitcnt lgkmcnt(0)
	s_barrier
	s_setprio 1
	s_waitcnt lgkmcnt(0)
	v_mfma_f32_16x16x32_bf16 v[124:127], v[154:157], v[188:191], 0
	v_mfma_f32_16x16x32_bf16 v[120:123], v[162:165], v[188:191], 0
	v_mfma_f32_16x16x32_bf16 v[116:119], v[154:157], v[196:199], 0
	v_mfma_f32_16x16x32_bf16 v[108:111], v[162:165], v[196:199], 0
	v_mfma_f32_16x16x32_bf16 v[100:103], v[154:157], v[204:207], 0
	v_mfma_f32_16x16x32_bf16 v[92:95], v[162:165], v[204:207], 0
	v_mfma_f32_16x16x32_bf16 v[84:87], v[154:157], v[212:215], 0
	v_mfma_f32_16x16x32_bf16 v[76:79], v[162:165], v[212:215], 0
	v_mfma_f32_16x16x32_bf16 v[124:127], v[158:161], v[192:195], v[124:127]
	v_mfma_f32_16x16x32_bf16 v[120:123], v[166:169], v[192:195], v[120:123]
	v_mfma_f32_16x16x32_bf16 v[116:119], v[158:161], v[200:203], v[116:119]
	v_mfma_f32_16x16x32_bf16 v[108:111], v[166:169], v[200:203], v[108:111]
	v_mfma_f32_16x16x32_bf16 v[100:103], v[158:161], v[208:211], v[100:103]
	v_mfma_f32_16x16x32_bf16 v[92:95], v[166:169], v[208:211], v[92:95]
	v_mfma_f32_16x16x32_bf16 v[84:87], v[158:161], v[216:219], v[84:87]
	v_mfma_f32_16x16x32_bf16 v[76:79], v[166:169], v[216:219], v[76:79]
	s_setprio 0
	s_setprio 1
	v_mfma_f32_16x16x32_bf16 v[112:115], v[172:175], v[188:191], 0
	v_mfma_f32_16x16x32_bf16 v[104:107], v[180:183], v[188:191], 0
	v_mfma_f32_16x16x32_bf16 v[96:99], v[172:175], v[196:199], 0
	v_mfma_f32_16x16x32_bf16 v[88:91], v[180:183], v[196:199], 0
	v_mfma_f32_16x16x32_bf16 v[80:83], v[172:175], v[204:207], 0
	v_mfma_f32_16x16x32_bf16 v[72:75], v[180:183], v[204:207], 0
	v_mfma_f32_16x16x32_bf16 v[68:71], v[172:175], v[212:215], 0
	v_mfma_f32_16x16x32_bf16 v[64:67], v[180:183], v[212:215], 0
	v_mfma_f32_16x16x32_bf16 v[112:115], v[176:179], v[192:195], v[112:115]
	v_mfma_f32_16x16x32_bf16 v[104:107], v[184:187], v[192:195], v[104:107]
	v_mfma_f32_16x16x32_bf16 v[96:99], v[176:179], v[200:203], v[96:99]
	v_mfma_f32_16x16x32_bf16 v[88:91], v[184:187], v[200:203], v[88:91]
	v_mfma_f32_16x16x32_bf16 v[80:83], v[176:179], v[208:211], v[80:83]
	v_mfma_f32_16x16x32_bf16 v[72:75], v[184:187], v[208:211], v[72:75]
	v_mfma_f32_16x16x32_bf16 v[68:71], v[176:179], v[216:219], v[68:71]
	v_mfma_f32_16x16x32_bf16 v[64:67], v[184:187], v[216:219], v[64:67]
	s_setprio 0
	s_barrier
	s_add_i32 s4, s75, s6
	v_lshl_add_u64 v[220:221], s[62:63], 0, v[132:133]
	s_mov_b32 m0, s4
	ds_read_b128 v[188:191], v153 offset:16384
	ds_read_b128 v[192:195], v153 offset:17408
	ds_read_b128 v[196:199], v153 offset:18432
	ds_read_b128 v[200:203], v153 offset:19456
	ds_read_b128 v[204:207], v153 offset:20480
	ds_read_b128 v[208:211], v153 offset:21504
	ds_read_b128 v[212:215], v153 offset:22528
	ds_read_b128 v[216:219], v153 offset:23552
	global_load_lds_dwordx4 v[220:221], off
	s_add_i32 m0, s4, 0x2000
	s_add_u32 s90, s62, 0x40000
	v_lshl_add_u64 v[222:223], s[62:63], 0, v[128:129]
	s_addc_u32 s91, s63, 0
	s_add_i32 s4, s80, s6
	global_load_lds_dwordx4 v[222:223], off
	v_lshl_add_u64 v[224:225], s[90:91], 0, v[132:133]
	s_mov_b32 m0, s4
	s_nop 0
	global_load_lds_dwordx4 v[224:225], off
	v_lshl_add_u64 v[224:225], s[90:91], 0, v[128:129]
	s_add_i32 m0, s4, 0x2000
	s_nop 0
	global_load_lds_dwordx4 v[224:225], off
	v_lshl_add_u64 v[224:225], s[64:65], 0, v[134:135]
	s_mov_b32 m0, s29
	s_nop 0
	global_load_lds_dwordx4 v[224:225], off
	v_lshl_add_u64 v[224:225], s[64:65], 0, v[130:131]
	s_mov_b32 m0, s38
	s_nop 0
	global_load_lds_dwordx4 v[224:225], off
	s_waitcnt vmcnt(8)
	s_waitcnt lgkmcnt(0)
	s_barrier
; #define PG8_STAGE(bufoff, gbase, voff) do { _Pragma("unroll") for (int _i = 0; _i < 2; ++_i) \
;         __builtin_amdgcn_global_load_lds((const unsigned*)((const char*)(gbase) + (voff)[_i]), (LAS unsigned*)(lds + (bufoff) + ldsw + _i * 8192), 16, 0, 0); } while (0)
; #define PG8_LDA(dst, b, h) do { _Pragma("unroll") for (int m = 0; m < 4; ++m) _Pragma("unroll") for (int k = 0; k < 2; ++k) dst[m][k] = *(const LAS bf16x8*)(lds + PG8_SA(b, h) + aoff + m * 2048 + k * 1024); } while (0)
; #define PG8_LDB(dst, b, h) do { _Pragma("unroll") for (int n = 0; n < 2; ++n) _Pragma("unroll") for (int k = 0; k < 2; ++k) dst[n][k] = *(const LAS bf16x8*)(lds + PG8_SB(b, h) + boff + n * 2048 + k * 1024); } while (0)
; #define PG8_MMA(ai, bj, At, Bt) do { __builtin_amdgcn_s_setprio(1); _Pragma("unroll") for (int m = 0; m < 4; ++m) _Pragma("unroll") for (int n = 0; n < 2; ++n) _Pragma("unroll") for (int k = 0; k < 2; ++k) \
;         acc[ai][bj][m][n] = __builtin_amdgcn_mfma_f32_16x16x32_bf16(Bt[n][k], At[m][k], acc[ai][bj][m][n], 0, 0, 0); __builtin_amdgcn_s_setprio(0); } while (0)
; #define PG8_WAIT_V(n) asm volatile("s_waitcnt vmcnt(" #n ")" ::: "memory")
; #define PG8_WAIT_L(n) asm volatile("s_waitcnt lgkmcnt(" #n ")" ::: "memory")
; #define PG8_BAR __builtin_amdgcn_s_barrier()
; #define PG8_SCHED __builtin_amdgcn_sched_barrier(0)
; template <class Epi, bool ALIGN_EPI = true, bool SP2 = true>
; __device__ __forceinline__ void gemm_phase(LAS unsigned char* lds, const Gemm g, const StaticOrder& S, const Epi& E) {
;     ...
;             PG8_WAIT_V(8); PG8_WAIT_L(0); PG8_BAR; PG8_MMA(1, 0, At, B0); PG8_MMA(1, 1, At, B1); PG8_BAR; PG8_SCHED;
;             PG8_LDB(B0, 1, 0); PG8_LDB(B1, 1, 1); PG8_SCHED; PG8_LDA(At, 1, 0); PG8_STAGE(PG8_SA(0, 1), a2 + hstepA, voffA);
;             PG8_WAIT_V(8); PG8_WAIT_L(0); PG8_BAR; PG8_MMA(0, 0, At, B0); PG8_MMA(0, 1, At, B1); PG8_BAR; PG8_SCHED;
	s_setprio 1
	s_waitcnt lgkmcnt(0)
	v_mfma_f32_16x16x32_bf16 v[60:63], v[154:157], v[188:191], 0
	v_mfma_f32_16x16x32_bf16 v[56:59], v[162:165], v[188:191], 0
	v_mfma_f32_16x16x32_bf16 v[52:55], v[154:157], v[196:199], 0
	v_mfma_f32_16x16x32_bf16 v[44:47], v[162:165], v[196:199], 0
	v_mfma_f32_16x16x32_bf16 v[36:39], v[154:157], v[204:207], 0
	v_mfma_f32_16x16x32_bf16 v[28:31], v[162:165], v[204:207], 0
	v_mfma_f32_16x16x32_bf16 v[20:23], v[154:157], v[212:215], 0
	v_mfma_f32_16x16x32_bf16 v[12:15], v[162:165], v[212:215], 0
	v_mfma_f32_16x16x32_bf16 v[60:63], v[158:161], v[192:195], v[60:63]
	v_mfma_f32_16x16x32_bf16 v[56:59], v[166:169], v[192:195], v[56:59]
	v_mfma_f32_16x16x32_bf16 v[52:55], v[158:161], v[200:203], v[52:55]
	v_mfma_f32_16x16x32_bf16 v[44:47], v[166:169], v[200:203], v[44:47]
	v_mfma_f32_16x16x32_bf16 v[36:39], v[158:161], v[208:211], v[36:39]
	v_mfma_f32_16x16x32_bf16 v[28:31], v[166:169], v[208:211], v[28:31]
	v_mfma_f32_16x16x32_bf16 v[20:23], v[158:161], v[216:219], v[20:23]
	v_mfma_f32_16x16x32_bf16 v[12:15], v[166:169], v[216:219], v[12:15]
	s_setprio 0
	s_setprio 1
	v_mfma_f32_16x16x32_bf16 v[48:51], v[172:175], v[188:191], 0
	v_mfma_f32_16x16x32_bf16 v[40:43], v[180:183], v[188:191], 0
	v_mfma_f32_16x16x32_bf16 v[32:35], v[172:175], v[196:199], 0
	v_mfma_f32_16x16x32_bf16 v[24:27], v[180:183], v[196:199], 0
	v_mfma_f32_16x16x32_bf16 v[16:19], v[172:175], v[204:207], 0
	v_mfma_f32_16x16x32_bf16 v[8:11], v[180:183], v[204:207], 0
	v_mfma_f32_16x16x32_bf16 v[4:7], v[172:175], v[212:215], 0
	v_mfma_f32_16x16x32_bf16 v[0:3], v[180:183], v[212:215], 0
	v_mfma_f32_16x16x32_bf16 v[48:51], v[176:179], v[192:195], v[48:51]
	v_mfma_f32_16x16x32_bf16 v[40:43], v[184:187], v[192:195], v[40:43]
	v_mfma_f32_16x16x32_bf16 v[32:35], v[176:179], v[200:203], v[32:35]
	v_mfma_f32_16x16x32_bf16 v[24:27], v[184:187], v[200:203], v[24:27]
	v_mfma_f32_16x16x32_bf16 v[16:19], v[176:179], v[208:211], v[16:19]
	v_mfma_f32_16x16x32_bf16 v[8:11], v[184:187], v[208:211], v[8:11]
	v_mfma_f32_16x16x32_bf16 v[4:7], v[176:179], v[216:219], v[4:7]
	v_mfma_f32_16x16x32_bf16 v[0:3], v[184:187], v[216:219], v[0:3]
	s_setprio 0
	s_barrier
	s_add_i32 s4, 0, 0x18000
	s_add_i32 s89, 0, 0x1c000
	v_add_u32_e32 v166, s4, v149
	v_add_u32_e32 v171, s89, v149
	ds_read_b128 v[154:157], v166
	ds_read_b128 v[158:161], v166 offset:1024
	ds_read_b128 v[162:165], v166 offset:2048
	ds_read_b128 v[166:169], v166 offset:3072
	ds_read_b128 v[172:175], v171
	ds_read_b128 v[176:179], v171 offset:1024
	ds_read_b128 v[180:183], v171 offset:2048
	ds_read_b128 v[184:187], v171 offset:3072
	s_add_u32 s64, s64, 0x40000
	s_addc_u32 s65, s65, 0
	s_mov_b32 m0, s39
	v_lshl_add_u64 v[224:225], s[64:65], 0, v[134:135]
	ds_read_b128 v[188:191], v153 offset:32768
	ds_read_b128 v[192:195], v153 offset:33792
	ds_read_b128 v[196:199], v153 offset:34816
	ds_read_b128 v[200:203], v153 offset:35840
	ds_read_b128 v[204:207], v153 offset:36864
	ds_read_b128 v[208:211], v153 offset:37888
	ds_read_b128 v[212:215], v153 offset:38912
	ds_read_b128 v[216:219], v153 offset:39936
	global_load_lds_dwordx4 v[224:225], off
	v_lshl_add_u64 v[224:225], s[64:65], 0, v[130:131]
	s_mov_b32 m0, s66
	s_nop 0
	global_load_lds_dwordx4 v[224:225], off
	s_waitcnt vmcnt(8)
	s_waitcnt lgkmcnt(0)
	s_barrier
	s_setprio 1
	s_waitcnt lgkmcnt(0)
	v_mfma_f32_16x16x32_bf16 v[124:127], v[154:157], v[188:191], v[124:127]
	v_mfma_f32_16x16x32_bf16 v[120:123], v[162:165], v[188:191], v[120:123]
	v_mfma_f32_16x16x32_bf16 v[116:119], v[154:157], v[196:199], v[116:119]
	v_mfma_f32_16x16x32_bf16 v[108:111], v[162:165], v[196:199], v[108:111]
	v_mfma_f32_16x16x32_bf16 v[100:103], v[154:157], v[204:207], v[100:103]
	v_mfma_f32_16x16x32_bf16 v[92:95], v[162:165], v[204:207], v[92:95]
	v_mfma_f32_16x16x32_bf16 v[84:87], v[154:157], v[212:215], v[84:87]
	v_mfma_f32_16x16x32_bf16 v[76:79], v[162:165], v[212:215], v[76:79]
	v_mfma_f32_16x16x32_bf16 v[124:127], v[158:161], v[192:195], v[124:127]
	v_mfma_f32_16x16x32_bf16 v[120:123], v[166:169], v[192:195], v[120:123]
	v_mfma_f32_16x16x32_bf16 v[116:119], v[158:161], v[200:203], v[116:119]
	v_mfma_f32_16x16x32_bf16 v[108:111], v[166:169], v[200:203], v[108:111]
	v_mfma_f32_16x16x32_bf16 v[100:103], v[158:161], v[208:211], v[100:103]
	v_mfma_f32_16x16x32_bf16 v[92:95], v[166:169], v[208:211], v[92:95]
	v_mfma_f32_16x16x32_bf16 v[84:87], v[158:161], v[216:219], v[84:87]
	v_mfma_f32_16x16x32_bf16 v[76:79], v[166:169], v[216:219], v[76:79]
	s_setprio 0
	s_setprio 1
	v_mfma_f32_16x16x32_bf16 v[112:115], v[172:175], v[188:191], v[112:115]
	v_mfma_f32_16x16x32_bf16 v[104:107], v[180:183], v[188:191], v[104:107]
	v_mfma_f32_16x16x32_bf16 v[96:99], v[172:175], v[196:199], v[96:99]
	v_mfma_f32_16x16x32_bf16 v[88:91], v[180:183], v[196:199], v[88:91]
	v_mfma_f32_16x16x32_bf16 v[80:83], v[172:175], v[204:207], v[80:83]
	v_mfma_f32_16x16x32_bf16 v[72:75], v[180:183], v[204:207], v[72:75]
	v_mfma_f32_16x16x32_bf16 v[68:71], v[172:175], v[212:215], v[68:71]
	v_mfma_f32_16x16x32_bf16 v[64:67], v[180:183], v[212:215], v[64:67]
	v_mfma_f32_16x16x32_bf16 v[112:115], v[176:179], v[192:195], v[112:115]
	v_mfma_f32_16x16x32_bf16 v[104:107], v[184:187], v[192:195], v[104:107]
	v_mfma_f32_16x16x32_bf16 v[96:99], v[176:179], v[200:203], v[96:99]
	v_mfma_f32_16x16x32_bf16 v[88:91], v[184:187], v[200:203], v[88:91]
	v_mfma_f32_16x16x32_bf16 v[80:83], v[176:179], v[208:211], v[80:83]
	v_mfma_f32_16x16x32_bf16 v[72:75], v[184:187], v[208:211], v[72:75]
	v_mfma_f32_16x16x32_bf16 v[68:71], v[176:179], v[216:219], v[68:71]
	v_mfma_f32_16x16x32_bf16 v[64:67], v[184:187], v[216:219], v[64:67]
	s_setprio 0
	s_barrier
; #define PG8_STAGE(bufoff, gbase, voff) do { _Pragma("unroll") for (int _i = 0; _i < 2; ++_i) \
;         __builtin_amdgcn_global_load_lds((const unsigned*)((const char*)(gbase) + (voff)[_i]), (LAS unsigned*)(lds + (bufoff) + ldsw + _i * 8192), 16, 0, 0); } while (0)
; #define PG8_LDA(dst, b, h) do { _Pragma("unroll") for (int m = 0; m < 4; ++m) _Pragma("unroll") for (int k = 0; k < 2; ++k) dst[m][k] = *(const LAS bf16x8*)(lds + PG8_SA(b, h) + aoff + m * 2048 + k * 1024); } while (0)
; #define PG8_MMA(ai, bj, At, Bt) do { __builtin_amdgcn_s_setprio(1); _Pragma("unroll") for (int m = 0; m < 4; ++m) _Pragma("unroll") for (int n = 0; n < 2; ++n) _Pragma("unroll") for (int k = 0; k < 2; ++k) \
;         acc[ai][bj][m][n] = __builtin_amdgcn_mfma_f32_16x16x32_bf16(Bt[n][k], At[m][k], acc[ai][bj][m][n], 0, 0, 0); __builtin_amdgcn_s_setprio(0); } while (0)
; #define PG8_WAIT_V(n) asm volatile("s_waitcnt vmcnt(" #n ")" ::: "memory")
; #define PG8_WAIT_L(n) asm volatile("s_waitcnt lgkmcnt(" #n ")" ::: "memory")
; #define PG8_BAR __builtin_amdgcn_s_barrier()
; #define PG8_SCHED __builtin_amdgcn_sched_barrier(0)
; template <class Epi, bool ALIGN_EPI = true, bool SP2 = true>
; __device__ __forceinline__ void gemm_phase(LAS unsigned char* lds, const Gemm g, const StaticOrder& S, const Epi& E) {
;     ...
;             PG8_LDA(At, 1, 1); PG8_STAGE(PG8_SB(1, 0), b3, voffB); PG8_STAGE(PG8_SB(1, 1), b3 + hstepB, voffB); PG8_STAGE(PG8_SA(1, 0), a3, voffA);
;             PG8_WAIT_V(8); PG8_WAIT_L(0); PG8_BAR; PG8_MMA(1, 0, At, B0); PG8_MMA(1, 1, At, B1); PG8_BAR; PG8_SCHED;
	s_add_i32 s4, s4, s6
	v_lshl_add_u64 v[220:221], v[220:221], 0, s[10:11]
	s_mov_b32 m0, s4
	ds_read_b128 v[188:191], v153 offset:49152
	ds_read_b128 v[192:195], v153 offset:50176
	ds_read_b128 v[196:199], v153 offset:51200
	ds_read_b128 v[200:203], v153 offset:52224
	ds_read_b128 v[204:207], v153 offset:53248
	ds_read_b128 v[208:211], v153 offset:54272
	ds_read_b128 v[212:215], v153 offset:55296
	ds_read_b128 v[216:219], v153 offset:56320
	global_load_lds_dwordx4 v[220:221], off
	s_add_i32 m0, s4, 0x2000
	s_add_u32 s62, s62, 0x40080
	v_lshl_add_u64 v[220:221], v[222:223], 0, s[10:11]
	s_addc_u32 s63, s63, 0
	s_add_i32 s4, s89, s6
	global_load_lds_dwordx4 v[220:221], off
	v_lshl_add_u64 v[220:221], s[62:63], 0, v[132:133]
	s_mov_b32 m0, s4
	s_nop 0
	global_load_lds_dwordx4 v[220:221], off
	v_lshl_add_u64 v[220:221], s[62:63], 0, v[128:129]
	s_add_i32 m0, s4, 0x2000
	s_nop 0
	global_load_lds_dwordx4 v[220:221], off
	v_lshl_add_u64 v[220:221], s[60:61], 0, v[134:135]
	s_mov_b32 m0, s71
	s_nop 0
	global_load_lds_dwordx4 v[220:221], off
	v_lshl_add_u64 v[220:221], s[60:61], 0, v[130:131]
	s_mov_b32 m0, s74
	s_nop 0
	global_load_lds_dwordx4 v[220:221], off
	s_waitcnt vmcnt(8)
	s_waitcnt lgkmcnt(0)
	s_barrier
	s_setprio 1
	s_waitcnt lgkmcnt(0)
	v_mfma_f32_16x16x32_bf16 v[60:63], v[154:157], v[188:191], v[60:63]
	v_mfma_f32_16x16x32_bf16 v[56:59], v[162:165], v[188:191], v[56:59]
	v_mfma_f32_16x16x32_bf16 v[52:55], v[154:157], v[196:199], v[52:55]
	v_mfma_f32_16x16x32_bf16 v[44:47], v[162:165], v[196:199], v[44:47]
	v_mfma_f32_16x16x32_bf16 v[36:39], v[154:157], v[204:207], v[36:39]
	v_mfma_f32_16x16x32_bf16 v[28:31], v[162:165], v[204:207], v[28:31]
	v_mfma_f32_16x16x32_bf16 v[20:23], v[154:157], v[212:215], v[20:23]
	v_mfma_f32_16x16x32_bf16 v[12:15], v[162:165], v[212:215], v[12:15]
	v_mfma_f32_16x16x32_bf16 v[60:63], v[158:161], v[192:195], v[60:63]
	v_mfma_f32_16x16x32_bf16 v[56:59], v[166:169], v[192:195], v[56:59]
	v_mfma_f32_16x16x32_bf16 v[52:55], v[158:161], v[200:203], v[52:55]
	v_mfma_f32_16x16x32_bf16 v[44:47], v[166:169], v[200:203], v[44:47]
	v_mfma_f32_16x16x32_bf16 v[36:39], v[158:161], v[208:211], v[36:39]
	v_mfma_f32_16x16x32_bf16 v[28:31], v[166:169], v[208:211], v[28:31]
	v_mfma_f32_16x16x32_bf16 v[20:23], v[158:161], v[216:219], v[20:23]
	v_mfma_f32_16x16x32_bf16 v[12:15], v[166:169], v[216:219], v[12:15]
	s_setprio 0
	s_setprio 1
	v_mfma_f32_16x16x32_bf16 v[48:51], v[172:175], v[188:191], v[48:51]
	v_mfma_f32_16x16x32_bf16 v[40:43], v[180:183], v[188:191], v[40:43]
	v_mfma_f32_16x16x32_bf16 v[32:35], v[172:175], v[196:199], v[32:35]
	v_mfma_f32_16x16x32_bf16 v[24:27], v[180:183], v[196:199], v[24:27]
	v_mfma_f32_16x16x32_bf16 v[16:19], v[172:175], v[204:207], v[16:19]
	v_mfma_f32_16x16x32_bf16 v[8:11], v[180:183], v[204:207], v[8:11]
	v_mfma_f32_16x16x32_bf16 v[4:7], v[172:175], v[212:215], v[4:7]
	v_mfma_f32_16x16x32_bf16 v[0:3], v[180:183], v[212:215], v[0:3]
	v_mfma_f32_16x16x32_bf16 v[48:51], v[176:179], v[192:195], v[48:51]
	v_mfma_f32_16x16x32_bf16 v[40:43], v[184:187], v[192:195], v[40:43]
	v_mfma_f32_16x16x32_bf16 v[32:35], v[176:179], v[200:203], v[32:35]
	v_mfma_f32_16x16x32_bf16 v[24:27], v[184:187], v[200:203], v[24:27]
	v_mfma_f32_16x16x32_bf16 v[16:19], v[176:179], v[208:211], v[16:19]
	v_mfma_f32_16x16x32_bf16 v[8:11], v[184:187], v[208:211], v[8:11]
	v_mfma_f32_16x16x32_bf16 v[4:7], v[176:179], v[216:219], v[4:7]
	v_mfma_f32_16x16x32_bf16 v[0:3], v[184:187], v[216:219], v[0:3]
	s_setprio 0
	s_barrier
	s_add_u32 s58, s58, 0x100
	s_addc_u32 s59, s59, 0
	s_cmp_gt_u32 s88, 13
	s_mov_b32 s4, s88

; template <bool PASSB>
; __device__ __forceinline__ void lru_unit(LAS unsigned char* lds, const Params& p, int b, int hd, int chunk) {
;     ...
;     float clv; { const float L = p.in[12][gch]; clv = -8.0f * (fmaxf(-L, 0.f) + log1pf(expf(-fabsf(L)))); }
;     ...
;                 const float e1 = __expf(fminf(-(ar[j] + brv), 40.f)), e2 = __expf(fminf(-(ai[j] + biv), 40.f));
;                 const float inv = __builtin_amdgcn_rcpf((1.0f + e1) * (1.0f + e2));
;                 const float r = inv * (1.0f + e2), ig = inv * (1.0f + e1);
;                 const float a = __expf(clv * r);
;                 const float bb = __builtin_amdgcn_sqrtf(fmaxf(1.0f - a * a, 0.f)) * (ig * xcv);
.LBB0_492:
	s_or_b64 exec, exec, s[12:13]
	s_waitcnt vmcnt(11)
	v_mul_f32_e64 v104, |v108|, s58
	v_rndne_f32_e32 v115, v104
	v_sub_f32_e32 v119, v104, v115
	v_fma_f32 v104, |v108|, s58, -v104
	v_fma_f32 v104, |v108|, s59, v104
	v_add_f32_e32 v104, v119, v104
	v_exp_f32_e32 v104, v104
	v_cvt_i32_f32_e32 v115, v115
	v_cmp_ngt_f32_e64 vcc, |v108|, s60
	v_max_f32_e64 v119, -v108, -v108
	v_max_f32_e32 v119, 0, v119
	v_ldexp_f32 v104, v104, v115
	v_cndmask_b32_e32 v104, 0, v104, vcc
	v_cmp_nlt_f32_e64 vcc, |v108|, s61
	v_mov_b32_e32 v108, 1.0
	s_mov_b32 s0, 0
	v_cndmask_b32_e32 v104, v121, v104, vcc
	v_add_f32_e32 v115, 1.0, v104
	v_add_f32_e32 v126, -1.0, v115
	v_sub_f32_e32 v129, v126, v115
	v_add_f32_e32 v129, 1.0, v129
	v_sub_f32_e32 v126, v104, v126
	v_add_f32_e32 v126, v126, v129
	v_frexp_mant_f32_e32 v129, v115
	v_cvt_f64_f32_e32 v[130:131], v115
	v_frexp_exp_i32_f64_e32 v130, v[130:131]
	v_cmp_gt_f32_e32 vcc, s63, v129
	s_mov_b32 s11, 0
	s_nop 0
	v_subbrev_co_u32_e32 v129, vcc, 0, v130, vcc
	v_sub_u32_e32 v130, 0, v129
	v_ldexp_f32 v115, v115, v130
	v_ldexp_f32 v126, v126, v130
	v_add_f32_e32 v130, -1.0, v115
	v_add_f32_e32 v133, 1.0, v115
	v_add_f32_e32 v131, 1.0, v130
	v_add_f32_e32 v134, -1.0, v133
	v_sub_f32_e32 v131, v115, v131
	v_sub_f32_e32 v115, v115, v134
	v_add_f32_e32 v115, v126, v115
	v_add_f32_e32 v131, v126, v131
	v_add_f32_e32 v126, v133, v115
	v_rcp_f32_e32 v134, v126
	v_add_f32_e32 v132, v130, v131
	v_sub_f32_e32 v130, v130, v132
	v_add_f32_e32 v130, v131, v130
	v_sub_f32_e32 v131, v133, v126
	v_add_f32_e32 v115, v115, v131
	v_mul_f32_e32 v131, v132, v134
	v_mul_f32_e32 v133, v126, v131
	v_fma_f32 v135, v131, v126, -v133
	v_fmac_f32_e32 v135, v131, v115
	v_add_f32_e32 v136, v133, v135
	v_sub_f32_e32 v137, v132, v136
	v_sub_f32_e32 v132, v132, v137
	v_sub_f32_e32 v133, v136, v133
	v_sub_f32_e32 v132, v132, v136
	v_add_f32_e32 v130, v130, v132
	v_sub_f32_e32 v132, v133, v135
	v_add_f32_e32 v130, v132, v130
	v_add_f32_e32 v132, v137, v130
	v_mul_f32_e32 v133, v134, v132
	v_mul_f32_e32 v135, v126, v133
	v_fma_f32 v126, v133, v126, -v135
	v_fmac_f32_e32 v126, v133, v115
	v_sub_f32_e32 v115, v137, v132
	v_add_f32_e32 v115, v130, v115
	v_add_f32_e32 v130, v135, v126
	v_sub_f32_e32 v136, v132, v130
	v_sub_f32_e32 v132, v132, v136
	v_sub_f32_e32 v135, v130, v135
	v_sub_f32_e32 v130, v132, v130
	v_add_f32_e32 v115, v115, v130
	v_sub_f32_e32 v126, v135, v126
	v_cvt_f32_i32_e32 v129, v129
	v_add_f32_e32 v115, v126, v115
	v_add_f32_e32 v126, v131, v133
	v_add_f32_e32 v115, v136, v115
	v_sub_f32_e32 v130, v126, v131
	v_mul_f32_e32 v115, v134, v115
	v_sub_f32_e32 v130, v133, v130
	v_add_f32_e32 v115, v130, v115
	v_mul_f32_e32 v133, 0x3f317218, v129
	v_add_f32_e32 v130, v126, v115
	v_fma_f32 v134, v129, s64, -v133
	v_mul_f32_e32 v131, v130, v130
	v_fmac_f32_e32 v134, 0xb102e308, v129
	v_sub_f32_e32 v126, v130, v126
	v_fmamk_f32 v132, v131, 0x3e9b6dac, v120
	v_sub_f32_e32 v115, v115, v126
	v_add_f32_e32 v126, v133, v134
	v_fmaak_f32 v132, v131, v132, 0x3f2aaada
	v_sub_f32_e32 v129, v126, v133
	v_ldexp_f32 v133, v130, 1
	v_mul_f32_e32 v130, v130, v131
	v_mul_f32_e32 v130, v130, v132
	v_add_f32_e32 v131, v133, v130
	v_sub_f32_e32 v132, v131, v133
	v_ldexp_f32 v115, v115, 1
	v_sub_f32_e32 v130, v130, v132
	v_add_f32_e32 v115, v115, v130
	v_add_f32_e32 v130, v131, v115
	v_sub_f32_e32 v131, v130, v131
	v_sub_f32_e32 v115, v115, v131
	v_add_f32_e32 v131, v126, v130
	v_sub_f32_e32 v132, v131, v126
	v_sub_f32_e32 v133, v131, v132
	v_sub_f32_e32 v129, v134, v129
	v_sub_f32_e32 v126, v126, v133
	v_sub_f32_e32 v130, v130, v132
	v_add_f32_e32 v126, v130, v126
	v_add_f32_e32 v130, v129, v115
	v_sub_f32_e32 v132, v130, v129
	v_sub_f32_e32 v133, v130, v132
	v_sub_f32_e32 v129, v129, v133
	v_sub_f32_e32 v115, v115, v132
	v_add_f32_e32 v126, v130, v126
	v_add_f32_e32 v115, v115, v129
	v_add_f32_e32 v129, v131, v126
	v_sub_f32_e32 v130, v129, v131
	v_sub_f32_e32 v126, v126, v130
	v_add_f32_e32 v115, v115, v126
	v_add_f32_e32 v115, v129, v115
	v_cmp_neq_f32_e32 vcc, s62, v104
	v_mul_lo_u32 v129, v128, s67
	v_mul_u32_u24_e32 v126, 0x2100, v123
	v_cndmask_b32_e32 v115, v121, v115, vcc
	v_cmp_lt_f32_e64 vcc, |v104|, s65
	s_nop 1
	v_cndmask_b32_e32 v104, v115, v104, vcc
	v_add_f32_e32 v104, v119, v104
	v_mul_f32_e32 v115, 0xc1000000, v104
	v_lshrrev_b32_e32 v104, 2, v127
	v_ashrrev_i32_e32 v119, 6, v127
	v_and_or_b32 v104, v104, 48, v123
	v_and_b32_e32 v119, 0xffffffc, v119
	v_add_u32_e32 v119, v104, v119
	v_mul_lo_u32 v130, v119, s66
	v_add_u32_e32 v119, 32, v128
	v_lshrrev_b32_e32 v119, 2, v119
	v_and_b32_e32 v119, 0xffffffc, v119
	v_add_u32_e32 v104, v119, v104
	v_mul_lo_u32 v128, v104, s66
	v_and_or_b32 v104, v122, 64, v125
	v_mul_u32_u24_e32 v127, 0x110, v125
	v_lshlrev_b32_e32 v119, 2, v104
	s_mov_b32 s72, 0xbfb8aa3b
	s_mov_b32 s73, 0x4266d4ca
	v_mul_f32_e32 v200, s72, v111
	v_mul_f32_e32 v201, s72, v109
	v_mul_f32_e32 v202, 0x3fb8aa3b, v115
	s_branch .LBB0_494
; #define LAS __attribute__((address_space(3)))
; template <bool PASSB>
; __device__ __forceinline__ void lru_unit(LAS unsigned char* lds, const Params& p, int b, int hd, int chunk) {
;     ...
;             for (int ks = 0; ks < 4; ++ks) {
;                 const bf16x8 a = *(const LAS bf16x8*)(XCB + (tb * 16 + fr) * 272 + (ks * 32 + fq * 8) * 2);
;                 ar = __builtin_amdgcn_mfma_f32_16x16x32_bf16(a, wf[0][ks], ar, 0, 0, 0);
;                 ai = __builtin_amdgcn_mfma_f32_16x16x32_bf16(a, wf[1][ks], ai, 0, 0, 0);
;             }
; #pragma unroll
;             for (int j = 0; j < 4; ++j) {
;                 const int token = fq * 16 + tb * 4 + j;
;                 const float xcv = XCF[token * 132 + chl];
;                 const float e1 = __expf(fminf(-(ar[j] + brv), 40.f)), e2 = __expf(fminf(-(ai[j] + biv), 40.f));
;                 const float inv = __builtin_amdgcn_rcpf((1.0f + e1) * (1.0f + e2));
;                 const float r = inv * (1.0f + e2), ig = inv * (1.0f + e1);
;                 const float a = __expf(clv * r);
;                 const float bb = __builtin_amdgcn_sqrtf(fmaxf(1.0f - a * a, 0.f)) * (ig * xcv);
;                 hrun = a * hrun + bb; prun *= a;
;                 if (PASSB) { hl[tb * 4 + j] = hrun; pl[tb * 4 + j] = prun; }
.LBB0_493:
	s_or_b64 exec, exec, s[12:13]
	v_add3_u32 v132, s28, v110, v127
	ds_read_b128 v[134:137], v132
	ds_read_b128 v[138:141], v132 offset:64
	ds_read_b128 v[146:149], v132 offset:128
	v_lshl_add_u32 v131, v124, 2, s28
	v_lshlrev_b32_e32 v104, 2, v125
	s_waitcnt lgkmcnt(2)
	v_mfma_f32_16x16x32_bf16 v[142:145], v[134:137], v[24:27], 0
	v_add3_u32 v131, v131, v104, v126
	v_add_u32_e32 v133, 0x4400, v131
	ds_read2_b32 v[150:151], v133 offset1:132
	v_mfma_f32_16x16x32_bf16 v[134:137], v[134:137], v[28:31], 0
	s_add_i32 s0, s0, 64
	s_add_i32 s11, s11, 1
	s_cmpk_eq_i32 s0, 0x3c0
	s_waitcnt lgkmcnt(2)
	v_mfma_f32_16x16x32_bf16 v[142:145], v[138:141], v[16:19], v[142:145]
	v_mfma_f32_16x16x32_bf16 v[134:137], v[138:141], v[20:23], v[134:137]
	ds_read_b128 v[138:141], v132 offset:192
	s_waitcnt lgkmcnt(2)
	v_mfma_f32_16x16x32_bf16 v[142:145], v[146:149], v[8:11], v[142:145]
	v_mfma_f32_16x16x32_bf16 v[134:137], v[146:149], v[12:15], v[134:137]
	s_waitcnt lgkmcnt(0)
	v_mfma_f32_16x16x32_bf16 v[142:145], v[138:141], v[0:3], v[142:145]
	v_mfma_f32_16x16x32_bf16 v[134:137], v[138:141], v[4:7], v[134:137]
	s_nop 6
	v_fma_f32 v133, v142, s72, v200
	v_fma_f32 v134, v134, s72, v201
	v_min_f32_e32 v133, s73, v133
	v_min_f32_e32 v134, s73, v134
	v_fma_f32 v138, v143, s72, v200
	v_fma_f32 v135, v135, s72, v201
	v_exp_f32_e32 v133, v133
	v_exp_f32_e32 v134, v134
	v_min_f32_e32 v138, s73, v138
	v_min_f32_e32 v135, s73, v135
	v_exp_f32_e32 v138, v138
	v_exp_f32_e32 v135, v135
	v_add_f32_e32 v133, 1.0, v133
	v_add_f32_e32 v134, 1.0, v134
	v_mul_f32_e32 v139, v133, v134
	v_rcp_f32_e32 v139, v139
	v_add_f32_e32 v138, 1.0, v138
	v_add_f32_e32 v135, 1.0, v135
	v_mul_f32_e32 v140, v138, v135
	v_rcp_f32_e32 v140, v140
	v_mul_f32_e32 v134, v134, v139
	v_mul_f32_e32 v134, v202, v134
	v_mul_f32_e32 v135, v135, v140
	v_mul_f32_e32 v138, v138, v140
	v_fma_f32 v140, v144, s72, v200
	v_fma_f32 v136, v136, s72, v201
	v_exp_f32_e32 v134, v134
	v_min_f32_e32 v140, s73, v140
	v_min_f32_e32 v136, s73, v136
	v_exp_f32_e32 v140, v140
	v_exp_f32_e32 v136, v136
	v_mul_f32_e32 v133, v133, v139
	v_fma_f32 v139, -v134, v134, 1.0 clamp
	v_sqrt_f32_e32 v139, v139
	v_mul_f32_e32 v135, v202, v135
	v_add_f32_e32 v142, 1.0, v140
	v_add_f32_e32 v136, 1.0, v136
	v_mul_f32_e32 v140, v142, v136
	v_exp_f32_e32 v135, v135
	v_rcp_f32_e32 v143, v140
	v_mul_f32_e32 v133, v150, v133
	v_mul_f32_e32 v133, v133, v139
	v_fmac_f32_e32 v133, 0, v134
	v_fma_f32 v139, -v135, v135, 1.0 clamp
	v_mul_f32_e32 v133, v135, v133
	v_mul_f32_e32 v152, v134, v135
	v_mul_f32_e32 v135, v136, v143
	v_mul_f32_e32 v135, v202, v135
	v_sqrt_f32_e32 v139, v139
	v_exp_f32_e32 v153, v135
	v_mul_f32_e32 v138, v151, v138
	v_add_u32_e32 v134, 0x4800, v131
	v_fmac_f32_e32 v133, v138, v139
	ds_read2_b32 v[150:151], v134 offset0:8 offset1:140
	ds_read_b128 v[138:141], v132 offset:4352
	v_fma_f32 v134, -v153, v153, 1.0 clamp
	v_sqrt_f32_e32 v155, v134
	v_fma_f32 v134, v145, s72, v200
	v_min_f32_e32 v134, s73, v134
	v_mul_f32_e32 v154, v142, v143
	ds_read_b128 v[142:145], v132 offset:4416
	v_exp_f32_e32 v156, v134
	v_fma_f32 v134, v137, s72, v201
	v_min_f32_e32 v157, s73, v134
	s_waitcnt lgkmcnt(1)
	v_mfma_f32_16x16x32_bf16 v[146:149], v[138:141], v[24:27], 0
	v_mul_f32_e32 v150, v150, v154
	v_add_f32_e32 v154, 1.0, v156
	v_mul_f32_e32 v133, v153, v133
	v_mfma_f32_16x16x32_bf16 v[134:137], v[138:141], v[28:31], 0
	v_exp_f32_e32 v157, v157
	ds_read_b128 v[138:141], v132 offset:4480
	s_waitcnt lgkmcnt(1)
	v_mfma_f32_16x16x32_bf16 v[146:149], v[142:145], v[16:19], v[146:149]
	v_fmac_f32_e32 v133, v150, v155
	v_add_f32_e32 v156, 1.0, v157
	v_mfma_f32_16x16x32_bf16 v[134:137], v[142:145], v[20:23], v[134:137]
	v_mul_f32_e32 v142, v154, v156
	v_rcp_f32_e32 v157, v142
	ds_read_b128 v[142:145], v132 offset:4544
	s_waitcnt lgkmcnt(1)
	v_mfma_f32_16x16x32_bf16 v[146:149], v[138:141], v[8:11], v[146:149]
	v_mul_f32_e32 v150, v156, v157
	v_mfma_f32_16x16x32_bf16 v[134:137], v[138:141], v[12:15], v[134:137]
	v_mul_f32_e32 v138, v202, v150
	v_exp_f32_e32 v150, v138
	s_waitcnt lgkmcnt(0)
	v_mfma_f32_16x16x32_bf16 v[138:141], v[142:145], v[0:3], v[146:149]
	v_mul_f32_e32 v133, v150, v133
	v_mfma_f32_16x16x32_bf16 v[134:137], v[142:145], v[4:7], v[134:137]
	s_nop 0
	v_fma_f32 v148, -v150, v150, 1.0 clamp
	s_nop 3
	v_fma_f32 v138, v138, s72, v200
	v_min_f32_e32 v138, s73, v138
	v_exp_f32_e32 v138, v138
	v_fma_f32 v134, v134, s72, v201
	v_min_f32_e32 v134, s73, v134
	v_exp_f32_e32 v134, v134
	v_add_f32_e32 v138, 1.0, v138
	v_fma_f32 v139, v139, s72, v200
	v_fma_f32 v135, v135, s72, v201
	v_add_f32_e32 v134, 1.0, v134
	v_mul_f32_e32 v143, v138, v134
	v_rcp_f32_e32 v144, v143
	v_min_f32_e32 v139, s73, v139
	v_min_f32_e32 v135, s73, v135
	v_exp_f32_e32 v139, v139
	v_exp_f32_e32 v135, v135
	v_mul_f32_e32 v134, v134, v144
	v_mul_f32_e32 v134, v202, v134
	v_mul_f32_e32 v147, v154, v157
	v_sqrt_f32_e32 v142, v148
	v_add_f32_e32 v139, 1.0, v139
	v_add_f32_e32 v135, 1.0, v135
	v_mul_f32_e32 v143, v151, v147
	v_exp_f32_e32 v134, v134
	v_mul_f32_e32 v147, v139, v135
	v_rcp_f32_e32 v147, v147
	v_mul_f32_e32 v146, v153, v152
	v_fmac_f32_e32 v133, v143, v142
	v_add_u32_e32 v142, 0x4c00, v131
	v_mul_f32_e32 v145, v150, v146
	ds_read2_b32 v[142:143], v142 offset0:16 offset1:148
	v_fma_f32 v146, -v134, v134, 1.0 clamp
	v_mul_f32_e32 v135, v135, v147
	v_fma_f32 v140, v140, s72, v200
	v_fma_f32 v136, v136, s72, v201
	v_sqrt_f32_e32 v146, v146
	v_mul_f32_e32 v135, v202, v135
	v_min_f32_e32 v140, s73, v140
	v_min_f32_e32 v136, s73, v136
	v_mul_f32_e32 v138, v138, v144
	v_exp_f32_e32 v135, v135
	v_exp_f32_e32 v140, v140
	v_exp_f32_e32 v136, v136
	s_waitcnt lgkmcnt(0)
; #define LAS __attribute__((address_space(3)))
; template <bool PASSB>
; __device__ __forceinline__ void lru_unit(LAS unsigned char* lds, const Params& p, int b, int hd, int chunk) {
;     ...
;             for (int ks = 0; ks < 4; ++ks) {
;                 const bf16x8 a = *(const LAS bf16x8*)(XCB + (tb * 16 + fr) * 272 + (ks * 32 + fq * 8) * 2);
;                 ar = __builtin_amdgcn_mfma_f32_16x16x32_bf16(a, wf[0][ks], ar, 0, 0, 0);
;                 ai = __builtin_amdgcn_mfma_f32_16x16x32_bf16(a, wf[1][ks], ai, 0, 0, 0);
;             }
; #pragma unroll
;             for (int j = 0; j < 4; ++j) {
;                 const int token = fq * 16 + tb * 4 + j;
;                 const float xcv = XCF[token * 132 + chl];
;                 const float e1 = __expf(fminf(-(ar[j] + brv), 40.f)), e2 = __expf(fminf(-(ai[j] + biv), 40.f));
;                 const float inv = __builtin_amdgcn_rcpf((1.0f + e1) * (1.0f + e2));
;                 const float r = inv * (1.0f + e2), ig = inv * (1.0f + e1);
;                 const float a = __expf(clv * r);
;                 const float bb = __builtin_amdgcn_sqrtf(fmaxf(1.0f - a * a, 0.f)) * (ig * xcv);
;                 hrun = a * hrun + bb; prun *= a;
;                 if (PASSB) { hl[tb * 4 + j] = hrun; pl[tb * 4 + j] = prun; }
	v_mul_f32_e32 v138, v142, v138
	v_mul_f32_e32 v138, v138, v146
	v_fmac_f32_e32 v138, v133, v134
	v_mul_f32_e32 v152, v135, v138
	v_add_f32_e32 v138, 1.0, v140
	v_add_f32_e32 v136, 1.0, v136
	v_mul_f32_e32 v140, v138, v136
	v_rcp_f32_e32 v140, v140
	v_mul_f32_e32 v133, v145, v134
	v_mul_f32_e32 v134, v139, v147
	v_fma_f32 v139, -v135, v135, 1.0 clamp
	v_mul_f32_e32 v133, v135, v133
	v_mul_f32_e32 v135, v136, v140
	v_mul_f32_e32 v135, v202, v135
	v_sqrt_f32_e32 v139, v139
	v_exp_f32_e32 v153, v135
	v_mul_f32_e32 v134, v143, v134
	v_fmac_f32_e32 v152, v134, v139
	v_add_u32_e32 v134, 0x5000, v131
	ds_read2_b32 v[150:151], v134 offset0:24 offset1:156
	ds_read_b128 v[142:145], v132 offset:8704
	v_fma_f32 v134, -v153, v153, 1.0 clamp
	v_sqrt_f32_e32 v155, v134
	v_fma_f32 v134, v141, s72, v200
	v_min_f32_e32 v134, s73, v134
	v_mul_f32_e32 v154, v138, v140
	ds_read_b128 v[138:141], v132 offset:8768
	v_exp_f32_e32 v156, v134
	v_fma_f32 v134, v137, s72, v201
	v_min_f32_e32 v157, s73, v134
	s_waitcnt lgkmcnt(1)
	v_mfma_f32_16x16x32_bf16 v[146:149], v[142:145], v[24:27], 0
	v_mul_f32_e32 v150, v150, v154
	v_add_f32_e32 v154, 1.0, v156
	v_mul_f32_e32 v152, v153, v152
	v_mfma_f32_16x16x32_bf16 v[134:137], v[142:145], v[28:31], 0
	v_exp_f32_e32 v157, v157
	ds_read_b128 v[142:145], v132 offset:8832
	s_waitcnt lgkmcnt(1)
	v_mfma_f32_16x16x32_bf16 v[146:149], v[138:141], v[16:19], v[146:149]
	v_fmac_f32_e32 v152, v150, v155
	v_add_f32_e32 v156, 1.0, v157
	v_mul_f32_e32 v133, v153, v133
	v_mfma_f32_16x16x32_bf16 v[134:137], v[138:141], v[20:23], v[134:137]
	v_mul_f32_e32 v138, v154, v156
	v_rcp_f32_e32 v157, v138
	ds_read_b128 v[138:141], v132 offset:8896
	s_waitcnt lgkmcnt(1)
	v_mfma_f32_16x16x32_bf16 v[146:149], v[142:145], v[8:11], v[146:149]
	v_mul_f32_e32 v150, v156, v157
	v_mfma_f32_16x16x32_bf16 v[134:137], v[142:145], v[12:15], v[134:137]
	v_mul_f32_e32 v142, v202, v150
	v_exp_f32_e32 v150, v142
	s_waitcnt lgkmcnt(0)
	v_mfma_f32_16x16x32_bf16 v[142:145], v[138:141], v[0:3], v[146:149]
	v_mul_f32_e32 v133, v150, v133
	v_mfma_f32_16x16x32_bf16 v[134:137], v[138:141], v[4:7], v[134:137]
	s_nop 0
	v_fma_f32 v147, -v150, v150, 1.0 clamp
	s_nop 3
	v_fma_f32 v138, v142, s72, v200
	v_min_f32_e32 v138, s73, v138
	v_exp_f32_e32 v138, v138
	v_fma_f32 v134, v134, s72, v201
	v_min_f32_e32 v134, s73, v134
	v_exp_f32_e32 v134, v134
	v_add_f32_e32 v140, 1.0, v138
	v_fma_f32 v143, v143, s72, v200
	v_add_f32_e32 v134, 1.0, v134
	v_mul_f32_e32 v138, v140, v134
	v_rcp_f32_e32 v141, v138
	v_fma_f32 v135, v135, s72, v201
	v_sqrt_f32_e32 v139, v147
	v_min_f32_e32 v143, s73, v143
	v_mul_f32_e32 v134, v134, v141
	v_mul_f32_e32 v134, v202, v134
	v_min_f32_e32 v135, s73, v135
	v_exp_f32_e32 v134, v134
	v_mul_f32_e32 v146, v154, v157
	v_exp_f32_e32 v143, v143
	v_exp_f32_e32 v135, v135
	v_mul_f32_e32 v138, v151, v146
	v_mul_f32_e32 v142, v150, v152
	v_fmac_f32_e32 v142, v138, v139
	v_add_u32_e32 v138, 0x5400, v131
	ds_read2_b32 v[138:139], v138 offset0:32 offset1:164
	v_fma_f32 v146, -v134, v134, 1.0 clamp
	v_add_f32_e32 v143, 1.0, v143
	v_add_f32_e32 v135, 1.0, v135
	v_mul_f32_e32 v140, v140, v141
	v_fma_f32 v141, v144, s72, v200
	v_fma_f32 v136, v136, s72, v201
	v_sqrt_f32_e32 v146, v146
	v_mul_f32_e32 v147, v143, v135
	v_min_f32_e32 v141, s73, v141
	v_min_f32_e32 v136, s73, v136
	v_rcp_f32_e32 v147, v147
	v_exp_f32_e32 v141, v141
	v_exp_f32_e32 v136, v136
	s_waitcnt lgkmcnt(0)
	v_mul_f32_e32 v138, v138, v140
	v_mul_f32_e32 v138, v138, v146
	v_mul_f32_e32 v135, v135, v147
	v_fmac_f32_e32 v138, v142, v134
	v_mul_f32_e32 v133, v133, v134
	v_mul_f32_e32 v134, v143, v147
	v_mul_f32_e32 v135, v202, v135
	v_mul_f32_e32 v134, v139, v134
	v_add_f32_e32 v139, 1.0, v141
	v_add_f32_e32 v136, 1.0, v136
	v_mul_f32_e32 v141, v139, v136
	v_exp_f32_e32 v135, v135
	v_rcp_f32_e32 v141, v141
	v_mul_f32_e32 v153, v135, v133
	v_mul_f32_e32 v133, v136, v141
	v_fma_f32 v140, -v135, v135, 1.0 clamp
	v_mul_f32_e32 v133, v202, v133
	v_sqrt_f32_e32 v140, v140
	v_exp_f32_e32 v154, v133
	v_mul_f32_e32 v152, v135, v138
	v_add_u32_e32 v133, 0x5800, v131
	v_fmac_f32_e32 v152, v134, v140
	v_fma_f32 v134, -v154, v154, 1.0 clamp
	v_sqrt_f32_e32 v155, v134
	v_fma_f32 v134, v145, s72, v200
	ds_read2_b32 v[150:151], v133 offset0:40 offset1:172
	v_mul_f32_e32 v133, v139, v141
	ds_read_b128 v[138:141], v132 offset:13056
	v_min_f32_e32 v134, s73, v134
	v_exp_f32_e32 v146, v134
	v_fma_f32 v134, v137, s72, v201
	v_min_f32_e32 v147, s73, v134
	ds_read_b128 v[134:137], v132 offset:13120
	v_exp_f32_e32 v147, v147
	s_waitcnt lgkmcnt(1)
	v_mfma_f32_16x16x32_bf16 v[142:145], v[138:141], v[24:27], 0
	v_mul_f32_e32 v133, v150, v133
	v_add_f32_e32 v150, 1.0, v146
	v_add_f32_e32 v156, 1.0, v147
	v_mfma_f32_16x16x32_bf16 v[138:141], v[138:141], v[28:31], 0
	ds_read_b128 v[146:149], v132 offset:13184
	v_mul_f32_e32 v157, v150, v156
	v_rcp_f32_e32 v157, v157
	s_waitcnt lgkmcnt(1)
; #define LAS __attribute__((address_space(3)))
; template <bool PASSB>
; __device__ __forceinline__ void lru_unit(LAS unsigned char* lds, const Params& p, int b, int hd, int chunk) {
;     ...
;             for (int ks = 0; ks < 4; ++ks) {
;                 const bf16x8 a = *(const LAS bf16x8*)(XCB + (tb * 16 + fr) * 272 + (ks * 32 + fq * 8) * 2);
;                 ar = __builtin_amdgcn_mfma_f32_16x16x32_bf16(a, wf[0][ks], ar, 0, 0, 0);
;                 ai = __builtin_amdgcn_mfma_f32_16x16x32_bf16(a, wf[1][ks], ai, 0, 0, 0);
;             }
; #pragma unroll
;             for (int j = 0; j < 4; ++j) {
;                 const int token = fq * 16 + tb * 4 + j;
;                 const float xcv = XCF[token * 132 + chl];
;                 const float e1 = __expf(fminf(-(ar[j] + brv), 40.f)), e2 = __expf(fminf(-(ai[j] + biv), 40.f));
;                 const float inv = __builtin_amdgcn_rcpf((1.0f + e1) * (1.0f + e2));
;                 const float r = inv * (1.0f + e2), ig = inv * (1.0f + e1);
;                 const float a = __expf(clv * r);
;                 const float bb = __builtin_amdgcn_sqrtf(fmaxf(1.0f - a * a, 0.f)) * (ig * xcv);
;                 hrun = a * hrun + bb; prun *= a;
;                 if (PASSB) { hl[tb * 4 + j] = hrun; pl[tb * 4 + j] = prun; }
;             }
;         }
;         const float P0 = __shfl(prun, fr), H0 = __shfl(hrun, fr), P1 = __shfl(prun, fr + 16), H1 = __shfl(hrun, fr + 16);
;         const float P2 = __shfl(prun, fr + 32), H2 = __shfl(hrun, fr + 32), P3 = __shfl(prun, fr + 48), H3 = __shfl(hrun, fr + 48);
;         const float s0 = P0 * Cst + H0, s1 = P1 * s0 + H1, s2 = P2 * s1 + H2, s3 = P3 * s2 + H3;
;         const float cin = fq == 0 ? Cst : (fq == 1 ? s0 : (fq == 2 ? s1 : s2));
;         Cst = s3;
;     ...
;             Pacc *= (P0 * P1) * (P2 * P3);
	v_mfma_f32_16x16x32_bf16 v[142:145], v[134:137], v[16:19], v[142:145]
	v_mul_f32_e32 v152, v154, v152
	v_fmac_f32_e32 v152, v133, v155
	v_mul_f32_e32 v133, v156, v157
	v_mfma_f32_16x16x32_bf16 v[134:137], v[134:137], v[20:23], v[138:141]
	s_nop 2
	ds_read_b128 v[138:141], v132 offset:13248
	v_mul_f32_e32 v132, v202, v133
	s_waitcnt lgkmcnt(1)
	v_mfma_f32_16x16x32_bf16 v[142:145], v[146:149], v[8:11], v[142:145]
	v_exp_f32_e32 v155, v132
	v_mfma_f32_16x16x32_bf16 v[132:135], v[146:149], v[12:15], v[134:137]
	v_fma_f32 v146, -v155, v155, 1.0 clamp
	v_sqrt_f32_e32 v146, v146
	s_waitcnt lgkmcnt(0)
	v_mfma_f32_16x16x32_bf16 v[142:145], v[138:141], v[0:3], v[142:145]
	v_mul_f32_e32 v137, v150, v157
	v_mul_f32_e32 v137, v151, v137
	v_mul_f32_e32 v136, v154, v153
	v_mfma_f32_16x16x32_bf16 v[132:135], v[138:141], v[4:7], v[132:135]
	s_nop 3
	v_fma_f32 v138, v142, s72, v200
	s_nop 2
	v_fma_f32 v132, v132, s72, v201
	v_min_f32_e32 v138, s73, v138
	v_min_f32_e32 v132, s73, v132
	v_exp_f32_e32 v138, v138
	v_exp_f32_e32 v139, v132
	v_mul_f32_e32 v132, v155, v152
	v_fmac_f32_e32 v132, v137, v146
	v_add_f32_e32 v138, 1.0, v138
	v_add_f32_e32 v139, 1.0, v139
	v_mul_f32_e32 v137, v138, v139
	v_rcp_f32_e32 v140, v137
	v_fma_f32 v133, v133, s72, v201
	v_min_f32_e32 v133, s73, v133
	v_mul_f32_e32 v139, v139, v140
	v_mul_f32_e32 v140, v138, v140
	v_mul_f32_e32 v138, v202, v139
	v_fma_f32 v139, v143, s72, v200
	v_min_f32_e32 v139, s73, v139
	v_exp_f32_e32 v139, v139
	v_exp_f32_e32 v133, v133
	v_mul_f32_e32 v142, v155, v136
	v_add_u32_e32 v136, 0x5c00, v131
	v_add_f32_e32 v143, 1.0, v139
	v_add_f32_e32 v146, 1.0, v133
	ds_read2_b32 v[136:137], v136 offset0:48 offset1:180
	v_mul_f32_e32 v133, v143, v146
	v_rcp_f32_e32 v147, v133
	v_exp_f32_e32 v138, v138
	s_waitcnt lgkmcnt(0)
	v_mul_f32_e32 v133, v136, v140
	v_fma_f32 v134, v134, s72, v201
	v_mul_f32_e32 v140, v146, v147
	v_fma_f32 v141, -v138, v138, 1.0 clamp
	v_mul_f32_e32 v140, v202, v140
	v_sqrt_f32_e32 v139, v141
	v_exp_f32_e32 v141, v140
	v_mul_f32_e32 v136, v132, v138
	v_min_f32_e32 v134, s73, v134
	v_pk_fma_f32 v[132:133], v[132:133], v[138:139], v[136:137] op_sel_hi:[1,1,0]
	v_mul_f32_e32 v136, v142, v138
	v_fma_f32 v138, -v141, v141, 1.0 clamp
	v_sqrt_f32_e32 v140, v138
	v_fma_f32 v138, v144, s72, v200
	v_min_f32_e32 v138, s73, v138
	v_exp_f32_e32 v138, v138
	v_exp_f32_e32 v139, v134
	v_mul_f32_e32 v132, v143, v147
	v_mul_f32_e32 v132, v137, v132
	v_add_f32_e32 v142, 1.0, v138
	v_add_f32_e32 v137, 1.0, v139
	v_mul_f32_e32 v138, v142, v137
	v_rcp_f32_e32 v143, v138
	v_mul_f32_e32 v134, v132, v140
	v_pk_fma_f32 v[132:133], v[132:133], v[140:141], v[134:135] op_sel_hi:[1,1,0]
	v_add_u32_e32 v131, 0x6000, v131
	v_mul_f32_e32 v132, v137, v143
	v_mul_f32_e32 v132, v202, v132
	v_exp_f32_e32 v137, v132
	v_fma_f32 v132, v145, s72, v200
	v_min_f32_e32 v132, s73, v132
	v_exp_f32_e32 v134, v132
	v_fma_f32 v132, v135, s72, v201
	v_min_f32_e32 v132, s73, v132
	v_exp_f32_e32 v135, v132
	v_mul_f32_e32 v140, v141, v136
	ds_read2_b32 v[138:139], v131 offset0:56 offset1:188
	v_mul_f32_e32 v131, v142, v143
	v_pk_add_f32 v[134:135], v[134:135], 1.0 op_sel_hi:[1,0]
	v_fma_f32 v132, -v137, v137, 1.0 clamp
	v_mul_f32_e32 v136, v134, v135
	v_rcp_f32_e32 v142, v136
	v_sqrt_f32_e32 v136, v132
	s_waitcnt lgkmcnt(0)
	v_mul_f32_e32 v132, v138, v131
	v_mul_f32_e32 v131, v135, v142
	v_mul_f32_e32 v131, v202, v131
	v_exp_f32_e32 v141, v131
	v_mul_f32_e32 v138, v132, v136
	v_pk_fma_f32 v[132:133], v[132:133], v[136:137], v[138:139] op_sel_hi:[1,1,0]
	v_mul_f32_e32 v131, v137, v140
	v_fma_f32 v132, -v141, v141, 1.0 clamp
	v_sqrt_f32_e32 v140, v132
	v_mul_f32_e32 v132, v134, v142
	v_mul_f32_e32 v132, v139, v132
	v_mul_f32_e32 v134, v133, v141
	v_pk_fma_f32 v[132:133], v[132:133], v[140:141], v[134:135] op_sel_hi:[1,1,0]
	v_mul_f32_e32 v131, v141, v131
	ds_bpermute_b32 v134, v119, v131
	ds_bpermute_b32 v133, v119, v132
	ds_bpermute_b32 v136, v119, v131 offset:64
	ds_bpermute_b32 v138, v119, v132 offset:64
	ds_bpermute_b32 v135, v119, v131 offset:128
	ds_bpermute_b32 v139, v119, v132 offset:128
	ds_bpermute_b32 v132, v119, v132 offset:192
	ds_bpermute_b32 v137, v119, v131 offset:192
	s_waitcnt lgkmcnt(6)
	v_fmac_f32_e32 v133, v113, v134
	s_waitcnt lgkmcnt(4)
	v_fmac_f32_e32 v138, v133, v136
	s_waitcnt lgkmcnt(2)
	v_fmac_f32_e32 v139, v138, v135
	s_waitcnt lgkmcnt(1)
	v_mov_b32_e32 v113, v132
	s_waitcnt lgkmcnt(0)
	v_pk_mul_f32 v[132:133], v[134:135], v[136:137]
	v_fmac_f32_e32 v113, v139, v137
	v_mul_f32_e32 v131, v132, v133
	v_mul_f32_e32 v108, v108, v131
	s_cbranch_scc1 .LBB0_510

; #define LAS __attribute__((address_space(3)))
; #define ATT_LOAD(kbi) do { const int k0_ = (kbi) * 64; _Pragma("unroll") for (int i_ = 0; i_ < 4; ++i_) { const int ci = (tid + 512 * i_) & 1023, hh_ = 2 * hp + (i_ >> 1); \
;         pk[i_] = *(const u32x4*)(Km + (rowbase + k0_ + (ci >> 4)) * 1024 + hh_ * 128 + (ci & 15) * 8); \
;         pv[i_] = *(const u32x4*)(VT + (size_t)(hh_ * 128 + (ci >> 3)) * T + rowbase + k0_ + (ci & 7) * 8); } } while (0)
; __device__ __forceinline__ void attn_unit(LAS unsigned char* lds, const bf16_t* Qm, const bf16_t* Km, const bf16_t* VT, const bf16_t* GBm, bf16_t* YB, int b, int hp, int qb) {
;     int tidl_ = threadIdx.x; asm volatile("" : "+v"(tidl_));
;     const int tid = tidl_, wave = tid >> 6, lane = tid & 63, fr = lane & 15, fq = lane >> 4;
;     const int hsel = wave >> 2, h = 2 * hp + hsel;
;     const int q0 = qb * 64, qw = q0 + (hsel ? 3 - (wave & 3) : (wave & 3)) * 16;
;     const size_t rowbase = (size_t)b * SEQ;
;     LAS unsigned char* KL = lds + hsel * 35840;
;     LAS unsigned char* VL = KL + 17408;
;     volatile LAS int* FL = (volatile LAS int*)(lds + 71680);
;     bf16x8 qf[4];
;     { const bf16_t* qp = Qm + (rowbase + qw + fr) * 1024 + h * 128 + fq * 8;
; #pragma unroll
;       for (int ks = 0; ks < 4; ++ks) qf[ks] = *(const bf16x8*)(qp + ks * 32); }
;     f32x4 o[8];
; #pragma unroll
;     for (int d = 0; d < 8; ++d) o[d] = (f32x4){0.f, 0.f, 0.f, 0.f};
;     float Rs = 1.f;
;     int kb = q0 >> 6;
;     u32x4 pk[4], pv[4];
;     ...
;     ATT_LOAD(kb);
;     int it = 0;
.LBB0_515:
	v_mov_b32_e32 v32, v226
	s_ashr_i32 s0, s39, 4
	s_sub_i32 s0, 0x7f, s0
	v_ashrrev_i32_e32 v33, 6, v32
	v_bitop3_b32 v0, v33, 3, v33 bitop3:0xc
	v_cmp_gt_u32_e32 vcc, s6, v32
	s_lshl_b32 s1, s39, 11
	s_lshl_b32 s56, s0, 6
	v_cndmask_b32_e32 v0, v0, v33, vcc
	s_and_b32 s60, s1, 0x6000
	s_lshl_b32 s1, s39, 8
	v_lshl_add_u32 v44, v0, 4, s56
	s_and_b32 s8, s1, 0x300
	s_and_b32 s61, s0, 0x3ffffff
	s_add_i32 s9, s56, s60
	s_lshl_b32 s0, s60, 1
	v_and_b32_e32 v34, 15, v32
	v_add_u32_e32 v0, s60, v44
	s_add_u32 s0, s26, s0
	v_bitop3_b32 v36, v32, s7, v104 bitop3:0x6c
	v_ashrrev_i32_e32 v35, 8, v32
	v_or_b32_e32 v80, v0, v34
	s_addc_u32 s1, s27, 0
	s_lshl_b64 s[4:5], s[56:57], 1
	v_lshrrev_b32_e32 v88, 4, v36
	v_lshlrev_b64 v[0:1], 11, v[80:81]
	v_lshl_add_u32 v84, v35, 7, s8
	s_add_u32 s4, s0, s4
	v_lshlrev_b32_e32 v22, 4, v32
	v_bfe_u32 v86, v32, 4, 6
	v_bfe_u32 v45, v32, 3, 7
	v_or_b32_e32 v26, s9, v88
	v_mov_b32_e32 v27, v81
	v_lshl_add_u64 v[0:1], s[46:47], 0, v[0:1]
	v_ashrrev_i32_e32 v85, 31, v84
	s_addc_u32 s5, s1, s5
	v_and_b32_e32 v16, 0x70, v22
	v_mov_b32_e32 v17, v81
	v_or_b32_e32 v20, s9, v86
	v_mov_b32_e32 v21, v81
	v_or_b32_e32 v46, s8, v45
	v_lshlrev_b64 v[26:27], 11, v[26:27]
	v_lshlrev_b64 v[82:83], 10, v[80:81]
	v_lshl_add_u64 v[0:1], v[84:85], 1, v[0:1]
	v_and_b32_e32 v80, 48, v32
	v_lshl_add_u64 v[18:19], s[4:5], 0, v[16:17]
	v_lshlrev_b64 v[20:21], 11, v[20:21]
	s_lshl_b32 s12, s8, 1
	s_mov_b32 s13, s57
	v_lshlrev_b32_e32 v24, 16, v46
	v_mov_b32_e32 v25, v81
	v_lshl_add_u64 v[26:27], s[44:45], 0, v[26:27]
	v_lshrrev_b32_e32 v47, 3, v36
	v_lshl_add_u64 v[12:13], v[0:1], 0, v[80:81]
	v_lshl_add_u64 v[20:21], s[44:45], 0, v[20:21]
	v_and_b32_e32 v22, 0xf0, v22
	v_mov_b32_e32 v23, v81
	v_lshl_add_u64 v[24:25], v[18:19], 0, v[24:25]
	v_lshl_add_u64 v[26:27], v[26:27], 0, s[12:13]
	v_or_b32_e32 v56, s8, v47
	v_lshl_add_u64 v[188:189], v[82:83], 0, v[84:85]
	v_bfe_u32 v190, v226, 4, 2
	v_lshl_or_b32 v188, v190, 2, v188
	v_lshlrev_b64 v[188:189], 1, v[188:189]
	v_lshl_add_u64 v[188:189], s[30:31], 0, v[188:189]
	v_and_b32_e32 v190, 1, v190
	v_mul_u32_u24_e32 v190, 24, v190
	v_mov_b32_e32 v191, 0
	v_lshl_add_u64 v[188:189], v[190:191], 0, v[188:189]
	global_load_dwordx4 v[172:175], v[188:189], off
	global_load_dwordx4 v[176:179], v[188:189], off offset:64
	global_load_dwordx4 v[180:183], v[188:189], off offset:128
	global_load_dwordx4 v[184:187], v[188:189], off offset:192
	global_load_dwordx4 v[0:3], v[12:13], off
	global_load_dwordx4 v[4:7], v[12:13], off offset:64
	global_load_dwordx4 v[8:11], v[12:13], off offset:128
	s_nop 0
	global_load_dwordx4 v[12:15], v[12:13], off offset:192
	v_lshl_add_u64 v[20:21], v[20:21], 0, s[12:13]
	v_lshl_add_u64 v[26:27], v[26:27], 0, v[22:23]
	v_lshrrev_b32_e32 v196, 3, v226
	v_and_b32_e32 v197, 7, v226
	v_lshlrev_b32_e32 v197, 4, v197
	v_add_u32_e32 v198, s8, v196
	v_lshlrev_b32_e32 v198, 9, v198
	v_or_b32_e32 v198, v198, v197
	v_mov_b32_e32 v199, 0
	s_mov_b32 s66, 0x8000
	s_mov_b32 s67, 0
	v_lshl_add_u64 v[216:217], v[198:199], 0, s[26:27]
	v_lshl_add_u64 v[218:219], v[216:217], 0, s[66:67]
	v_lshl_add_u64 v[220:221], v[218:219], 0, s[66:67]
	v_lshl_add_u64 v[222:223], v[220:221], 0, s[66:67]
	s_add_i32 s68, s60, s56
	s_lshr_b32 s66, s68, 8
	s_lshl_b32 s66, s66, 19
	s_bfe_u32 s67, s68, 0x20006
	s_lshl_b32 s67, s67, 7
	s_or_b32 s68, s66, s67
	s_mov_b32 s69, 0
	v_lshl_add_u64 v[200:201], v[216:217], 0, s[68:69]
	v_lshl_add_u64 v[202:203], v[218:219], 0, s[68:69]
	v_lshl_add_u64 v[204:205], v[220:221], 0, s[68:69]
	v_lshl_add_u64 v[206:207], v[222:223], 0, s[68:69]
	global_load_dwordx4 v[28:31], v[200:201], off
	global_load_dwordx4 v[40:43], v[26:27], off
	v_lshlrev_b32_e32 v24, 16, v56
	v_mov_b32_e32 v25, v81
	s_or_b32 s58, s8, 0x80
	v_lshl_add_u64 v[20:21], v[20:21], 0, v[22:23]
	v_lshl_add_u64 v[24:25], v[18:19], 0, v[24:25]
	v_or_b32_e32 v57, s58, v45
	global_load_dwordx4 v[36:39], v[20:21], off
	global_load_dwordx4 v[48:51], v[20:21], off offset:256
	v_lshlrev_b32_e32 v20, 16, v57
	v_mov_b32_e32 v21, v81
	global_load_dwordx4 v[52:55], v[202:203], off
	global_load_dwordx4 v[64:67], v[26:27], off offset:256
	v_or_b32_e32 v26, s58, v47
	v_lshl_add_u64 v[20:21], v[18:19], 0, v[20:21]
	v_lshlrev_b32_e32 v24, 16, v26
	v_mov_b32_e32 v25, v81
	v_lshl_add_u64 v[18:19], v[18:19], 0, v[24:25]
	global_load_dwordx4 v[68:71], v[204:205], off
	global_load_dwordx4 v[76:79], v[206:207], off
	v_lshl_add_u64 v[90:91], s[0:1], 0, v[16:17]
	v_lshlrev_b32_e32 v17, 1, v32
	v_and_b32_e32 v21, 3, v32
	v_and_or_b32 v17, v17, 24, v21
	v_add_u32_e32 v21, 16, v32
	v_mul_i32_i24_e32 v19, 0x8c00, v35
	v_and_b32_e32 v21, 63, v21
	v_add_u32_e32 v25, 48, v32
	v_mad_u32_u24 v35, v45, s38, 0
	v_mad_u32_u24 v45, v47, s38, 0
	s_add_u32 s12, s44, s12
	v_and_b32_e32 v25, 63, v25
	s_addc_u32 s13, s45, 0
	v_add_u32_e32 v113, v35, v16
	v_add_u32_e32 v115, v45, v16
	v_or_b32_e32 v16, v105, v21
	v_and_b32_e32 v107, 63, v32
	v_bfe_u32 v106, v32, 4, 2
	v_lshlrev_b32_e32 v18, 15, v46
	v_lshlrev_b32_e32 v20, 15, v56
	v_lshlrev_b32_e32 v24, 15, v57
	v_lshlrev_b32_e32 v26, 15, v26
	v_or_b32_e32 v109, 15, v44
	v_lshl_add_u32 v110, v33, 2, s28
	v_add3_u32 v19, 0, v19, v80
	v_or_b32_e32 v111, v44, v34
	v_mad_u32_u24 v27, v86, s29, 0
	v_mad_u32_u24 v44, v88, s29, 0
	v_lshl_add_u64 v[92:93], s[12:13], 0, v[22:23]
	v_lshl_add_u64 v[32:33], s[44:45], 0, v[22:23]
	v_mul_u32_u24_e32 v17, 0x110, v17
	v_mul_u32_u24_e32 v23, 0x90, v34
	s_lshl_b32 s12, s58, 1
	s_mov_b32 s13, s57
	v_mov_b32_e32 v60, v81
	v_mov_b32_e32 v61, v81
	v_mov_b32_e32 v62, v81
	v_mov_b32_e32 v63, v81
	v_lshlrev_b32_e32 v118, 2, v16
	v_or_b32_e32 v16, v105, v25
	v_lshl_add_u64 v[94:95], v[32:33], 0, s[12:13]
	v_add_u32_e32 v112, v27, v22
	v_add_u32_e32 v114, v44, v22
	v_lshlrev_b32_e32 v80, 1, v18
	v_lshlrev_b32_e32 v98, 1, v20
	v_lshlrev_b32_e32 v100, 1, v24
	v_lshlrev_b32_e32 v102, 1, v26
	v_add_u32_e32 v116, v19, v17
	v_add_u32_e32 v117, v19, v23
	v_lshlrev_b32_e32 v119, 2, v16
	v_mov_b64_e32 v[74:75], v[62:63]
	v_mov_b64_e32 v[56:57], v[60:61]
	v_mov_b64_e32 v[44:45], v[60:61]
	v_mov_b64_e32 v[32:33], v[60:61]
	v_mov_b64_e32 v[24:25], v[60:61]
	v_mov_b64_e32 v[20:21], v[60:61]
	v_mov_b64_e32 v[16:17], v[60:61]
	v_lshlrev_b32_e32 v108, 3, v106
	v_mov_b32_e32 v87, v81
	v_mov_b32_e32 v89, v81
	v_cmp_eq_u32_e64 s[0:1], 3, v106
	v_cmp_gt_u32_e64 s[10:11], 32, v107
	v_cmp_gt_u32_e64 s[4:5], 16, v107
	v_cmp_eq_u32_e64 s[8:9], 0, v107
	s_lshl_b32 s62, s61, 3
	s_sub_i32 s56, s56, 64
	v_mov_b32_e32 v96, 1.0
	s_mov_b32 s63, s57
	v_mov_b64_e32 v[72:73], v[60:61]
	v_mov_b64_e32 v[58:59], v[62:63]
	v_mov_b64_e32 v[46:47], v[62:63]
	v_mov_b64_e32 v[34:35], v[62:63]
	v_mov_b64_e32 v[26:27], v[62:63]
	v_mov_b64_e32 v[22:23], v[62:63]
	v_mov_b64_e32 v[18:19], v[62:63]
	s_mov_b32 s72, 0x12040
	s_mov_b32 s73, 0
	s_branch .LBB0_517
; #define LAS __attribute__((address_space(3)))
; #define ATT_LOAD(kbi) do { const int k0_ = (kbi) * 64; _Pragma("unroll") for (int i_ = 0; i_ < 4; ++i_) { const int ci = (tid + 512 * i_) & 1023, hh_ = 2 * hp + (i_ >> 1); \
;         pk[i_] = *(const u32x4*)(Km + (rowbase + k0_ + (ci >> 4)) * 1024 + hh_ * 128 + (ci & 15) * 8); \
;         pv[i_] = *(const u32x4*)(VT + (size_t)(hh_ * 128 + (ci >> 3)) * T + rowbase + k0_ + (ci & 7) * 8); } } while (0)
; __device__ __forceinline__ void attn_unit(LAS unsigned char* lds, const bf16_t* Qm, const bf16_t* Km, const bf16_t* VT, const bf16_t* GBm, bf16_t* YB, int b, int hp, int qb) {
;     ...
;     for (;;) {
; #pragma unroll
;         for (int i = 0; i < 4; ++i) { const int ci = (tid + 512 * i) & 1023; LAS unsigned char* kd = lds + (i >> 1) * 35840;
;             *(LAS u32x4*)(kd + (ci >> 4) * 272 + (ci & 15) * 16) = pk[i];
;             *(LAS u32x4*)(kd + 17408 + (ci >> 3) * 144 + (ci & 7) * 16) = pv[i]; }
;         __syncthreads();
;         if (kb > 0) ATT_LOAD(kb - 1);
;     ...
;         const bool wdone = __all(Rs == 0.f);
;         if (lane == 0) FL[(it & 1) * 8 + wave] = wdone ? 1 : 0;
;         __syncthreads();
;         int alld = 1;
; #pragma unroll
;         for (int w8 = 0; w8 < 8; ++w8) alld &= FL[(it & 1) * 8 + w8];
;         if (alld || kb == 0) break;
.LBB0_516:
	s_or_b64 exec, exec, s[58:59]
	s_cmp_lg_u32 s62, s63
	s_cbranch_scc0 .LBB0_514
	s_lshl_b32 s12, s64, 2
	s_add_i32 s73, s12, 0x11800
	s_add_i32 s61, s61, -1
	s_add_i32 s63, s63, 8
	s_sub_i32 s56, s56, 64
	v_add_u32_e32 v112, s72, v112
	v_add_u32_e32 v113, s72, v113
	v_add_u32_e32 v114, s72, v114
	v_add_u32_e32 v115, s72, v115
	v_add_u32_e32 v116, s72, v116
	v_add_u32_e32 v117, s72, v117
	s_sub_i32 s72, 0, s72
.LBB0_517:
	s_cmp_lt_i32 s61, 1
	s_waitcnt vmcnt(5)
	ds_write_b128 v112, v[36:39]
	ds_write_b128 v113, v[28:31] offset:17408
	ds_write_b128 v114, v[40:43]
	s_waitcnt vmcnt(3)
	ds_write_b128 v115, v[52:55] offset:17408
	ds_write_b128 v112, v[48:51] offset:35840
	s_waitcnt vmcnt(1)
	ds_write_b128 v113, v[68:71] offset:53248
	ds_write_b128 v114, v[64:67] offset:35840
	s_waitcnt vmcnt(0)
	ds_write_b128 v115, v[76:79] offset:53248
	s_waitcnt lgkmcnt(0)
	s_barrier
	s_cmp_eq_u32 s73, 0
	s_cbranch_scc1 .Lattn_nochk
	v_mov_b32_e32 v97, s73
	ds_read_b32 v99, v97
	ds_read_b32 v101, v97 offset:4
	ds_read_b32 v103, v97 offset:8
	ds_read_b32 v120, v97 offset:12
	ds_read_b32 v121, v97 offset:16
	ds_read_b32 v122, v97 offset:20
	ds_read_b32 v123, v97 offset:24
	ds_read_b32 v97, v97 offset:28
	s_waitcnt lgkmcnt(0)
	v_and_b32_e32 v99, v99, v101
	v_and_b32_e32 v103, v103, v120
	v_and_b32_e32 v121, v121, v122
	v_and_b32_e32 v97, v123, v97
	v_and_b32_e32 v99, v99, v103
	v_and_b32_e32 v97, v121, v97
	v_and_b32_e32 v97, v99, v97
	v_and_b32_e32 v97, 1, v97
	v_cmp_eq_u32_e32 vcc, 0, v97
	s_and_b64 vcc, exec, vcc
	s_cbranch_vccz .LBB0_514
.Lattn_nochk:
	s_cmp_lt_i32 s61, 1
	s_cbranch_scc1 .LBB0_519
	s_add_i32 s12, s56, s60
	v_or_b32_e32 v28, s12, v86
	v_mov_b32_e32 v29, v87
	v_or_b32_e32 v40, s12, v88
	v_mov_b32_e32 v41, v89
	v_lshl_add_u64 v[64:65], s[56:57], 1, v[90:91]
	v_lshlrev_b64 v[48:49], 11, v[28:29]
	v_lshlrev_b64 v[66:67], 11, v[40:41]
	v_mov_b32_e32 v99, v81
	v_mov_b32_e32 v101, v81
	v_mov_b32_e32 v103, v81
	v_lshl_add_u64 v[28:29], v[92:93], 0, v[48:49]
	v_lshl_add_u64 v[30:31], v[64:65], 0, v[80:81]
	v_lshl_add_u64 v[40:41], v[92:93], 0, v[66:67]
	v_lshl_add_u64 v[50:51], v[64:65], 0, v[98:99]
	v_lshl_add_u64 v[48:49], v[94:95], 0, v[48:49]
	v_lshl_add_u64 v[68:69], v[64:65], 0, v[100:101]
	v_lshl_add_u64 v[66:67], v[94:95], 0, v[66:67]
	v_lshl_add_u64 v[76:77], v[64:65], 0, v[102:103]
	s_mov_b32 s68, s12
	s_lshr_b32 s66, s68, 8
	s_lshl_b32 s66, s66, 19
	s_bfe_u32 s67, s68, 0x20006
	s_lshl_b32 s67, s67, 7
	s_or_b32 s68, s66, s67
	s_mov_b32 s69, 0
	v_lshl_add_u64 v[200:201], v[216:217], 0, s[68:69]
	v_lshl_add_u64 v[202:203], v[218:219], 0, s[68:69]
	v_lshl_add_u64 v[204:205], v[220:221], 0, s[68:69]
	v_lshl_add_u64 v[206:207], v[222:223], 0, s[68:69]
	global_load_dwordx4 v[36:39], v[28:29], off
	s_nop 0
	global_load_dwordx4 v[28:31], v[200:201], off
	s_nop 0
	global_load_dwordx4 v[40:43], v[40:41], off
	s_nop 0
	global_load_dwordx4 v[52:55], v[202:203], off
	s_nop 0
	global_load_dwordx4 v[48:51], v[48:49], off
	s_nop 0
	global_load_dwordx4 v[68:71], v[204:205], off
	s_nop 0
	global_load_dwordx4 v[64:67], v[66:67], off
	s_nop 0
	global_load_dwordx4 v[76:79], v[206:207], off

; template <bool PASSB>
; __device__ __forceinline__ void lru_unit(LAS unsigned char* lds, const Params& p, int b, int hd, int chunk) {
;     ...
;     const int gch = hd * 128 + wave * 16 + fr, chl = wave * 16 + fr;
;     const float brv = p.in[9][gch], biv = p.in[11][gch];
;     float clv; { const float L = p.in[12][gch]; clv = -8.0f * (fmaxf(-L, 0.f) + log1pf(expf(-fabsf(L)))); }
;     const int ch8 = (tid & 15) * 8, tok = tid >> 4;
;     float Cst = 0.f, Pacc = 1.f;
;     if (PASSB) {
;         f32x2 e[LRU_NC];
; #pragma unroll
;         for (int j = 0; j < LRU_NC - 1; ++j) { const int jj = j < chunk ? j : 0; e[j] = *(const f32x2*)(AGG + ((size_t)(b * LRU_NC + jj) * 1024 + gch) * 2); }
; #pragma unroll
;         for (int j = 0; j < LRU_NC - 1; ++j) if (j < chunk) Cst = e[j][0] * Cst + e[j][1];
;     }
.LBB0_598:
	s_or_b64 exec, exec, s[60:61]
	s_waitcnt vmcnt(15)
	v_fmac_f32_e32 v125, v124, v129
	v_cndmask_b32_e64 v112, v129, v125, s[0:1]
	s_waitcnt vmcnt(14)
	v_fmac_f32_e32 v109, v108, v112
	v_cndmask_b32_e64 v108, v112, v109, s[14:15]
	s_waitcnt vmcnt(13)
	v_fmac_f32_e32 v107, v106, v108
	v_cndmask_b32_e64 v106, v108, v107, s[4:5]
	s_waitcnt vmcnt(12)
	v_fmac_f32_e32 v105, v104, v106
	v_cndmask_b32_e64 v104, v106, v105, s[8:9]
	v_mul_f32_e64 v105, |v117|, s62
	v_rndne_f32_e32 v106, v105
	v_sub_f32_e32 v107, v105, v106
	v_fma_f32 v105, |v117|, s62, -v105
	s_mov_b32 s0, 0xb2a5705f
	v_fma_f32 v105, |v117|, s0, v105
	v_add_f32_e32 v105, v107, v105
	s_waitcnt vmcnt(11)
	v_fmac_f32_e32 v127, v126, v104
	v_exp_f32_e32 v105, v105
	v_cvt_i32_f32_e32 v106, v106
	v_cndmask_b32_e64 v104, v104, v127, s[12:13]
	s_waitcnt vmcnt(10)
	v_fmac_f32_e32 v111, v110, v104
	v_cndmask_b32_e64 v137, v104, v111, s[10:11]
	v_max_f32_e64 v104, -v117, -v117
	s_mov_b32 s0, 0x42ce8ed0
	v_max_f32_e32 v107, 0, v104
	v_ldexp_f32 v104, v105, v106
	v_cmp_ngt_f32_e64 vcc, |v117|, s0
	s_mov_b32 s0, 0xc2b17218
	s_lshl_b64 s[4:5], s[58:59], 13
	v_cndmask_b32_e32 v104, 0, v104, vcc
	v_cmp_nlt_f32_e64 vcc, |v117|, s0
	s_mov_b32 s0, 0x3f2aaaab
	s_ashr_i32 s9, s83, 31
	v_cndmask_b32_e32 v106, v134, v104, vcc
	v_add_f32_e32 v108, 1.0, v106
	v_add_f32_e32 v104, -1.0, v108
	v_sub_f32_e32 v105, v104, v108
	v_add_f32_e32 v105, 1.0, v105
	v_sub_f32_e32 v104, v106, v104
	v_add_f32_e32 v109, v104, v105
	v_frexp_mant_f32_e32 v110, v108
	v_cvt_f64_f32_e32 v[104:105], v108
	v_frexp_exp_i32_f64_e32 v104, v[104:105]
	v_cmp_gt_f32_e32 vcc, s0, v110
	s_mov_b32 s0, 0x3f317218
	s_add_u32 s8, s83, s4
	v_subbrev_co_u32_e32 v104, vcc, 0, v104, vcc
	v_sub_u32_e32 v105, 0, v104
	v_ldexp_f32 v108, v108, v105
	v_ldexp_f32 v105, v109, v105
	v_add_f32_e32 v109, -1.0, v108
	v_add_f32_e32 v112, 1.0, v108
	v_add_f32_e32 v110, 1.0, v109
	v_add_f32_e32 v117, -1.0, v112
	v_sub_f32_e32 v110, v108, v110
	v_sub_f32_e32 v108, v108, v117
	v_add_f32_e32 v110, v105, v110
	v_add_f32_e32 v105, v105, v108
	v_add_f32_e32 v108, v112, v105
	v_rcp_f32_e32 v117, v108
	v_add_f32_e32 v111, v109, v110
	v_sub_f32_e32 v109, v109, v111
	v_add_f32_e32 v109, v110, v109
	v_sub_f32_e32 v110, v112, v108
	v_add_f32_e32 v105, v105, v110
	v_mul_f32_e32 v110, v111, v117
	v_mul_f32_e32 v112, v108, v110
	v_fma_f32 v119, v110, v108, -v112
	v_fmac_f32_e32 v119, v110, v105
	v_add_f32_e32 v121, v112, v119
	v_sub_f32_e32 v124, v111, v121
	v_sub_f32_e32 v111, v111, v124
	v_sub_f32_e32 v112, v121, v112
	v_sub_f32_e32 v111, v111, v121
	v_add_f32_e32 v109, v109, v111
	v_sub_f32_e32 v111, v112, v119
	v_add_f32_e32 v109, v111, v109
	v_add_f32_e32 v111, v124, v109
	v_mul_f32_e32 v112, v117, v111
	v_mul_f32_e32 v119, v108, v112
	v_fma_f32 v108, v112, v108, -v119
	v_fmac_f32_e32 v108, v112, v105
	v_sub_f32_e32 v105, v124, v111
	v_add_f32_e32 v105, v109, v105
	v_add_f32_e32 v109, v119, v108
	v_sub_f32_e32 v121, v111, v109
	v_sub_f32_e32 v111, v111, v121
	v_sub_f32_e32 v119, v109, v119
	v_sub_f32_e32 v109, v111, v109
	v_add_f32_e32 v105, v105, v109
	v_sub_f32_e32 v108, v119, v108
	v_cvt_f32_i32_e32 v104, v104
	v_add_f32_e32 v105, v108, v105
	v_add_f32_e32 v108, v110, v112
	v_add_f32_e32 v105, v121, v105
	v_sub_f32_e32 v109, v108, v110
	v_mul_f32_e32 v105, v117, v105
	v_sub_f32_e32 v109, v112, v109
	v_add_f32_e32 v105, v109, v105
	v_mul_f32_e32 v112, 0x3f317218, v104
	v_add_f32_e32 v109, v108, v105
	v_fma_f32 v117, v104, s0, -v112
	v_mul_f32_e32 v110, v109, v109
	v_fmac_f32_e32 v117, 0xb102e308, v104
	v_sub_f32_e32 v104, v109, v108
	v_fmamk_f32 v111, v110, 0x3e9b6dac, v132
	v_sub_f32_e32 v104, v105, v104
	v_add_f32_e32 v105, v112, v117
	v_fmaak_f32 v111, v110, v111, 0x3f2aaada
	v_sub_f32_e32 v108, v105, v112
	v_ldexp_f32 v112, v109, 1
	v_mul_f32_e32 v109, v109, v110
	v_mul_f32_e32 v109, v109, v111
	v_add_f32_e32 v110, v112, v109
	v_sub_f32_e32 v111, v110, v112
	v_ldexp_f32 v104, v104, 1
	v_sub_f32_e32 v109, v109, v111
	v_add_f32_e32 v104, v104, v109
	v_add_f32_e32 v109, v110, v104
	v_sub_f32_e32 v110, v109, v110
	v_sub_f32_e32 v104, v104, v110
	v_add_f32_e32 v110, v105, v109
	v_sub_f32_e32 v111, v110, v105
	v_sub_f32_e32 v112, v110, v111
	v_sub_f32_e32 v108, v117, v108
	v_sub_f32_e32 v105, v105, v112
	v_sub_f32_e32 v109, v109, v111
	v_add_f32_e32 v105, v109, v105
	v_add_f32_e32 v109, v108, v104
	v_sub_f32_e32 v111, v109, v108
	v_sub_f32_e32 v112, v109, v111
	v_sub_f32_e32 v108, v108, v112
	v_sub_f32_e32 v104, v104, v111
	v_add_f32_e32 v105, v109, v105
	v_add_f32_e32 v104, v104, v108
	v_add_f32_e32 v108, v110, v105
	v_sub_f32_e32 v109, v108, v110
	v_sub_f32_e32 v105, v105, v109
	v_add_f32_e32 v104, v104, v105
	s_mov_b32 s0, 0x7f800000
	v_add_f32_e32 v104, v108, v104
	v_cmp_neq_f32_e32 vcc, s0, v106
	v_ashrrev_i32_e32 v105, 6, v138
	v_and_b32_e32 v105, 0xffffffc, v105
	v_cndmask_b32_e32 v104, v134, v104, vcc
	v_cmp_lt_f32_e64 vcc, |v106|, s63
	v_mov_b32_e32 v117, v113
	s_addc_u32 s9, s9, s5
	v_cndmask_b32_e32 v104, v104, v106, vcc
	v_add_f32_e32 v104, v107, v104
	v_mul_f32_e32 v119, 0xc1000000, v104
	v_lshrrev_b32_e32 v104, 2, v138
	v_and_or_b32 v104, v104, 48, v135
	v_add_u32_e32 v105, v104, v105
	v_mul_lo_u32 v139, v105, s64
	v_add_u32_e32 v105, 32, v128
	v_lshrrev_b32_e32 v105, 2, v105
	v_and_b32_e32 v105, 0xffffffc, v105
	v_add_u32_e32 v104, v105, v104
	v_mul_lo_u32 v131, v104, s64
	v_lshl_add_u64 v[104:105], s[8:9], 0, v[116:117]
	v_lshlrev_b64 v[104:105], 10, v[104:105]
	v_add_u32_e32 v106, v141, v140
	v_or_b32_e32 v104, s56, v104
	v_ashrrev_i32_e32 v107, 31, v106
	v_lshl_add_u64 v[104:105], v[104:105], 0, v[106:107]
	v_lshl_add_u64 v[124:125], v[104:105], 1, s[78:79]
	v_lshl_add_u32 v104, s82, 10, v128
	s_lshl_b32 s8, s28, 13
	v_subrev_u32_e32 v104, s8, v104
	v_add_u32_e32 v126, 0x60, v104
	v_and_or_b32 v104, v133, 64, v140
	s_mov_b32 s14, 0
	v_cmp_eq_u32_e64 s[0:1], 2, v135
	v_mul_lo_u32 v138, v128, s65
	v_mul_u32_u24_e32 v130, 0x110, v140
	v_mul_u32_u24_e32 v121, 0x2100, v135
	s_mov_b64 s[8:9], 0
	v_lshlrev_b32_e32 v117, 2, v104
	s_mov_b32 s72, 0xbfb8aa3b
	s_mov_b32 s73, 0x4266d4ca
	v_mul_f32_e32 v200, s72, v136
	v_mul_f32_e32 v201, s72, v115
	v_mul_f32_e32 v202, 0x3fb8aa3b, v119
	s_waitcnt vmcnt(0)

; #define LAS __attribute__((address_space(3)))
; template <bool PASSB>
; __device__ __forceinline__ void lru_unit(LAS unsigned char* lds, const Params& p, int b, int hd, int chunk) {
;     ...
;             for (int ks = 0; ks < 4; ++ks) {
;                 const bf16x8 a = *(const LAS bf16x8*)(XCB + (tb * 16 + fr) * 272 + (ks * 32 + fq * 8) * 2);
;                 ar = __builtin_amdgcn_mfma_f32_16x16x32_bf16(a, wf[0][ks], ar, 0, 0, 0);
;                 ai = __builtin_amdgcn_mfma_f32_16x16x32_bf16(a, wf[1][ks], ai, 0, 0, 0);
;             }
; #pragma unroll
;             for (int j = 0; j < 4; ++j) {
;                 const int token = fq * 16 + tb * 4 + j;
;                 const float xcv = XCF[token * 132 + chl];
;                 const float e1 = __expf(fminf(-(ar[j] + brv), 40.f)), e2 = __expf(fminf(-(ai[j] + biv), 40.f));
;                 const float inv = __builtin_amdgcn_rcpf((1.0f + e1) * (1.0f + e2));
;                 const float r = inv * (1.0f + e2), ig = inv * (1.0f + e1);
;                 const float a = __expf(clv * r);
;                 const float bb = __builtin_amdgcn_sqrtf(fmaxf(1.0f - a * a, 0.f)) * (ig * xcv);
;                 hrun = a * hrun + bb; prun *= a;
;                 if (PASSB) { hl[tb * 4 + j] = hrun; pl[tb * 4 + j] = prun; }
.LBB0_615:
	s_or_b64 exec, exec, s[10:11]
	v_add3_u32 v145, s12, v116, v130
	ds_read_b128 v[104:107], v145
	ds_read_b128 v[108:111], v145 offset:64
	ds_read_b128 v[146:149], v145 offset:128
	ds_read_b128 v[150:153], v145 offset:192
	v_lshlrev_b32_e32 v112, 2, v114
	s_waitcnt lgkmcnt(3)
	v_mfma_f32_16x16x32_bf16 v[140:143], v[104:107], v[24:27], 0
	v_mfma_f32_16x16x32_bf16 v[104:107], v[104:107], v[28:31], 0
	s_waitcnt lgkmcnt(2)
	v_mfma_f32_16x16x32_bf16 v[140:143], v[108:111], v[16:19], v[140:143]
	v_mfma_f32_16x16x32_bf16 v[104:107], v[108:111], v[20:23], v[104:107]
	s_waitcnt lgkmcnt(1)
	v_mfma_f32_16x16x32_bf16 v[108:111], v[146:149], v[8:11], v[140:143]
	v_mfma_f32_16x16x32_bf16 v[104:107], v[146:149], v[12:15], v[104:107]
	s_nop 3
	v_add3_u32 v143, s12, v112, v121
	v_add_u32_e32 v127, 0x4400, v143
	s_waitcnt lgkmcnt(0)
	v_mfma_f32_16x16x32_bf16 v[108:111], v[150:153], v[0:3], v[108:111]
	v_mfma_f32_16x16x32_bf16 v[104:107], v[150:153], v[4:7], v[104:107]
	s_nop 6
	v_fma_f32 v108, v108, s72, v200
	v_fma_f32 v104, v104, s72, v201
	v_min_f32_e32 v108, s73, v108
	v_min_f32_e32 v104, s73, v104
	v_exp_f32_e32 v108, v108
	v_exp_f32_e32 v104, v104
	v_fma_f32 v105, v105, s72, v201
	v_min_f32_e32 v105, s73, v105
	v_add_f32_e32 v108, 1.0, v108
	v_add_f32_e32 v129, 1.0, v104
	v_mul_f32_e32 v104, v108, v129
	v_rcp_f32_e32 v140, v104
	v_fma_f32 v109, v109, s72, v200
	v_exp_f32_e32 v128, v105
	ds_read2_b32 v[104:105], v127 offset1:132
	v_mul_f32_e32 v127, v129, v140
	v_min_f32_e32 v109, s73, v109
	v_mul_f32_e32 v127, v202, v127
	v_exp_f32_e32 v109, v109
	v_exp_f32_e32 v127, v127
	v_add_f32_e32 v128, 1.0, v128
	v_mul_f32_e32 v108, v108, v140
	v_add_f32_e32 v109, 1.0, v109
	v_fma_f32 v140, -v127, v127, 1.0 clamp
	v_fma_f32 v110, v110, s72, v200
	v_fma_f32 v106, v106, s72, v201
	v_mul_f32_e32 v129, v109, v128
	v_min_f32_e32 v110, s73, v110
	v_min_f32_e32 v106, s73, v106
	v_rcp_f32_e32 v129, v129
	v_sqrt_f32_e32 v140, v140
	v_exp_f32_e32 v110, v110
	v_exp_f32_e32 v106, v106
	s_waitcnt lgkmcnt(0)
	v_mul_f32_e32 v104, v104, v108
	v_mul_f32_e32 v108, v128, v129
	v_mul_f32_e32 v140, v104, v140
	v_mul_f32_e32 v104, v109, v129
	v_mul_f32_e32 v108, v202, v108
	v_mul_f32_e32 v104, v105, v104
	v_add_f32_e32 v105, 1.0, v110
	v_add_f32_e32 v106, 1.0, v106
	v_mul_f32_e32 v110, v105, v106
	v_exp_f32_e32 v108, v108
	v_rcp_f32_e32 v110, v110
	v_fmac_f32_e32 v140, 0, v127
	v_fma_f32 v109, -v108, v108, 1.0 clamp
	v_mul_f32_e32 v106, v106, v110
	v_mul_f32_e32 v106, v202, v106
	v_sqrt_f32_e32 v109, v109
	v_exp_f32_e32 v158, v106
	v_mul_f32_e32 v141, v108, v140
	v_fmac_f32_e32 v141, v104, v109
	v_add_u32_e32 v104, 0x4800, v143
	ds_read2_b32 v[128:129], v104 offset0:8 offset1:140
	ds_read_b128 v[146:149], v145 offset:4352
	v_fma_f32 v104, -v158, v158, 1.0 clamp
	v_sqrt_f32_e32 v159, v104
	v_fma_f32 v104, v111, s72, v200
	v_min_f32_e32 v104, s73, v104
	v_mul_f32_e32 v142, v127, v108
	v_mul_f32_e32 v144, v105, v110
	ds_read_b128 v[108:111], v145 offset:4416
	v_exp_f32_e32 v154, v104
	v_fma_f32 v104, v107, s72, v201
	v_min_f32_e32 v155, s73, v104
	s_waitcnt lgkmcnt(1)
	v_mfma_f32_16x16x32_bf16 v[150:153], v[146:149], v[24:27], 0
	v_add_f32_e32 v160, 1.0, v154
	v_mul_f32_e32 v128, v128, v144
	v_mul_f32_e32 v144, v158, v141
	v_mfma_f32_16x16x32_bf16 v[104:107], v[146:149], v[28:31], 0
	v_exp_f32_e32 v155, v155
	ds_read_b128 v[146:149], v145 offset:4480
	s_waitcnt lgkmcnt(1)
	v_mfma_f32_16x16x32_bf16 v[150:153], v[108:111], v[16:19], v[150:153]
	v_fmac_f32_e32 v144, v128, v159
	v_add_f32_e32 v161, 1.0, v155
	ds_read_b128 v[154:157], v145 offset:4544
	v_mfma_f32_16x16x32_bf16 v[104:107], v[108:111], v[20:23], v[104:107]
	v_mul_f32_e32 v108, v160, v161
	v_rcp_f32_e32 v162, v108
	s_waitcnt lgkmcnt(1)
	v_mfma_f32_16x16x32_bf16 v[108:111], v[146:149], v[8:11], v[150:153]
	v_mul_f32_e32 v128, v161, v162
	v_mul_f32_e32 v128, v202, v128
	v_mfma_f32_16x16x32_bf16 v[104:107], v[146:149], v[12:15], v[104:107]
	v_exp_f32_e32 v128, v128
	v_mul_f32_e32 v147, v160, v162
	s_waitcnt lgkmcnt(0)
	v_mfma_f32_16x16x32_bf16 v[108:111], v[154:157], v[0:3], v[108:111]
	v_mul_f32_e32 v146, v158, v142
	v_fma_f32 v148, -v128, v128, 1.0 clamp
	v_mfma_f32_16x16x32_bf16 v[104:107], v[154:157], v[4:7], v[104:107]
	v_sqrt_f32_e32 v148, v148
	s_nop 2
	s_nop 0
	v_fma_f32 v108, v108, s72, v200
	v_min_f32_e32 v108, s73, v108
	v_exp_f32_e32 v108, v108
	v_fma_f32 v104, v104, s72, v201
	v_min_f32_e32 v104, s73, v104
	v_exp_f32_e32 v104, v104
	v_add_f32_e32 v108, 1.0, v108
	v_fma_f32 v109, v109, s72, v200
	v_fma_f32 v105, v105, s72, v201
	v_add_f32_e32 v104, 1.0, v104
	v_mul_f32_e32 v149, v108, v104
	v_rcp_f32_e32 v149, v149
	v_min_f32_e32 v109, s73, v109
	v_min_f32_e32 v105, s73, v105
	v_mul_f32_e32 v104, v104, v149
	v_mul_f32_e32 v104, v202, v104
	v_exp_f32_e32 v104, v104
	v_exp_f32_e32 v109, v109
	v_exp_f32_e32 v105, v105
	v_mul_f32_e32 v129, v129, v147
	v_mul_f32_e32 v147, v128, v144
	v_fmac_f32_e32 v147, v129, v148
	v_mul_f32_e32 v148, v128, v146
	v_add_u32_e32 v128, 0x4c00, v143
	ds_read2_b32 v[128:129], v128 offset0:16 offset1:148
	v_fma_f32 v150, -v104, v104, 1.0 clamp
	v_add_f32_e32 v109, 1.0, v109
	v_add_f32_e32 v105, 1.0, v105
	v_sqrt_f32_e32 v150, v150
	v_mul_f32_e32 v151, v109, v105
	v_rcp_f32_e32 v151, v151
	v_mul_f32_e32 v108, v108, v149
	s_waitcnt lgkmcnt(0)
; #define LAS __attribute__((address_space(3)))
; template <bool PASSB>
; __device__ __forceinline__ void lru_unit(LAS unsigned char* lds, const Params& p, int b, int hd, int chunk) {
;     ...
;             for (int ks = 0; ks < 4; ++ks) {
;                 const bf16x8 a = *(const LAS bf16x8*)(XCB + (tb * 16 + fr) * 272 + (ks * 32 + fq * 8) * 2);
;                 ar = __builtin_amdgcn_mfma_f32_16x16x32_bf16(a, wf[0][ks], ar, 0, 0, 0);
;                 ai = __builtin_amdgcn_mfma_f32_16x16x32_bf16(a, wf[1][ks], ai, 0, 0, 0);
;             }
; #pragma unroll
;             for (int j = 0; j < 4; ++j) {
;                 const int token = fq * 16 + tb * 4 + j;
;                 const float xcv = XCF[token * 132 + chl];
;                 const float e1 = __expf(fminf(-(ar[j] + brv), 40.f)), e2 = __expf(fminf(-(ai[j] + biv), 40.f));
;                 const float inv = __builtin_amdgcn_rcpf((1.0f + e1) * (1.0f + e2));
;                 const float r = inv * (1.0f + e2), ig = inv * (1.0f + e1);
;                 const float a = __expf(clv * r);
;                 const float bb = __builtin_amdgcn_sqrtf(fmaxf(1.0f - a * a, 0.f)) * (ig * xcv);
;                 hrun = a * hrun + bb; prun *= a;
;                 if (PASSB) { hl[tb * 4 + j] = hrun; pl[tb * 4 + j] = prun; }
	v_mul_f32_e32 v108, v128, v108
	v_mul_f32_e32 v149, v108, v150
	v_fmac_f32_e32 v149, v147, v104
	v_mul_f32_e32 v150, v148, v104
	v_mul_f32_e32 v104, v109, v151
	v_fma_f32 v109, v110, s72, v200
	v_fma_f32 v106, v106, s72, v201
	v_min_f32_e32 v109, s73, v109
	v_min_f32_e32 v106, s73, v106
	v_exp_f32_e32 v109, v109
	v_exp_f32_e32 v106, v106
	v_mul_f32_e32 v105, v105, v151
	v_mul_f32_e32 v105, v202, v105
	v_add_f32_e32 v109, 1.0, v109
	v_add_f32_e32 v106, 1.0, v106
	v_mul_f32_e32 v110, v109, v106
	v_exp_f32_e32 v105, v105
	v_rcp_f32_e32 v110, v110
	v_mul_f32_e32 v104, v129, v104
	v_fma_f32 v108, -v105, v105, 1.0 clamp
	v_mul_f32_e32 v151, v105, v149
	v_mul_f32_e32 v152, v105, v150
	v_mul_f32_e32 v105, v106, v110
	v_mul_f32_e32 v105, v202, v105
	v_sqrt_f32_e32 v108, v108
	v_exp_f32_e32 v153, v105
	v_mul_f32_e32 v162, v109, v110
	v_fmac_f32_e32 v151, v104, v108
	v_add_u32_e32 v104, 0x5000, v143
	ds_read2_b32 v[128:129], v104 offset0:24 offset1:156
	ds_read_b128 v[154:157], v145 offset:8704
	v_fma_f32 v104, -v153, v153, 1.0 clamp
	v_sqrt_f32_e32 v166, v104
	v_fma_f32 v104, v111, s72, v200
	v_min_f32_e32 v104, s73, v104
	ds_read_b128 v[108:111], v145 offset:8768
	v_exp_f32_e32 v163, v104
	v_fma_f32 v104, v107, s72, v201
	v_min_f32_e32 v164, s73, v104
	s_waitcnt lgkmcnt(1)
	v_mfma_f32_16x16x32_bf16 v[158:161], v[154:157], v[24:27], 0
	v_mul_f32_e32 v167, v128, v162
	v_add_f32_e32 v168, 1.0, v163
	v_mul_f32_e32 v128, v153, v151
	v_mfma_f32_16x16x32_bf16 v[104:107], v[154:157], v[28:31], 0
	v_exp_f32_e32 v164, v164
	ds_read_b128 v[154:157], v145 offset:8832
	s_waitcnt lgkmcnt(1)
	v_mfma_f32_16x16x32_bf16 v[158:161], v[108:111], v[16:19], v[158:161]
	v_fmac_f32_e32 v128, v167, v166
	v_add_f32_e32 v169, 1.0, v164
	ds_read_b128 v[162:165], v145 offset:8896
	v_mfma_f32_16x16x32_bf16 v[104:107], v[108:111], v[20:23], v[104:107]
	v_mul_f32_e32 v108, v168, v169
	v_rcp_f32_e32 v171, v108
	v_mul_f32_e32 v153, v153, v152
	s_waitcnt lgkmcnt(1)
	v_mfma_f32_16x16x32_bf16 v[108:111], v[154:157], v[8:11], v[158:161]
	v_mfma_f32_16x16x32_bf16 v[104:107], v[154:157], v[12:15], v[104:107]
	s_nop 1
	v_mul_f32_e32 v158, v169, v171
	v_mul_f32_e32 v154, v202, v158
	s_waitcnt lgkmcnt(0)
	v_mfma_f32_16x16x32_bf16 v[108:111], v[162:165], v[0:3], v[108:111]
	v_exp_f32_e32 v154, v154
	v_mul_f32_e32 v155, v168, v171
	v_mul_f32_e32 v155, v129, v155
	v_mfma_f32_16x16x32_bf16 v[104:107], v[162:165], v[4:7], v[104:107]
	v_fma_f32 v156, -v154, v154, 1.0 clamp
	s_nop 2
	v_fma_f32 v108, v108, s72, v200
	v_min_f32_e32 v108, s73, v108
	v_exp_f32_e32 v108, v108
	s_nop 0
	v_fma_f32 v104, v104, s72, v201
	v_min_f32_e32 v104, s73, v104
	v_exp_f32_e32 v104, v104
	v_add_f32_e32 v108, 1.0, v108
	v_fma_f32 v109, v109, s72, v200
	v_fma_f32 v105, v105, s72, v201
	v_add_f32_e32 v104, 1.0, v104
	v_mul_f32_e32 v157, v108, v104
	v_rcp_f32_e32 v158, v157
	v_min_f32_e32 v109, s73, v109
	v_min_f32_e32 v105, s73, v105
	v_mul_f32_e32 v104, v104, v158
	v_exp_f32_e32 v109, v109
	v_exp_f32_e32 v105, v105
	v_sqrt_f32_e32 v156, v156
	v_mul_f32_e32 v104, v202, v104
	v_exp_f32_e32 v104, v104
	v_mul_f32_e32 v129, v154, v128
	v_add_f32_e32 v159, 1.0, v109
	v_add_f32_e32 v105, 1.0, v105
	v_fmac_f32_e32 v129, v155, v156
	v_add_u32_e32 v155, 0x5400, v143
	v_mul_f32_e32 v109, v159, v105
	ds_read2_b32 v[156:157], v155 offset0:32 offset1:164
	v_rcp_f32_e32 v160, v109
	v_fma_f32 v155, -v104, v104, 1.0 clamp
	v_fma_f32 v110, v110, s72, v200
	v_fma_f32 v106, v106, s72, v201
	v_sqrt_f32_e32 v155, v155
	v_min_f32_e32 v110, s73, v110
	v_min_f32_e32 v106, s73, v106
	v_mul_f32_e32 v108, v108, v158
	v_mul_f32_e32 v105, v105, v160
	s_waitcnt lgkmcnt(0)
	v_mul_f32_e32 v108, v156, v108
	v_mul_f32_e32 v105, v202, v105
	v_exp_f32_e32 v156, v110
	v_exp_f32_e32 v106, v106
	v_mul_f32_e32 v154, v154, v153
	v_mul_f32_e32 v109, v108, v155
	v_exp_f32_e32 v105, v105
	v_fmac_f32_e32 v109, v129, v104
	v_mul_f32_e32 v155, v154, v104
	v_mul_f32_e32 v104, v159, v160
	v_mul_f32_e32 v104, v157, v104
	v_add_f32_e32 v157, 1.0, v156
	v_add_f32_e32 v106, 1.0, v106
	v_mul_f32_e32 v156, v157, v106
	v_fma_f32 v108, -v105, v105, 1.0 clamp
	v_rcp_f32_e32 v162, v156
	v_sqrt_f32_e32 v108, v108
	v_mul_f32_e32 v110, v105, v109
	v_mul_f32_e32 v156, v105, v155
	v_mul_f32_e32 v105, v106, v162
	v_mul_f32_e32 v105, v202, v105
	v_fmac_f32_e32 v110, v104, v108
	v_add_u32_e32 v104, 0x5800, v143
	v_exp_f32_e32 v106, v105
	ds_read2_b32 v[104:105], v104 offset0:40 offset1:172
	ds_read_b128 v[158:161], v145 offset:13056
	v_mul_f32_e32 v108, v157, v162
	ds_read_b128 v[162:165], v145 offset:13120
	ds_read_b128 v[172:175], v145 offset:13184
	s_waitcnt lgkmcnt(2)
	v_mfma_f32_16x16x32_bf16 v[166:169], v[158:161], v[24:27], 0
	v_fma_f32 v111, v111, s72, v200
	v_fma_f32 v107, v107, s72, v201
	v_min_f32_e32 v111, s73, v111
	v_mfma_f32_16x16x32_bf16 v[158:161], v[158:161], v[28:31], 0
	v_min_f32_e32 v107, s73, v107
	s_waitcnt lgkmcnt(1)
	v_mfma_f32_16x16x32_bf16 v[166:169], v[162:165], v[16:19], v[166:169]
	v_exp_f32_e32 v111, v111
	v_exp_f32_e32 v107, v107
	v_fma_f32 v157, -v106, v106, 1.0 clamp
	v_mfma_f32_16x16x32_bf16 v[158:161], v[162:165], v[20:23], v[158:161]
	ds_read_b128 v[162:165], v145 offset:13248
	v_mul_f32_e32 v104, v104, v108
	v_add_f32_e32 v108, 1.0, v111
	s_waitcnt lgkmcnt(1)
	v_mfma_f32_16x16x32_bf16 v[166:169], v[172:175], v[8:11], v[166:169]
	v_add_f32_e32 v107, 1.0, v107
	v_mul_f32_e32 v111, v108, v107
	v_mfma_f32_16x16x32_bf16 v[158:161], v[172:175], v[12:15], v[158:161]
	v_sqrt_f32_e32 v157, v157
	v_rcp_f32_e32 v171, v111
	v_mul_f32_e32 v111, v106, v110
	s_waitcnt lgkmcnt(0)
; #define LAS __attribute__((address_space(3)))
; template <bool PASSB>
; __device__ __forceinline__ void lru_unit(LAS unsigned char* lds, const Params& p, int b, int hd, int chunk) {
;     ...
;             for (int ks = 0; ks < 4; ++ks) {
;                 const bf16x8 a = *(const LAS bf16x8*)(XCB + (tb * 16 + fr) * 272 + (ks * 32 + fq * 8) * 2);
;                 ar = __builtin_amdgcn_mfma_f32_16x16x32_bf16(a, wf[0][ks], ar, 0, 0, 0);
;                 ai = __builtin_amdgcn_mfma_f32_16x16x32_bf16(a, wf[1][ks], ai, 0, 0, 0);
;             }
; #pragma unroll
;             for (int j = 0; j < 4; ++j) {
;                 const int token = fq * 16 + tb * 4 + j;
;                 const float xcv = XCF[token * 132 + chl];
;                 const float e1 = __expf(fminf(-(ar[j] + brv), 40.f)), e2 = __expf(fminf(-(ai[j] + biv), 40.f));
;                 const float inv = __builtin_amdgcn_rcpf((1.0f + e1) * (1.0f + e2));
;                 const float r = inv * (1.0f + e2), ig = inv * (1.0f + e1);
;                 const float a = __expf(clv * r);
;                 const float bb = __builtin_amdgcn_sqrtf(fmaxf(1.0f - a * a, 0.f)) * (ig * xcv);
;                 hrun = a * hrun + bb; prun *= a;
;                 if (PASSB) { hl[tb * 4 + j] = hrun; pl[tb * 4 + j] = prun; }
;             }
;         }
;         const float P0 = __shfl(prun, fr), H0 = __shfl(hrun, fr), P1 = __shfl(prun, fr + 16), H1 = __shfl(hrun, fr + 16);
;         const float P2 = __shfl(prun, fr + 32), H2 = __shfl(hrun, fr + 32), P3 = __shfl(prun, fr + 48), H3 = __shfl(hrun, fr + 48);
;         const float s0 = P0 * Cst + H0, s1 = P1 * s0 + H1, s2 = P2 * s1 + H2, s3 = P3 * s2 + H3;
;         const float cin = fq == 0 ? Cst : (fq == 1 ? s0 : (fq == 2 ? s1 : s2));
	v_mfma_f32_16x16x32_bf16 v[166:169], v[162:165], v[0:3], v[166:169]
	v_fmac_f32_e32 v111, v104, v157
	v_mul_f32_e32 v104, v107, v171
	v_mul_f32_e32 v145, v106, v156
	v_mfma_f32_16x16x32_bf16 v[160:163], v[162:165], v[4:7], v[158:161]
	v_mul_f32_e32 v106, v108, v171
	s_nop 2
	v_fma_f32 v108, v166, s72, v200
	v_mul_f32_e32 v104, v202, v104
	v_min_f32_e32 v108, s73, v108
	s_nop 0
	v_fma_f32 v157, v160, s72, v201
	v_min_f32_e32 v157, s73, v157
	v_exp_f32_e32 v104, v104
	v_exp_f32_e32 v108, v108
	v_exp_f32_e32 v157, v157
	v_mul_f32_e32 v105, v105, v106
	v_fma_f32 v107, -v104, v104, 1.0 clamp
	v_add_f32_e32 v108, 1.0, v108
	v_add_f32_e32 v158, 1.0, v157
	v_mul_f32_e32 v157, v108, v158
	v_sqrt_f32_e32 v107, v107
	v_rcp_f32_e32 v159, v157
	v_mul_f32_e32 v157, v104, v111
	v_fma_f32 v160, v167, s72, v200
	v_fmac_f32_e32 v157, v105, v107
	v_mul_f32_e32 v105, v158, v159
	v_fma_f32 v161, v161, s72, v201
	v_mul_f32_e32 v105, v202, v105
	v_min_f32_e32 v160, s73, v160
	v_min_f32_e32 v161, s73, v161
	v_exp_f32_e32 v106, v105
	v_exp_f32_e32 v160, v160
	v_exp_f32_e32 v161, v161
	v_mul_f32_e32 v158, v104, v145
	v_add_u32_e32 v104, 0x5c00, v143
	ds_read2_b32 v[104:105], v104 offset0:48 offset1:180
	v_fma_f32 v107, -v106, v106, 1.0 clamp
	v_add_f32_e32 v164, 1.0, v160
	v_add_f32_e32 v160, 1.0, v161
	v_mul_f32_e32 v161, v164, v160
	v_sqrt_f32_e32 v107, v107
	v_rcp_f32_e32 v161, v161
	v_mul_f32_e32 v108, v108, v159
	s_waitcnt lgkmcnt(0)
	v_mul_f32_e32 v104, v104, v108
	v_mul_f32_e32 v159, v104, v107
	v_mul_f32_e32 v104, v160, v161
	v_mul_f32_e32 v104, v202, v104
	v_exp_f32_e32 v104, v104
	v_fmac_f32_e32 v159, v157, v106
	v_mul_f32_e32 v160, v158, v106
	v_mul_f32_e32 v106, v164, v161
	v_mul_f32_e32 v105, v105, v106
	v_fma_f32 v106, v168, s72, v200
	v_fma_f32 v108, v162, s72, v201
	v_fma_f32 v107, -v104, v104, 1.0 clamp
	v_min_f32_e32 v106, s73, v106
	v_min_f32_e32 v108, s73, v108
	v_sqrt_f32_e32 v107, v107
	v_exp_f32_e32 v106, v106
	v_exp_f32_e32 v108, v108
	v_mul_f32_e32 v161, v104, v159
	v_mul_f32_e32 v162, v104, v160
	v_add_u32_e32 v104, 0x6000, v143
	v_fma_f32 v143, v169, s72, v200
	v_fma_f32 v163, v163, s72, v201
	v_fmac_f32_e32 v161, v105, v107
	v_add_f32_e32 v106, 1.0, v106
	v_add_f32_e32 v107, 1.0, v108
	v_min_f32_e32 v143, s73, v143
	v_min_f32_e32 v163, s73, v163
	v_mul_f32_e32 v105, v106, v107
	v_rcp_f32_e32 v108, v105
	v_exp_f32_e32 v143, v143
	v_exp_f32_e32 v163, v163
	ds_read2_b32 v[104:105], v104 offset0:56 offset1:188
	v_mul_f32_e32 v107, v107, v108
	v_add_f32_e32 v164, 1.0, v143
	v_add_f32_e32 v143, 1.0, v163
	v_mul_f32_e32 v107, v202, v107
	v_mul_f32_e32 v163, v164, v143
	v_rcp_f32_e32 v165, v163
	v_exp_f32_e32 v107, v107
	v_mul_f32_e32 v106, v106, v108
	s_waitcnt lgkmcnt(0)
	v_mul_f32_e32 v104, v104, v106
	v_mul_f32_e32 v106, v143, v165
	v_fma_f32 v108, -v107, v107, 1.0 clamp
	v_mul_f32_e32 v106, v202, v106
	v_sqrt_f32_e32 v108, v108
	v_exp_f32_e32 v106, v106
	v_mul_f32_e32 v143, v107, v161
	v_mul_f32_e32 v163, v107, v162
	v_fmac_f32_e32 v143, v104, v108
	v_fma_f32 v104, -v106, v106, 1.0 clamp
	v_sqrt_f32_e32 v104, v104
	v_mul_f32_e32 v107, v164, v165
	v_mul_f32_e32 v105, v105, v107
	v_mul_f32_e32 v164, v106, v143
	v_fmac_f32_e32 v164, v105, v104
	v_lshl_add_u64 v[104:105], v[124:125], 0, s[8:9]
	v_add_co_u32_e32 v166, vcc, 0xa000000, v104
	v_mul_f32_e32 v165, v106, v163
	s_nop 0
	v_addc_co_u32_e32 v167, vcc, 0, v105, vcc
	v_add_co_u32_e32 v168, vcc, 0xa001000, v104
	ds_bpermute_b32 v185, v117, v165
	s_nop 0
	v_addc_co_u32_e32 v169, vcc, 0, v105, vcc
	v_add_co_u32_e32 v172, vcc, 0xa002000, v104
	ds_bpermute_b32 v176, v117, v164
	s_nop 0
	v_addc_co_u32_e32 v173, vcc, 0, v105, vcc
	v_add_co_u32_e32 v190, vcc, 0xa003000, v104
	ds_bpermute_b32 v187, v117, v165 offset:64
	s_nop 0
	v_addc_co_u32_e32 v191, vcc, 0, v105, vcc
	global_load_ushort v189, v[166:167], off
	global_load_ushort v186, v[166:167], off offset:2048
	global_load_ushort v184, v[168:169], off
	global_load_ushort v181, v[168:169], off offset:2048
	global_load_ushort v179, v[172:173], off
	s_nop 0
	global_load_ushort v173, v[172:173], off offset:2048
	s_nop 0
	global_load_ushort v177, v[190:191], off
	global_load_ushort v171, v[190:191], off offset:2048
	v_add_co_u32_e32 v166, vcc, 0xa004000, v104
	ds_bpermute_b32 v182, v117, v164 offset:64
	s_nop 0
	v_addc_co_u32_e32 v167, vcc, 0, v105, vcc
	v_add_co_u32_e32 v168, vcc, 0xa005000, v104
	ds_bpermute_b32 v188, v117, v165 offset:128
	s_nop 0
	v_addc_co_u32_e32 v169, vcc, 0, v105, vcc
	v_add_co_u32_e32 v190, vcc, 0xa006000, v104
	ds_bpermute_b32 v174, v117, v164 offset:128
	s_nop 0
	v_addc_co_u32_e32 v191, vcc, 0, v105, vcc
	v_add_co_u32_e32 v192, vcc, 0xa007000, v104
	ds_bpermute_b32 v175, v117, v165 offset:192
	s_nop 0
	v_addc_co_u32_e32 v193, vcc, 0, v105, vcc
	global_load_ushort v183, v[166:167], off
	global_load_ushort v180, v[166:167], off offset:2048
	global_load_ushort v178, v[168:169], off
	global_load_ushort v172, v[168:169], off offset:2048
	s_nop 0
	global_load_ushort v169, v[190:191], off
	global_load_ushort v167, v[190:191], off offset:2048
	global_load_ushort v168, v[192:193], off
	global_load_ushort v166, v[192:193], off offset:2048
	ds_bpermute_b32 v106, v117, v164 offset:192
	s_waitcnt lgkmcnt(6)
	v_fmac_f32_e32 v176, v137, v185
	s_waitcnt lgkmcnt(4)
	v_fmac_f32_e32 v182, v176, v187
	v_or_b32_e32 v108, 64, v117
	v_or_b32_e32 v107, 0x80, v117
	s_waitcnt lgkmcnt(2)
	v_fmac_f32_e32 v174, v182, v188
	v_cmp_lt_i32_e32 vcc, 0, v135
	s_and_saveexec_b64 s[10:11], vcc
	s_cbranch_execz .LBB0_621
	v_cmp_ne_u32_e32 vcc, 1, v135
	s_and_saveexec_b64 s[12:13], vcc
	s_xor_b64 s[12:13], exec, s[12:13]
	v_cndmask_b32_e64 v137, v174, v182, s[0:1]
	s_andn2_saveexec_b64 s[12:13], s[12:13]
	v_mov_b32_e32 v137, v176
	s_or_b64 exec, exec, s[12:13]

; #define PG8_STAGE(bufoff, gbase, voff) do { _Pragma("unroll") for (int _i = 0; _i < 2; ++_i) \
;         __builtin_amdgcn_global_load_lds((const unsigned*)((const char*)(gbase) + (voff)[_i]), (LAS unsigned*)(lds + (bufoff) + ldsw + _i * 8192), 16, 0, 0); } while (0)
; #define PG8_LDA(dst, b, h) do { _Pragma("unroll") for (int m = 0; m < 4; ++m) _Pragma("unroll") for (int k = 0; k < 2; ++k) dst[m][k] = *(const LAS bf16x8*)(lds + PG8_SA(b, h) + aoff + m * 2048 + k * 1024); } while (0)
; #define PG8_LDB(dst, b, h) do { _Pragma("unroll") for (int n = 0; n < 2; ++n) _Pragma("unroll") for (int k = 0; k < 2; ++k) dst[n][k] = *(const LAS bf16x8*)(lds + PG8_SB(b, h) + boff + n * 2048 + k * 1024); } while (0)
; #define PG8_WAIT_V(n) asm volatile("s_waitcnt vmcnt(" #n ")" ::: "memory")
; #define PG8_WAIT_L(n) asm volatile("s_waitcnt lgkmcnt(" #n ")" ::: "memory")
; #define PG8_BAR __builtin_amdgcn_s_barrier()
; #define PG8_SCHED __builtin_amdgcn_sched_barrier(0)
; template <class Epi, bool ALIGN_EPI = true, bool SP2 = true>
; __device__ __forceinline__ void gemm_phase(LAS unsigned char* lds, const Gemm g, const StaticOrder& S, const Epi& E) {
;     ...
;         const bool has_next = S.next(ui + 1, nxt);
;         const int npm = has_next ? nxt.pm : cur.pm;
;         const char* nB = has_next ? (const char*)g.Bt + (size_t)nxt.pn * tstepB : cB;
;         for (int t = 0; t < nt; t += 2) {
;             const bool last = (t == nt - 2);
;             const char* a1 = PG8_ATILE(cur.pm, t + 1);
;             const char* a2 = last ? PG8_ATILE(npm, 0) : PG8_ATILE(cur.pm, t + 2);
;             const char* a3 = last ? PG8_ATILE(npm, 1) : PG8_ATILE(cur.pm, t + 3);
;             const char* b2 = last ? nB : cB + (size_t)(t + 2) * kstep;
;             const char* b3 = b2 + kstep;
;             if constexpr (SP2) {
;             PG8_LDB(B0, 0, 0); PG8_LDB(B1, 0, 1); PG8_SCHED; PG8_LDA(At, 0, 0); PG8_STAGE(PG8_SA(1, 1), a1 + hstepA, voffA);
;             PG8_WAIT_V(8); PG8_WAIT_L(0); PG8_BAR; PG8_MMA(0, 0, At, B0); PG8_MMA(0, 1, At, B1); PG8_BAR; PG8_SCHED;
;             PG8_LDA(At, 0, 1); PG8_STAGE(PG8_SB(0, 0), b2, voffB); PG8_STAGE(PG8_SB(0, 1), b2 + hstepB, voffB); PG8_STAGE(PG8_SA(0, 0), a2, voffA);
;             PG8_WAIT_V(8); PG8_WAIT_L(0); PG8_BAR; PG8_MMA(1, 0, At, B0); PG8_MMA(1, 1, At, B1); PG8_BAR; PG8_SCHED;
.LBB0_842:
	s_ashr_i32 s19, s18, 31
	s_lshl_b64 s[22:23], s[18:19], 19
	s_add_u32 s24, s6, s22
	s_addc_u32 s25, s7, s23
	s_and_b64 s[22:23], s[0:1], exec
	s_cselect_b32 s5, s25, s47
	s_cselect_b32 s19, s24, s46
	s_ashr_i32 s37, s36, 31
	s_ashr_i32 s63, s62, 31
	s_lshl_b64 s[40:41], s[36:37], 19
	s_lshl_b64 s[28:29], s[62:63], 19
	s_add_u32 s22, s20, s28
	s_addc_u32 s23, s21, s29
	v_readlane_b32 s8, v248, 14
	s_add_u32 s28, s8, s28
	v_readlane_b32 s8, v248, 15
	s_addc_u32 s29, s8, s29
	s_add_u32 s37, s78, s40
	s_addc_u32 s52, s79, s41
	s_add_u32 s53, s46, 0x100
	v_mov_b32_e32 v0, 0
	v_lshl_add_u64 v[146:147], v[138:139], 0, s[40:41]
	v_lshl_add_u64 v[148:149], v[140:141], 0, s[40:41]
	s_addc_u32 s68, s47, 0
	s_mov_b32 s8, -2
	s_mov_b64 s[46:47], 0
	s_add_i32 s69, s8, 2
	s_add_u32 s62, s37, s46
	s_addc_u32 s63, s52, s47
	s_add_u32 s64, s62, 0x2000100
	s_addc_u32 s65, s63, 0
	s_add_u32 s62, s78, s46
	s_addc_u32 s63, s79, s47
	s_add_u32 s66, s62, 0x2000180
	s_addc_u32 s67, s63, 0
	s_add_i32 s8, s8, -11
	ds_read_b128 v[150:153], v161
	ds_read_b128 v[154:157], v161 offset:1024
	ds_read_b128 v[164:167], v161 offset:2048
	ds_read_b128 v[168:171], v161 offset:3072
	ds_read_b128 v[172:175], v162
	ds_read_b128 v[176:179], v162 offset:1024
	ds_read_b128 v[180:183], v162 offset:2048
	ds_read_b128 v[184:187], v162 offset:3072
	s_lshl_b64 s[62:63], s[8:9], 7
	s_add_u32 s8, s20, s62
	s_addc_u32 s62, s21, s63
	s_cmp_lt_u32 s69, 13
	s_cselect_b32 s8, s66, s8
	s_cselect_b32 s62, s67, s62
	s_add_u32 s8, s8, s40
	s_addc_u32 s62, s62, s41
	s_add_u32 s72, s53, s46
	s_addc_u32 s73, s68, s47
	s_cmpk_eq_i32 s46, 0x700
	s_cselect_b32 s67, s23, s65
	s_cselect_b32 s66, s22, s64
	s_cselect_b32 s63, s29, s62
	s_cselect_b32 s62, s28, s8
	s_cselect_b32 s65, s5, s73
	s_cselect_b32 s64, s19, s72
	v_lshl_add_u64 v[220:221], v[146:147], 0, s[46:47]
	s_add_i32 m0, s39, 0xc000
	ds_read_b128 v[188:191], v163
	ds_read_b128 v[192:195], v163 offset:1024
	ds_read_b128 v[196:199], v163 offset:2048
	ds_read_b128 v[200:203], v163 offset:3072
	ds_read_b128 v[204:207], v163 offset:4096
	ds_read_b128 v[208:211], v163 offset:5120
	ds_read_b128 v[212:215], v163 offset:6144
	ds_read_b128 v[216:219], v163 offset:7168
	global_load_lds_dwordx4 v[220:221], off
	v_lshl_add_u64 v[220:221], v[148:149], 0, s[46:47]
	s_add_i32 m0, s39, 0xe000
	s_nop 0
	global_load_lds_dwordx4 v[220:221], off
	s_waitcnt vmcnt(8)
	s_waitcnt lgkmcnt(0)
	s_barrier
	s_setprio 1
	s_waitcnt lgkmcnt(0)
	v_mfma_f32_16x16x32_bf16 v[124:127], v[150:153], v[188:191], 0
	v_mfma_f32_16x16x32_bf16 v[120:123], v[164:167], v[188:191], 0
	v_mfma_f32_16x16x32_bf16 v[108:111], v[150:153], v[196:199], 0
	v_mfma_f32_16x16x32_bf16 v[104:107], v[164:167], v[196:199], 0
	v_mfma_f32_16x16x32_bf16 v[92:95], v[150:153], v[204:207], 0
	v_mfma_f32_16x16x32_bf16 v[88:91], v[164:167], v[204:207], 0
	v_mfma_f32_16x16x32_bf16 v[76:79], v[150:153], v[212:215], 0
	v_mfma_f32_16x16x32_bf16 v[72:75], v[164:167], v[212:215], 0
	v_mfma_f32_16x16x32_bf16 v[124:127], v[154:157], v[192:195], v[124:127]
	v_mfma_f32_16x16x32_bf16 v[120:123], v[168:171], v[192:195], v[120:123]
	v_mfma_f32_16x16x32_bf16 v[108:111], v[154:157], v[200:203], v[108:111]
	v_mfma_f32_16x16x32_bf16 v[104:107], v[168:171], v[200:203], v[104:107]
	v_mfma_f32_16x16x32_bf16 v[92:95], v[154:157], v[208:211], v[92:95]
	v_mfma_f32_16x16x32_bf16 v[88:91], v[168:171], v[208:211], v[88:91]
	v_mfma_f32_16x16x32_bf16 v[76:79], v[154:157], v[216:219], v[76:79]
	v_mfma_f32_16x16x32_bf16 v[72:75], v[168:171], v[216:219], v[72:75]
	s_setprio 0
	s_setprio 1
	v_mfma_f32_16x16x32_bf16 v[116:119], v[172:175], v[188:191], 0
	v_mfma_f32_16x16x32_bf16 v[112:115], v[180:183], v[188:191], 0
	v_mfma_f32_16x16x32_bf16 v[100:103], v[172:175], v[196:199], 0
	v_mfma_f32_16x16x32_bf16 v[96:99], v[180:183], v[196:199], 0
	v_mfma_f32_16x16x32_bf16 v[84:87], v[172:175], v[204:207], 0
	v_mfma_f32_16x16x32_bf16 v[80:83], v[180:183], v[204:207], 0
	v_mfma_f32_16x16x32_bf16 v[68:71], v[172:175], v[212:215], 0
	v_mfma_f32_16x16x32_bf16 v[64:67], v[180:183], v[212:215], 0
	v_mfma_f32_16x16x32_bf16 v[116:119], v[176:179], v[192:195], v[116:119]
	v_mfma_f32_16x16x32_bf16 v[112:115], v[184:187], v[192:195], v[112:115]
	v_mfma_f32_16x16x32_bf16 v[100:103], v[176:179], v[200:203], v[100:103]
	v_mfma_f32_16x16x32_bf16 v[96:99], v[184:187], v[200:203], v[96:99]
	v_mfma_f32_16x16x32_bf16 v[84:87], v[176:179], v[208:211], v[84:87]
	v_mfma_f32_16x16x32_bf16 v[80:83], v[184:187], v[208:211], v[80:83]
	v_mfma_f32_16x16x32_bf16 v[68:71], v[176:179], v[216:219], v[68:71]
	v_mfma_f32_16x16x32_bf16 v[64:67], v[184:187], v[216:219], v[64:67]
	s_setprio 0
	s_barrier
	s_add_i32 s8, s81, s38
	v_lshl_add_u64 v[220:221], s[64:65], 0, v[130:131]
	s_mov_b32 m0, s8
	ds_read_b128 v[188:191], v163 offset:16384
	ds_read_b128 v[192:195], v163 offset:17408
	ds_read_b128 v[196:199], v163 offset:18432
	ds_read_b128 v[200:203], v163 offset:19456
	ds_read_b128 v[204:207], v163 offset:20480
	ds_read_b128 v[208:211], v163 offset:21504
	ds_read_b128 v[212:215], v163 offset:22528
	ds_read_b128 v[216:219], v163 offset:23552
	global_load_lds_dwordx4 v[220:221], off
	s_add_i32 m0, s8, 0x2000
	s_add_u32 s72, s64, 0x40000
	v_lshl_add_u64 v[222:223], s[64:65], 0, v[134:135]
	s_addc_u32 s73, s65, 0
	s_add_i32 s8, s82, s38
	global_load_lds_dwordx4 v[222:223], off
	v_lshl_add_u64 v[224:225], s[72:73], 0, v[130:131]
	s_mov_b32 m0, s8
	s_nop 0
	global_load_lds_dwordx4 v[224:225], off
	v_lshl_add_u64 v[224:225], s[72:73], 0, v[134:135]
	s_add_i32 m0, s8, 0x2000
	s_nop 0
	global_load_lds_dwordx4 v[224:225], off
	v_lshl_add_u64 v[224:225], s[66:67], 0, v[128:129]
	s_mov_b32 m0, s39
	s_nop 0
	global_load_lds_dwordx4 v[224:225], off
	v_lshl_add_u64 v[224:225], s[66:67], 0, v[132:133]
	s_mov_b32 m0, s70
	s_nop 0
	global_load_lds_dwordx4 v[224:225], off
	s_waitcnt vmcnt(8)
	s_waitcnt lgkmcnt(0)
	s_barrier
; #define PG8_STAGE(bufoff, gbase, voff) do { _Pragma("unroll") for (int _i = 0; _i < 2; ++_i) \
;         __builtin_amdgcn_global_load_lds((const unsigned*)((const char*)(gbase) + (voff)[_i]), (LAS unsigned*)(lds + (bufoff) + ldsw + _i * 8192), 16, 0, 0); } while (0)
; #define PG8_LDA(dst, b, h) do { _Pragma("unroll") for (int m = 0; m < 4; ++m) _Pragma("unroll") for (int k = 0; k < 2; ++k) dst[m][k] = *(const LAS bf16x8*)(lds + PG8_SA(b, h) + aoff + m * 2048 + k * 1024); } while (0)
; #define PG8_LDB(dst, b, h) do { _Pragma("unroll") for (int n = 0; n < 2; ++n) _Pragma("unroll") for (int k = 0; k < 2; ++k) dst[n][k] = *(const LAS bf16x8*)(lds + PG8_SB(b, h) + boff + n * 2048 + k * 1024); } while (0)
; #define PG8_MMA(ai, bj, At, Bt) do { __builtin_amdgcn_s_setprio(1); _Pragma("unroll") for (int m = 0; m < 4; ++m) _Pragma("unroll") for (int n = 0; n < 2; ++n) _Pragma("unroll") for (int k = 0; k < 2; ++k) \
;         acc[ai][bj][m][n] = __builtin_amdgcn_mfma_f32_16x16x32_bf16(Bt[n][k], At[m][k], acc[ai][bj][m][n], 0, 0, 0); __builtin_amdgcn_s_setprio(0); } while (0)
; #define PG8_WAIT_V(n) asm volatile("s_waitcnt vmcnt(" #n ")" ::: "memory")
; #define PG8_WAIT_L(n) asm volatile("s_waitcnt lgkmcnt(" #n ")" ::: "memory")
; #define PG8_BAR __builtin_amdgcn_s_barrier()
; #define PG8_SCHED __builtin_amdgcn_sched_barrier(0)
; template <class Epi, bool ALIGN_EPI = true, bool SP2 = true>
; __device__ __forceinline__ void gemm_phase(LAS unsigned char* lds, const Gemm g, const StaticOrder& S, const Epi& E) {
;     ...
;             PG8_WAIT_V(8); PG8_WAIT_L(0); PG8_BAR; PG8_MMA(1, 0, At, B0); PG8_MMA(1, 1, At, B1); PG8_BAR; PG8_SCHED;
;             PG8_LDB(B0, 1, 0); PG8_LDB(B1, 1, 1); PG8_SCHED; PG8_LDA(At, 1, 0); PG8_STAGE(PG8_SA(0, 1), a2 + hstepA, voffA);
;             PG8_WAIT_V(8); PG8_WAIT_L(0); PG8_BAR; PG8_MMA(0, 0, At, B0); PG8_MMA(0, 1, At, B1); PG8_BAR; PG8_SCHED;
	s_setprio 1
	s_waitcnt lgkmcnt(0)
	v_mfma_f32_16x16x32_bf16 v[60:63], v[150:153], v[188:191], 0
	v_mfma_f32_16x16x32_bf16 v[56:59], v[164:167], v[188:191], 0
	v_mfma_f32_16x16x32_bf16 v[44:47], v[150:153], v[196:199], 0
	v_mfma_f32_16x16x32_bf16 v[40:43], v[164:167], v[196:199], 0
	v_mfma_f32_16x16x32_bf16 v[28:31], v[150:153], v[204:207], 0
	v_mfma_f32_16x16x32_bf16 v[24:27], v[164:167], v[204:207], 0
	v_mfma_f32_16x16x32_bf16 v[12:15], v[150:153], v[212:215], 0
	v_mfma_f32_16x16x32_bf16 v[8:11], v[164:167], v[212:215], 0
	v_mfma_f32_16x16x32_bf16 v[60:63], v[154:157], v[192:195], v[60:63]
	v_mfma_f32_16x16x32_bf16 v[56:59], v[168:171], v[192:195], v[56:59]
	v_mfma_f32_16x16x32_bf16 v[44:47], v[154:157], v[200:203], v[44:47]
	v_mfma_f32_16x16x32_bf16 v[40:43], v[168:171], v[200:203], v[40:43]
	v_mfma_f32_16x16x32_bf16 v[28:31], v[154:157], v[208:211], v[28:31]
	v_mfma_f32_16x16x32_bf16 v[24:27], v[168:171], v[208:211], v[24:27]
	v_mfma_f32_16x16x32_bf16 v[12:15], v[154:157], v[216:219], v[12:15]
	v_mfma_f32_16x16x32_bf16 v[8:11], v[168:171], v[216:219], v[8:11]
	s_setprio 0
	s_setprio 1
	v_mfma_f32_16x16x32_bf16 v[52:55], v[172:175], v[188:191], 0
	v_mfma_f32_16x16x32_bf16 v[48:51], v[180:183], v[188:191], 0
	v_mfma_f32_16x16x32_bf16 v[36:39], v[172:175], v[196:199], 0
	v_mfma_f32_16x16x32_bf16 v[32:35], v[180:183], v[196:199], 0
	v_mfma_f32_16x16x32_bf16 v[20:23], v[172:175], v[204:207], 0
	v_mfma_f32_16x16x32_bf16 v[16:19], v[180:183], v[204:207], 0
	v_mfma_f32_16x16x32_bf16 v[4:7], v[172:175], v[212:215], 0
	v_mfma_f32_16x16x32_bf16 v[0:3], v[180:183], v[212:215], 0
	v_mfma_f32_16x16x32_bf16 v[52:55], v[176:179], v[192:195], v[52:55]
	v_mfma_f32_16x16x32_bf16 v[48:51], v[184:187], v[192:195], v[48:51]
	v_mfma_f32_16x16x32_bf16 v[36:39], v[176:179], v[200:203], v[36:39]
	v_mfma_f32_16x16x32_bf16 v[32:35], v[184:187], v[200:203], v[32:35]
	v_mfma_f32_16x16x32_bf16 v[20:23], v[176:179], v[208:211], v[20:23]
	v_mfma_f32_16x16x32_bf16 v[16:19], v[184:187], v[208:211], v[16:19]
	v_mfma_f32_16x16x32_bf16 v[4:7], v[176:179], v[216:219], v[4:7]
	v_mfma_f32_16x16x32_bf16 v[0:3], v[184:187], v[216:219], v[0:3]
	s_setprio 0
	s_barrier
	s_add_i32 s8, 0, 0x18000
	s_add_i32 s72, 0, 0x1c000
	v_add_u32_e32 v168, s8, v159
	v_add_u32_e32 v184, s72, v159
	ds_read_b128 v[150:153], v168
	ds_read_b128 v[154:157], v168 offset:1024
	ds_read_b128 v[164:167], v168 offset:2048
	ds_read_b128 v[168:171], v168 offset:3072
	ds_read_b128 v[172:175], v184
	ds_read_b128 v[176:179], v184 offset:1024
	ds_read_b128 v[180:183], v184 offset:2048
	ds_read_b128 v[184:187], v184 offset:3072
	s_add_u32 s66, s66, 0x40000
	s_addc_u32 s67, s67, 0
	s_mov_b32 m0, s71
	v_lshl_add_u64 v[224:225], s[66:67], 0, v[128:129]
	ds_read_b128 v[188:191], v163 offset:32768
	ds_read_b128 v[192:195], v163 offset:33792
	ds_read_b128 v[196:199], v163 offset:34816
	ds_read_b128 v[200:203], v163 offset:35840
	ds_read_b128 v[204:207], v163 offset:36864
	ds_read_b128 v[208:211], v163 offset:37888
	ds_read_b128 v[212:215], v163 offset:38912
	ds_read_b128 v[216:219], v163 offset:39936
	global_load_lds_dwordx4 v[224:225], off
	v_lshl_add_u64 v[224:225], s[66:67], 0, v[132:133]
	s_mov_b32 m0, s74
	s_nop 0
	global_load_lds_dwordx4 v[224:225], off
	s_waitcnt vmcnt(8)
	s_waitcnt lgkmcnt(0)
	s_barrier
	s_setprio 1
	s_waitcnt lgkmcnt(0)
	v_mfma_f32_16x16x32_bf16 v[124:127], v[150:153], v[188:191], v[124:127]
	v_mfma_f32_16x16x32_bf16 v[120:123], v[164:167], v[188:191], v[120:123]
	v_mfma_f32_16x16x32_bf16 v[108:111], v[150:153], v[196:199], v[108:111]
	v_mfma_f32_16x16x32_bf16 v[104:107], v[164:167], v[196:199], v[104:107]
	v_mfma_f32_16x16x32_bf16 v[92:95], v[150:153], v[204:207], v[92:95]
	v_mfma_f32_16x16x32_bf16 v[88:91], v[164:167], v[204:207], v[88:91]
	v_mfma_f32_16x16x32_bf16 v[76:79], v[150:153], v[212:215], v[76:79]
	v_mfma_f32_16x16x32_bf16 v[72:75], v[164:167], v[212:215], v[72:75]
	v_mfma_f32_16x16x32_bf16 v[124:127], v[154:157], v[192:195], v[124:127]
	v_mfma_f32_16x16x32_bf16 v[120:123], v[168:171], v[192:195], v[120:123]
	v_mfma_f32_16x16x32_bf16 v[108:111], v[154:157], v[200:203], v[108:111]
	v_mfma_f32_16x16x32_bf16 v[104:107], v[168:171], v[200:203], v[104:107]
	v_mfma_f32_16x16x32_bf16 v[92:95], v[154:157], v[208:211], v[92:95]
	v_mfma_f32_16x16x32_bf16 v[88:91], v[168:171], v[208:211], v[88:91]
	v_mfma_f32_16x16x32_bf16 v[76:79], v[154:157], v[216:219], v[76:79]
	v_mfma_f32_16x16x32_bf16 v[72:75], v[168:171], v[216:219], v[72:75]
	s_setprio 0
	s_setprio 1
	v_mfma_f32_16x16x32_bf16 v[116:119], v[172:175], v[188:191], v[116:119]
	v_mfma_f32_16x16x32_bf16 v[112:115], v[180:183], v[188:191], v[112:115]
	v_mfma_f32_16x16x32_bf16 v[100:103], v[172:175], v[196:199], v[100:103]
	v_mfma_f32_16x16x32_bf16 v[96:99], v[180:183], v[196:199], v[96:99]
	v_mfma_f32_16x16x32_bf16 v[84:87], v[172:175], v[204:207], v[84:87]
	v_mfma_f32_16x16x32_bf16 v[80:83], v[180:183], v[204:207], v[80:83]
	v_mfma_f32_16x16x32_bf16 v[68:71], v[172:175], v[212:215], v[68:71]
	v_mfma_f32_16x16x32_bf16 v[64:67], v[180:183], v[212:215], v[64:67]
	v_mfma_f32_16x16x32_bf16 v[116:119], v[176:179], v[192:195], v[116:119]
	v_mfma_f32_16x16x32_bf16 v[112:115], v[184:187], v[192:195], v[112:115]
	v_mfma_f32_16x16x32_bf16 v[100:103], v[176:179], v[200:203], v[100:103]
	v_mfma_f32_16x16x32_bf16 v[96:99], v[184:187], v[200:203], v[96:99]
	v_mfma_f32_16x16x32_bf16 v[84:87], v[176:179], v[208:211], v[84:87]
	v_mfma_f32_16x16x32_bf16 v[80:83], v[184:187], v[208:211], v[80:83]
	v_mfma_f32_16x16x32_bf16 v[68:71], v[176:179], v[216:219], v[68:71]
	v_mfma_f32_16x16x32_bf16 v[64:67], v[184:187], v[216:219], v[64:67]
	s_setprio 0
	s_barrier
; #define PG8_STAGE(bufoff, gbase, voff) do { _Pragma("unroll") for (int _i = 0; _i < 2; ++_i) \
;         __builtin_amdgcn_global_load_lds((const unsigned*)((const char*)(gbase) + (voff)[_i]), (LAS unsigned*)(lds + (bufoff) + ldsw + _i * 8192), 16, 0, 0); } while (0)
; #define PG8_LDA(dst, b, h) do { _Pragma("unroll") for (int m = 0; m < 4; ++m) _Pragma("unroll") for (int k = 0; k < 2; ++k) dst[m][k] = *(const LAS bf16x8*)(lds + PG8_SA(b, h) + aoff + m * 2048 + k * 1024); } while (0)
; #define PG8_MMA(ai, bj, At, Bt) do { __builtin_amdgcn_s_setprio(1); _Pragma("unroll") for (int m = 0; m < 4; ++m) _Pragma("unroll") for (int n = 0; n < 2; ++n) _Pragma("unroll") for (int k = 0; k < 2; ++k) \
;         acc[ai][bj][m][n] = __builtin_amdgcn_mfma_f32_16x16x32_bf16(Bt[n][k], At[m][k], acc[ai][bj][m][n], 0, 0, 0); __builtin_amdgcn_s_setprio(0); } while (0)
; #define PG8_WAIT_V(n) asm volatile("s_waitcnt vmcnt(" #n ")" ::: "memory")
; #define PG8_WAIT_L(n) asm volatile("s_waitcnt lgkmcnt(" #n ")" ::: "memory")
; #define PG8_BAR __builtin_amdgcn_s_barrier()
; #define PG8_SCHED __builtin_amdgcn_sched_barrier(0)
; template <class Epi, bool ALIGN_EPI = true, bool SP2 = true>
; __device__ __forceinline__ void gemm_phase(LAS unsigned char* lds, const Gemm g, const StaticOrder& S, const Epi& E) {
;     ...
;             PG8_LDA(At, 1, 1); PG8_STAGE(PG8_SB(1, 0), b3, voffB); PG8_STAGE(PG8_SB(1, 1), b3 + hstepB, voffB); PG8_STAGE(PG8_SA(1, 0), a3, voffA);
;             PG8_WAIT_V(8); PG8_WAIT_L(0); PG8_BAR; PG8_MMA(1, 0, At, B0); PG8_MMA(1, 1, At, B1); PG8_BAR; PG8_SCHED;
	s_add_i32 s8, s8, s38
	v_lshl_add_u64 v[220:221], v[220:221], 0, s[12:13]
	s_mov_b32 m0, s8
	ds_read_b128 v[188:191], v163 offset:49152
	ds_read_b128 v[192:195], v163 offset:50176
	ds_read_b128 v[196:199], v163 offset:51200
	ds_read_b128 v[200:203], v163 offset:52224
	ds_read_b128 v[204:207], v163 offset:53248
	ds_read_b128 v[208:211], v163 offset:54272
	ds_read_b128 v[212:215], v163 offset:55296
	ds_read_b128 v[216:219], v163 offset:56320
	global_load_lds_dwordx4 v[220:221], off
	s_add_i32 m0, s8, 0x2000
	s_add_u32 s64, s64, 0x40080
	v_lshl_add_u64 v[220:221], v[222:223], 0, s[12:13]
	s_addc_u32 s65, s65, 0
	s_add_i32 s8, s72, s38
	global_load_lds_dwordx4 v[220:221], off
	v_lshl_add_u64 v[220:221], s[64:65], 0, v[130:131]
	s_mov_b32 m0, s8
	s_nop 0
	global_load_lds_dwordx4 v[220:221], off
	v_lshl_add_u64 v[220:221], s[64:65], 0, v[134:135]
	s_add_i32 m0, s8, 0x2000
	s_nop 0
	global_load_lds_dwordx4 v[220:221], off
	v_lshl_add_u64 v[220:221], s[62:63], 0, v[128:129]
	s_mov_b32 m0, s75
	s_nop 0
	global_load_lds_dwordx4 v[220:221], off
	v_lshl_add_u64 v[220:221], s[62:63], 0, v[132:133]
	s_mov_b32 m0, s80
	s_nop 0
	global_load_lds_dwordx4 v[220:221], off
	s_waitcnt vmcnt(8)
	s_waitcnt lgkmcnt(0)
	s_barrier
	s_setprio 1
	s_waitcnt lgkmcnt(0)
	v_mfma_f32_16x16x32_bf16 v[60:63], v[150:153], v[188:191], v[60:63]
	v_mfma_f32_16x16x32_bf16 v[56:59], v[164:167], v[188:191], v[56:59]
	v_mfma_f32_16x16x32_bf16 v[44:47], v[150:153], v[196:199], v[44:47]
	v_mfma_f32_16x16x32_bf16 v[40:43], v[164:167], v[196:199], v[40:43]
	v_mfma_f32_16x16x32_bf16 v[28:31], v[150:153], v[204:207], v[28:31]
	v_mfma_f32_16x16x32_bf16 v[24:27], v[164:167], v[204:207], v[24:27]
	v_mfma_f32_16x16x32_bf16 v[12:15], v[150:153], v[212:215], v[12:15]
	v_mfma_f32_16x16x32_bf16 v[8:11], v[164:167], v[212:215], v[8:11]
	v_mfma_f32_16x16x32_bf16 v[60:63], v[154:157], v[192:195], v[60:63]
	v_mfma_f32_16x16x32_bf16 v[56:59], v[168:171], v[192:195], v[56:59]
	v_mfma_f32_16x16x32_bf16 v[44:47], v[154:157], v[200:203], v[44:47]
	v_mfma_f32_16x16x32_bf16 v[40:43], v[168:171], v[200:203], v[40:43]
	v_mfma_f32_16x16x32_bf16 v[28:31], v[154:157], v[208:211], v[28:31]
	v_mfma_f32_16x16x32_bf16 v[24:27], v[168:171], v[208:211], v[24:27]
	v_mfma_f32_16x16x32_bf16 v[12:15], v[154:157], v[216:219], v[12:15]
	v_mfma_f32_16x16x32_bf16 v[8:11], v[168:171], v[216:219], v[8:11]
	s_setprio 0
	s_setprio 1
	v_mfma_f32_16x16x32_bf16 v[52:55], v[172:175], v[188:191], v[52:55]
	v_mfma_f32_16x16x32_bf16 v[48:51], v[180:183], v[188:191], v[48:51]
	v_mfma_f32_16x16x32_bf16 v[36:39], v[172:175], v[196:199], v[36:39]
	v_mfma_f32_16x16x32_bf16 v[32:35], v[180:183], v[196:199], v[32:35]
	v_mfma_f32_16x16x32_bf16 v[20:23], v[172:175], v[204:207], v[20:23]
	v_mfma_f32_16x16x32_bf16 v[16:19], v[180:183], v[204:207], v[16:19]
	v_mfma_f32_16x16x32_bf16 v[4:7], v[172:175], v[212:215], v[4:7]
	v_mfma_f32_16x16x32_bf16 v[0:3], v[180:183], v[212:215], v[0:3]
	v_mfma_f32_16x16x32_bf16 v[52:55], v[176:179], v[192:195], v[52:55]
	v_mfma_f32_16x16x32_bf16 v[48:51], v[184:187], v[192:195], v[48:51]
	v_mfma_f32_16x16x32_bf16 v[36:39], v[176:179], v[200:203], v[36:39]
	v_mfma_f32_16x16x32_bf16 v[32:35], v[184:187], v[200:203], v[32:35]
	v_mfma_f32_16x16x32_bf16 v[20:23], v[176:179], v[208:211], v[20:23]
	v_mfma_f32_16x16x32_bf16 v[16:19], v[184:187], v[208:211], v[16:19]
	v_mfma_f32_16x16x32_bf16 v[4:7], v[176:179], v[216:219], v[4:7]
	v_mfma_f32_16x16x32_bf16 v[0:3], v[184:187], v[216:219], v[0:3]
	s_setprio 0
	s_barrier
	s_add_u32 s46, s46, 0x100
	s_addc_u32 s47, s47, 0
	s_cmp_gt_u32 s69, 13
	s_mov_b32 s8, s69

; template <bool PASSB>
; __device__ __forceinline__ void s5_phase(LAS unsigned char* lds, const Params& p) {
;     ...
;         const size_t row0 = (size_t)b * SEQ + (size_t)c * S5_LC;
;         const bf16_t* up = U + ((size_t)g * T + row0 + fr) * 16 + (fq & 1) * 8;
;         bf16x8 au_q0 = (fq < 2) ? *(const bf16x8*)up : zero8;
;         bf16x8 au_q1 = (fq < 2) ? *(const bf16x8*)(up + (size_t)1 * 16 * 16) : zero8;
;         bf16x8 au_q2 = (fq < 2) ? *(const bf16x8*)(up + (size_t)2 * 16 * 16) : zero8;
;         constexpr int NST = S5_LC / 16;
.LBB0_1092:
	s_or_b64 exec, exec, s[24:25]
	v_and_b32_e32 v1, 63, v105
	v_lshl_or_b32 v98, v1, 15, v72
	v_mov_b32_e32 v99, v73
	v_lshl_add_u64 v[64:65], v[98:99], 0, v[64:65]
	v_lshl_add_u64 v[64:65], v[64:65], 0, v[66:67]
	v_lshlrev_b32_e32 v2, 5, v93
	v_mov_b32_e32 v3, v0
	v_lshlrev_b64 v[64:65], 5, v[64:65]
	v_lshl_add_u64 v[2:3], v[82:83], 0, v[2:3]
	v_mov_b32_e32 v89, v88
	v_mov_b32_e32 v93, v92
	v_lshl_add_u64 v[98:99], v[84:85], 0, v[64:65]
	s_mov_b32 s23, 0
	v_mov_b64_e32 v[100:101], v[86:87]
	v_or_b32_e32 v145, v97, v101
	v_or_b32_e32 v144, v96, v100
	v_lshlrev_b64 v[144:145], 11, v[144:145]
	s_mov_b64 s[80:81], 0x1000
	v_lshl_add_u64 v[144:145], v[2:3], 0, v[144:145]
	v_lshl_add_u64 v[146:147], v[144:145], 0, s[80:81]
	s_mov_b64 s[82:83], 0x8000
	v_add_u32_e32 v158, 0x2800, v109
	v_add_u32_e32 v159, 0x2c40, v109
	v_add_u32_e32 v160, 0x3080, v109
	v_add_u32_e32 v161, 0x34c0, v109
	s_branch .LBB0_1094
; #define LAS __attribute__((address_space(3)))
; __device__ __forceinline__ unsigned cvt_pk_bf16(float lo, float hi) { unsigned r; asm volatile("v_cvt_pk_bf16_f32 %0, %1, %2" : "=v"(r) : "v"(lo), "v"(hi)); return r; }
; template <bool PASSB>
; __device__ __forceinline__ void s5_phase(LAS unsigned char* lds, const Params& p) {
;     ...
;         for (int st = 0; st < NST; ++st) {
;             const size_t r0 = row0 + st * 16;
;             const bf16x8 au = au_q0; au_q0 = au_q1; au_q1 = au_q2;
;             if (st + 3 < NST) au_q2 = (fq < 2) ? *(const bf16x8*)(up + (size_t)(st + 3) * 16 * 16) : zero8;
; #pragma unroll
;             for (int nb = 0; nb < 8; ++nb) {
;                 const f32x4 d = __builtin_amdgcn_mfma_f32_16x16x32_bf16(au, bfm[nb], (f32x4){0.f, 0.f, 0.f, 0.f}, 0, 0, 0);
;                 *(LAS f32x4*)(BuL + (nb * 16 + fr) * 20 + fq * 4) = d;
;             }
;             LDS_WAIT();
;             f32x4 br4[4], bi4[4];
; #pragma unroll
;             for (int q = 0; q < 4; ++q) { br4[q] = *(const LAS f32x4*)(BuL + lane * 20 + q * 4); bi4[q] = *(const LAS f32x4*)(BuL + (64 + lane) * 20 + q * 4); }
; #pragma unroll
;             for (int t = 0; t < 16; ++t) {
;                 const float bur = br4[t >> 2][t & 3], bui = bi4[t >> 2][t & 3];
;                 const float nr = are * hr - aim * hi + bur, ni = are * hi + aim * hr + bui; hr = nr; hi = ni;
;                 if (PASSB) *(LAS unsigned*)(HbL + t * 272 + lane * 4) = cvt_pk_bf16(hr, hi);
;             }
;             if (PASSB) {
;                 LDS_WAIT();
;                 f32x4 y = __builtin_amdgcn_mfma_f32_16x16x32_bf16(au, dfm, (f32x4){0.f, 0.f, 0.f, 0.f}, 0, 0, 0);
; #pragma unroll
;                 for (int ks = 0; ks < 4; ++ks) {
;                     const bf16x8 a = *(const LAS bf16x8*)(HbL + fr * 272 + (ks * 32 + fq * 8) * 2);
;                     y = __builtin_amdgcn_mfma_f32_16x16x32_bf16(a, cfm[ks], y, 0, 0, 0);
;                 }
; #pragma unroll
;                 for (int j = 0; j < 4; ++j) {
;                     const float v = y[j];
;                     const float ge = v * sigmoidf_(1.5957691216057308f * (v + 0.044715f * v * v * v));
;                     YG[(r0 + fq * 4 + j) * 1024 + g * 16 + fr] = (bf16_t)(cvt_pk_bf16(ge, ge) & 0xffffu);
;                 }
;             }
;             LDS_WAIT();
;         }
.LBB0_1093:
	s_or_b64 exec, exec, s[24:25]
	v_mfma_f32_16x16x32_bf16 v[112:115], v[68:71], v[8:11], 0
	v_mfma_f32_16x16x32_bf16 v[116:119], v[68:71], v[4:7], 0
	s_nop 6
	ds_write_b128 v107, v[112:115]
	s_add_i32 s23, s23, 1
	v_mfma_f32_16x16x32_bf16 v[120:123], v[68:71], v[16:19], 0
	v_lshl_add_u64 v[98:99], v[98:99], 0, s[64:65]
	s_cmp_eq_u32 s23, 32
	v_mfma_f32_16x16x32_bf16 v[124:127], v[68:71], v[12:15], 0
	ds_write_b128 v107, v[116:119] offset:1280
	s_nop 3
	ds_write_b128 v107, v[120:123] offset:2560
	s_nop 1
	ds_write_b128 v107, v[124:127] offset:3840
	v_mfma_f32_16x16x32_bf16 v[128:131], v[68:71], v[20:23], 0
	v_mfma_f32_16x16x32_bf16 v[112:115], v[68:71], v[24:27], 0
	v_mfma_f32_16x16x32_bf16 v[116:119], v[68:71], v[28:31], 0
	s_nop 5
	ds_write_b128 v107, v[128:131] offset:5120
	ds_write_b128 v107, v[112:115] offset:6400
	ds_write_b128 v107, v[116:119] offset:7680
	v_mfma_f32_16x16x32_bf16 v[112:115], v[68:71], v[32:35], 0
	v_mfma_f32_16x16x32_bf16 v[68:71], v[68:71], v[52:55], 0
	s_nop 6
	ds_write_b128 v107, v[112:115] offset:8960
	s_waitcnt lgkmcnt(0)
	ds_read_b128 v[112:115], v108
	ds_read_b128 v[116:119], v108 offset:16
	ds_read_b128 v[120:123], v108 offset:32
	ds_read_b128 v[124:127], v108 offset:48
	ds_read_b128 v[128:131], v108 offset:5120
	ds_read_b128 v[132:135], v108 offset:5136
	ds_read_b128 v[136:139], v108 offset:5152
	ds_read_b128 v[140:143], v108 offset:5168
	s_waitcnt lgkmcnt(3)
	v_fmac_f32_e32 v112, v88, v94
	v_fmac_f32_e32 v128, v88, v95
	v_fma_f32 v112, -v92, v95, v112
	v_fmac_f32_e32 v128, v92, v94
	v_cvt_pk_bf16_f32 v1, v112, v128
	v_fmac_f32_e32 v113, v88, v112
	v_fmac_f32_e32 v129, v88, v128
	v_fma_f32 v113, -v92, v128, v113
	v_fmac_f32_e32 v129, v92, v112
	v_cvt_pk_bf16_f32 v152, v113, v129
	ds_write2_b32 v158, v1, v152 offset0:0 offset1:68
	v_fmac_f32_e32 v114, v88, v113
	v_fmac_f32_e32 v130, v88, v129
	v_fma_f32 v114, -v92, v129, v114
	v_fmac_f32_e32 v130, v92, v113
	v_cvt_pk_bf16_f32 v1, v114, v130
	v_fmac_f32_e32 v115, v88, v114
	v_fmac_f32_e32 v131, v88, v130
	v_fma_f32 v115, -v92, v130, v115
	v_fmac_f32_e32 v131, v92, v114
	v_cvt_pk_bf16_f32 v152, v115, v131
	ds_write2_b32 v158, v1, v152 offset0:136 offset1:204
	s_waitcnt lgkmcnt(4)
	v_fmac_f32_e32 v116, v88, v115
	v_fmac_f32_e32 v132, v88, v131
	v_fma_f32 v116, -v92, v131, v116
	v_fmac_f32_e32 v132, v92, v115
	v_cvt_pk_bf16_f32 v1, v116, v132
	v_fmac_f32_e32 v117, v88, v116
	v_fmac_f32_e32 v133, v88, v132
	v_fma_f32 v117, -v92, v132, v117
	v_fmac_f32_e32 v133, v92, v116
	v_cvt_pk_bf16_f32 v152, v117, v133
	ds_write2_b32 v159, v1, v152 offset0:0 offset1:68
	v_fmac_f32_e32 v118, v88, v117
	v_fmac_f32_e32 v134, v88, v133
	v_fma_f32 v118, -v92, v133, v118
	v_fmac_f32_e32 v134, v92, v117
	v_cvt_pk_bf16_f32 v1, v118, v134
	v_fmac_f32_e32 v119, v88, v118
	v_fmac_f32_e32 v135, v88, v134
	v_fma_f32 v119, -v92, v134, v119
	v_fmac_f32_e32 v135, v92, v118
	v_cvt_pk_bf16_f32 v152, v119, v135
	ds_write2_b32 v159, v1, v152 offset0:136 offset1:204
	s_waitcnt lgkmcnt(5)
	v_fmac_f32_e32 v120, v88, v119
	v_fmac_f32_e32 v136, v88, v135
	v_fma_f32 v120, -v92, v135, v120
	v_fmac_f32_e32 v136, v92, v119
	v_cvt_pk_bf16_f32 v1, v120, v136
	v_fmac_f32_e32 v121, v88, v120
	v_fmac_f32_e32 v137, v88, v136
	v_fma_f32 v121, -v92, v136, v121
	v_fmac_f32_e32 v137, v92, v120
	v_cvt_pk_bf16_f32 v152, v121, v137
	ds_write2_b32 v160, v1, v152 offset0:0 offset1:68
	v_fmac_f32_e32 v122, v88, v121
	v_fmac_f32_e32 v138, v88, v137
	v_fma_f32 v122, -v92, v137, v122
	v_fmac_f32_e32 v138, v92, v121
	v_cvt_pk_bf16_f32 v1, v122, v138
	v_fmac_f32_e32 v123, v88, v122
	v_fmac_f32_e32 v139, v88, v138
	v_fma_f32 v123, -v92, v138, v123
	v_fmac_f32_e32 v139, v92, v122
	v_cvt_pk_bf16_f32 v152, v123, v139
	ds_write2_b32 v160, v1, v152 offset0:136 offset1:204
	s_waitcnt lgkmcnt(6)
	v_fmac_f32_e32 v124, v88, v123
	v_fmac_f32_e32 v140, v88, v139
	v_fma_f32 v124, -v92, v139, v124
	v_fmac_f32_e32 v140, v92, v123
	v_cvt_pk_bf16_f32 v1, v124, v140
	v_fmac_f32_e32 v125, v88, v124
	v_fmac_f32_e32 v141, v88, v140
	v_fma_f32 v125, -v92, v140, v125
	v_fmac_f32_e32 v141, v92, v124
	v_cvt_pk_bf16_f32 v152, v125, v141
	ds_write2_b32 v161, v1, v152 offset0:0 offset1:68
	v_fmac_f32_e32 v126, v88, v125
	v_fmac_f32_e32 v142, v88, v141
	v_fma_f32 v126, -v92, v141, v126
	v_fmac_f32_e32 v142, v92, v125
	v_cvt_pk_bf16_f32 v1, v126, v142
	v_fmac_f32_e32 v127, v88, v126
	v_fmac_f32_e32 v143, v88, v142
	v_fma_f32 v127, -v92, v142, v127
	v_fmac_f32_e32 v143, v92, v126
	v_cvt_pk_bf16_f32 v152, v127, v143
	ds_write2_b32 v161, v1, v152 offset0:136 offset1:204
	v_mov_b32_e32 v94, v127
	v_mov_b32_e32 v95, v143
	s_waitcnt lgkmcnt(0)
	ds_read_b128 v[112:115], v110 offset:10240
	ds_read_b128 v[116:119], v110 offset:10304
	s_waitcnt lgkmcnt(1)
	v_mfma_f32_16x16x32_bf16 v[68:71], v[112:115], v[36:39], v[68:71]
	ds_read_b128 v[112:115], v110 offset:10368
	s_waitcnt lgkmcnt(1)
	v_mfma_f32_16x16x32_bf16 v[68:71], v[116:119], v[40:43], v[68:71]
	ds_read_b128 v[116:119], v110 offset:10432
	s_waitcnt lgkmcnt(1)
	v_mfma_f32_16x16x32_bf16 v[68:71], v[112:115], v[44:47], v[68:71]
	s_waitcnt lgkmcnt(0)
	v_mfma_f32_16x16x32_bf16 v[68:71], v[116:119], v[48:51], v[68:71]
	s_nop 7
	v_mul_f32_e32 v148, 0x3d372713, v68
	v_mul_f32_e32 v149, 0x3d372713, v69
	v_mul_f32_e32 v150, 0x3d372713, v70
	v_mul_f32_e32 v151, 0x3d372713, v71
	v_mul_f32_e32 v148, v68, v148
	v_mul_f32_e32 v149, v69, v149
	v_mul_f32_e32 v150, v70, v150
	v_mul_f32_e32 v151, v71, v151
	v_fma_f32 v148, v68, v148, v68
	v_fma_f32 v149, v69, v149, v69
	v_fma_f32 v150, v70, v150, v70
	v_fma_f32 v151, v71, v151, v71
	v_mul_f32_e32 v148, 0xc0135761, v148
	v_mul_f32_e32 v149, 0xc0135761, v149
	v_mul_f32_e32 v150, 0xc0135761, v150
	v_mul_f32_e32 v151, 0xc0135761, v151
	v_exp_f32_e32 v148, v148
	v_exp_f32_e32 v149, v149
	v_exp_f32_e32 v150, v150
	v_exp_f32_e32 v151, v151
	v_add_f32_e32 v148, 1.0, v148
	v_add_f32_e32 v149, 1.0, v149
	v_add_f32_e32 v150, 1.0, v150
	v_add_f32_e32 v151, 1.0, v151
	v_rcp_f32_e32 v148, v148
	v_rcp_f32_e32 v149, v149
	v_rcp_f32_e32 v150, v150
	v_rcp_f32_e32 v151, v151
	v_mul_f32_e32 v148, v68, v148
	v_mul_f32_e32 v149, v69, v149
	v_mul_f32_e32 v150, v70, v150
	v_mul_f32_e32 v151, v71, v151
	v_cvt_pk_bf16_f32 v148, v148, v149
	v_cvt_pk_bf16_f32 v150, v150, v151
	global_store_short v[144:145], v148, off
	global_store_short_d16_hi v[144:145], v148, off offset:2048
	global_store_short v[146:147], v150, off
	global_store_short_d16_hi v[146:147], v150, off offset:2048
	v_lshl_add_u64 v[144:145], v[144:145], 0, s[82:83]
	v_lshl_add_u64 v[146:147], v[146:147], 0, s[82:83]
	s_waitcnt lgkmcnt(0)
	v_mov_b64_e32 v[70:71], v[66:67]
	v_mov_b64_e32 v[68:69], v[64:65]
	s_cbranch_scc1 .LBB0_1061

; #define PG8_STAGE(bufoff, gbase, voff) do { _Pragma("unroll") for (int _i = 0; _i < 2; ++_i) \
;         __builtin_amdgcn_global_load_lds((const unsigned*)((const char*)(gbase) + (voff)[_i]), (LAS unsigned*)(lds + (bufoff) + ldsw + _i * 8192), 16, 0, 0); } while (0)
; #define PG8_LDA(dst, b, h) do { _Pragma("unroll") for (int m = 0; m < 4; ++m) _Pragma("unroll") for (int k = 0; k < 2; ++k) dst[m][k] = *(const LAS bf16x8*)(lds + PG8_SA(b, h) + aoff + m * 2048 + k * 1024); } while (0)
; #define PG8_LDB(dst, b, h) do { _Pragma("unroll") for (int n = 0; n < 2; ++n) _Pragma("unroll") for (int k = 0; k < 2; ++k) dst[n][k] = *(const LAS bf16x8*)(lds + PG8_SB(b, h) + boff + n * 2048 + k * 1024); } while (0)
; #define PG8_WAIT_V(n) asm volatile("s_waitcnt vmcnt(" #n ")" ::: "memory")
; #define PG8_WAIT_L(n) asm volatile("s_waitcnt lgkmcnt(" #n ")" ::: "memory")
; #define PG8_BAR __builtin_amdgcn_s_barrier()
; #define PG8_SCHED __builtin_amdgcn_sched_barrier(0)
; template <class Epi, bool ALIGN_EPI = true, bool SP2 = true>
; __device__ __forceinline__ void gemm_phase(LAS unsigned char* lds, const Gemm g, const StaticOrder& S, const Epi& E) {
;     ...
;         const bool has_next = S.next(ui + 1, nxt);
;         const int npm = has_next ? nxt.pm : cur.pm;
;         const char* nB = has_next ? (const char*)g.Bt + (size_t)nxt.pn * tstepB : cB;
;         for (int t = 0; t < nt; t += 2) {
;             const bool last = (t == nt - 2);
;             const char* a1 = PG8_ATILE(cur.pm, t + 1);
;             const char* a2 = last ? PG8_ATILE(npm, 0) : PG8_ATILE(cur.pm, t + 2);
;             const char* a3 = last ? PG8_ATILE(npm, 1) : PG8_ATILE(cur.pm, t + 3);
;             const char* b2 = last ? nB : cB + (size_t)(t + 2) * kstep;
;             const char* b3 = b2 + kstep;
;             if constexpr (SP2) {
;             PG8_LDB(B0, 0, 0); PG8_LDB(B1, 0, 1); PG8_SCHED; PG8_LDA(At, 0, 0); PG8_STAGE(PG8_SA(1, 1), a1 + hstepA, voffA);
;             PG8_WAIT_V(8); PG8_WAIT_L(0); PG8_BAR; PG8_MMA(0, 0, At, B0); PG8_MMA(0, 1, At, B1); PG8_BAR; PG8_SCHED;
;             PG8_LDA(At, 0, 1); PG8_STAGE(PG8_SB(0, 0), b2, voffB); PG8_STAGE(PG8_SB(0, 1), b2 + hstepB, voffB); PG8_STAGE(PG8_SA(0, 0), a2, voffA);
;             PG8_WAIT_V(8); PG8_WAIT_L(0); PG8_BAR; PG8_MMA(1, 0, At, B0); PG8_MMA(1, 1, At, B1); PG8_BAR; PG8_SCHED;
.LBB0_1160:
	s_ashr_i32 s15, s14, 31
	s_lshl_b64 s[16:17], s[14:15], 19
	s_add_u32 s16, s6, s16
	s_addc_u32 s17, s7, s17
	s_and_b64 s[20:21], s[0:1], exec
	s_cselect_b32 s15, s17, s25
	s_cselect_b32 s23, s16, s24
	s_ashr_i32 s19, s18, 31
	s_ashr_i32 s29, s28, 31
	s_lshl_b64 s[20:21], s[18:19], 19
	s_lshl_b64 s[28:29], s[28:29], 19
	s_add_u32 s19, s44, s28
	s_addc_u32 s52, s45, s29
	s_add_u32 s53, s63, s28
	s_addc_u32 s71, s64, s29
	s_add_u32 s72, s78, s20
	s_addc_u32 s73, s79, s21
	s_add_u32 s74, s24, 0x100
	v_mov_b32_e32 v0, 0
	v_lshl_add_u64 v[64:65], v[208:209], 0, s[20:21]
	v_lshl_add_u64 v[66:67], v[210:211], 0, s[20:21]
	s_addc_u32 s75, s25, 0
	s_mov_b32 s4, -2
	s_mov_b64 s[24:25], 0
	s_waitcnt vmcnt(0)
	s_add_i32 s80, s4, 2
	s_add_u32 s28, s72, s24
	s_addc_u32 s29, s73, s25
	s_add_u32 s36, s28, 0x12000100
	s_addc_u32 s37, s29, 0
	s_add_u32 s28, s78, s24
	s_addc_u32 s29, s79, s25
	s_add_u32 s40, s28, 0x12000180
	s_addc_u32 s41, s29, 0
	s_add_i32 s4, s4, -11
	ds_read_b128 v[68:71], v230
	ds_read_b128 v[72:75], v230 offset:1024
	ds_read_b128 v[76:79], v230 offset:2048
	ds_read_b128 v[136:139], v230 offset:3072
	ds_read_b128 v[140:143], v231
	ds_read_b128 v[152:155], v231 offset:1024
	ds_read_b128 v[156:159], v231 offset:2048
	ds_read_b128 v[160:163], v231 offset:3072
	s_lshl_b64 s[28:29], s[4:5], 7
	s_add_u32 s4, s44, s28
	s_addc_u32 s28, s45, s29
	s_cmp_lt_u32 s80, 13
	s_cselect_b32 s4, s40, s4
	s_cselect_b32 s28, s41, s28
	s_add_u32 s4, s4, s20
	s_addc_u32 s28, s28, s21
	s_add_u32 s81, s74, s24
	s_addc_u32 s82, s75, s25
	s_cmpk_eq_i32 s24, 0x700
	s_cselect_b32 s41, s52, s37
	s_cselect_b32 s40, s19, s36
	s_cselect_b32 s29, s71, s28
	s_cselect_b32 s28, s53, s4
	s_cselect_b32 s37, s15, s82
	s_cselect_b32 s36, s23, s81
	v_lshl_add_u64 v[196:197], v[64:65], 0, s[24:25]
	s_add_i32 m0, s39, 0xc000
	ds_read_b128 v[164:167], v232
	ds_read_b128 v[168:171], v232 offset:1024
	ds_read_b128 v[172:175], v232 offset:2048
	ds_read_b128 v[176:179], v232 offset:3072
	ds_read_b128 v[180:183], v232 offset:4096
	ds_read_b128 v[184:187], v232 offset:5120
	ds_read_b128 v[188:191], v232 offset:6144
	ds_read_b128 v[192:195], v232 offset:7168
	global_load_lds_dwordx4 v[196:197], off
	v_lshl_add_u64 v[196:197], v[66:67], 0, s[24:25]
	s_add_i32 m0, s39, 0xe000
	s_nop 0
	global_load_lds_dwordx4 v[196:197], off
	s_waitcnt vmcnt(8)
	s_waitcnt lgkmcnt(0)
	s_barrier
	s_setprio 1
	s_waitcnt lgkmcnt(0)
	v_mfma_f32_16x16x32_bf16 v[148:151], v[68:71], v[164:167], 0
	v_mfma_f32_16x16x32_bf16 v[144:147], v[76:79], v[164:167], 0
	v_mfma_f32_16x16x32_bf16 v[124:127], v[68:71], v[172:175], 0
	v_mfma_f32_16x16x32_bf16 v[120:123], v[76:79], v[172:175], 0
	v_mfma_f32_16x16x32_bf16 v[108:111], v[68:71], v[180:183], 0
	v_mfma_f32_16x16x32_bf16 v[104:107], v[76:79], v[180:183], 0
	v_mfma_f32_16x16x32_bf16 v[92:95], v[68:71], v[188:191], 0
	v_mfma_f32_16x16x32_bf16 v[88:91], v[76:79], v[188:191], 0
	v_mfma_f32_16x16x32_bf16 v[148:151], v[72:75], v[168:171], v[148:151]
	v_mfma_f32_16x16x32_bf16 v[144:147], v[136:139], v[168:171], v[144:147]
	v_mfma_f32_16x16x32_bf16 v[124:127], v[72:75], v[176:179], v[124:127]
	v_mfma_f32_16x16x32_bf16 v[120:123], v[136:139], v[176:179], v[120:123]
	v_mfma_f32_16x16x32_bf16 v[108:111], v[72:75], v[184:187], v[108:111]
	v_mfma_f32_16x16x32_bf16 v[104:107], v[136:139], v[184:187], v[104:107]
	v_mfma_f32_16x16x32_bf16 v[92:95], v[72:75], v[192:195], v[92:95]
	v_mfma_f32_16x16x32_bf16 v[88:91], v[136:139], v[192:195], v[88:91]
	s_setprio 0
	s_setprio 1
	v_mfma_f32_16x16x32_bf16 v[132:135], v[140:143], v[164:167], 0
	v_mfma_f32_16x16x32_bf16 v[128:131], v[156:159], v[164:167], 0
	v_mfma_f32_16x16x32_bf16 v[116:119], v[140:143], v[172:175], 0
	v_mfma_f32_16x16x32_bf16 v[112:115], v[156:159], v[172:175], 0
	v_mfma_f32_16x16x32_bf16 v[100:103], v[140:143], v[180:183], 0
	v_mfma_f32_16x16x32_bf16 v[96:99], v[156:159], v[180:183], 0
	v_mfma_f32_16x16x32_bf16 v[84:87], v[140:143], v[188:191], 0
	v_mfma_f32_16x16x32_bf16 v[80:83], v[156:159], v[188:191], 0
	v_mfma_f32_16x16x32_bf16 v[132:135], v[152:155], v[168:171], v[132:135]
	v_mfma_f32_16x16x32_bf16 v[128:131], v[160:163], v[168:171], v[128:131]
	v_mfma_f32_16x16x32_bf16 v[116:119], v[152:155], v[176:179], v[116:119]
	v_mfma_f32_16x16x32_bf16 v[112:115], v[160:163], v[176:179], v[112:115]
	v_mfma_f32_16x16x32_bf16 v[100:103], v[152:155], v[184:187], v[100:103]
	v_mfma_f32_16x16x32_bf16 v[96:99], v[160:163], v[184:187], v[96:99]
	v_mfma_f32_16x16x32_bf16 v[84:87], v[152:155], v[192:195], v[84:87]
	v_mfma_f32_16x16x32_bf16 v[80:83], v[160:163], v[192:195], v[80:83]
	s_setprio 0
	s_barrier
	s_add_i32 s4, s67, s38
	v_lshl_add_u64 v[196:197], s[36:37], 0, v[204:205]
	s_mov_b32 m0, s4
	ds_read_b128 v[164:167], v232 offset:16384
	ds_read_b128 v[168:171], v232 offset:17408
	ds_read_b128 v[172:175], v232 offset:18432
	ds_read_b128 v[176:179], v232 offset:19456
	ds_read_b128 v[180:183], v232 offset:20480
	ds_read_b128 v[184:187], v232 offset:21504
	ds_read_b128 v[188:191], v232 offset:22528
	ds_read_b128 v[192:195], v232 offset:23552
	global_load_lds_dwordx4 v[196:197], off
	s_add_i32 m0, s4, 0x2000
	s_add_u32 s82, s36, 0x40000
	v_lshl_add_u64 v[198:199], s[36:37], 0, v[200:201]
	s_addc_u32 s83, s37, 0
	s_add_i32 s4, s68, s38
	global_load_lds_dwordx4 v[198:199], off
	v_lshl_add_u64 v[216:217], s[82:83], 0, v[204:205]
	s_mov_b32 m0, s4
	s_nop 0
	global_load_lds_dwordx4 v[216:217], off
	v_lshl_add_u64 v[216:217], s[82:83], 0, v[200:201]
	s_add_i32 m0, s4, 0x2000
	s_nop 0
	global_load_lds_dwordx4 v[216:217], off
	v_lshl_add_u64 v[216:217], s[40:41], 0, v[206:207]
	s_mov_b32 m0, s39
	s_nop 0
	global_load_lds_dwordx4 v[216:217], off
	v_lshl_add_u64 v[216:217], s[40:41], 0, v[202:203]
	s_mov_b32 m0, s46
	s_nop 0
	global_load_lds_dwordx4 v[216:217], off
	s_waitcnt vmcnt(8)
	s_waitcnt lgkmcnt(0)
	s_barrier
; #define PG8_STAGE(bufoff, gbase, voff) do { _Pragma("unroll") for (int _i = 0; _i < 2; ++_i) \
;         __builtin_amdgcn_global_load_lds((const unsigned*)((const char*)(gbase) + (voff)[_i]), (LAS unsigned*)(lds + (bufoff) + ldsw + _i * 8192), 16, 0, 0); } while (0)
; #define PG8_LDA(dst, b, h) do { _Pragma("unroll") for (int m = 0; m < 4; ++m) _Pragma("unroll") for (int k = 0; k < 2; ++k) dst[m][k] = *(const LAS bf16x8*)(lds + PG8_SA(b, h) + aoff + m * 2048 + k * 1024); } while (0)
; #define PG8_LDB(dst, b, h) do { _Pragma("unroll") for (int n = 0; n < 2; ++n) _Pragma("unroll") for (int k = 0; k < 2; ++k) dst[n][k] = *(const LAS bf16x8*)(lds + PG8_SB(b, h) + boff + n * 2048 + k * 1024); } while (0)
; #define PG8_MMA(ai, bj, At, Bt) do { __builtin_amdgcn_s_setprio(1); _Pragma("unroll") for (int m = 0; m < 4; ++m) _Pragma("unroll") for (int n = 0; n < 2; ++n) _Pragma("unroll") for (int k = 0; k < 2; ++k) \
;         acc[ai][bj][m][n] = __builtin_amdgcn_mfma_f32_16x16x32_bf16(Bt[n][k], At[m][k], acc[ai][bj][m][n], 0, 0, 0); __builtin_amdgcn_s_setprio(0); } while (0)
; #define PG8_WAIT_V(n) asm volatile("s_waitcnt vmcnt(" #n ")" ::: "memory")
; #define PG8_WAIT_L(n) asm volatile("s_waitcnt lgkmcnt(" #n ")" ::: "memory")
; #define PG8_BAR __builtin_amdgcn_s_barrier()
; #define PG8_SCHED __builtin_amdgcn_sched_barrier(0)
; template <class Epi, bool ALIGN_EPI = true, bool SP2 = true>
; __device__ __forceinline__ void gemm_phase(LAS unsigned char* lds, const Gemm g, const StaticOrder& S, const Epi& E) {
;     ...
;             PG8_WAIT_V(8); PG8_WAIT_L(0); PG8_BAR; PG8_MMA(1, 0, At, B0); PG8_MMA(1, 1, At, B1); PG8_BAR; PG8_SCHED;
;             PG8_LDB(B0, 1, 0); PG8_LDB(B1, 1, 1); PG8_SCHED; PG8_LDA(At, 1, 0); PG8_STAGE(PG8_SA(0, 1), a2 + hstepA, voffA);
;             PG8_WAIT_V(8); PG8_WAIT_L(0); PG8_BAR; PG8_MMA(0, 0, At, B0); PG8_MMA(0, 1, At, B1); PG8_BAR; PG8_SCHED;
	s_setprio 1
	s_waitcnt lgkmcnt(0)
	v_mfma_f32_16x16x32_bf16 v[60:63], v[68:71], v[164:167], 0
	v_mfma_f32_16x16x32_bf16 v[56:59], v[76:79], v[164:167], 0
	v_mfma_f32_16x16x32_bf16 v[44:47], v[68:71], v[172:175], 0
	v_mfma_f32_16x16x32_bf16 v[40:43], v[76:79], v[172:175], 0
	v_mfma_f32_16x16x32_bf16 v[28:31], v[68:71], v[180:183], 0
	v_mfma_f32_16x16x32_bf16 v[24:27], v[76:79], v[180:183], 0
	v_mfma_f32_16x16x32_bf16 v[12:15], v[68:71], v[188:191], 0
	v_mfma_f32_16x16x32_bf16 v[8:11], v[76:79], v[188:191], 0
	v_mfma_f32_16x16x32_bf16 v[60:63], v[72:75], v[168:171], v[60:63]
	v_mfma_f32_16x16x32_bf16 v[56:59], v[136:139], v[168:171], v[56:59]
	v_mfma_f32_16x16x32_bf16 v[44:47], v[72:75], v[176:179], v[44:47]
	v_mfma_f32_16x16x32_bf16 v[40:43], v[136:139], v[176:179], v[40:43]
	v_mfma_f32_16x16x32_bf16 v[28:31], v[72:75], v[184:187], v[28:31]
	v_mfma_f32_16x16x32_bf16 v[24:27], v[136:139], v[184:187], v[24:27]
	v_mfma_f32_16x16x32_bf16 v[12:15], v[72:75], v[192:195], v[12:15]
	v_mfma_f32_16x16x32_bf16 v[8:11], v[136:139], v[192:195], v[8:11]
	s_setprio 0
	s_setprio 1
	v_mfma_f32_16x16x32_bf16 v[52:55], v[140:143], v[164:167], 0
	v_mfma_f32_16x16x32_bf16 v[48:51], v[156:159], v[164:167], 0
	v_mfma_f32_16x16x32_bf16 v[36:39], v[140:143], v[172:175], 0
	v_mfma_f32_16x16x32_bf16 v[32:35], v[156:159], v[172:175], 0
	v_mfma_f32_16x16x32_bf16 v[20:23], v[140:143], v[180:183], 0
	v_mfma_f32_16x16x32_bf16 v[16:19], v[156:159], v[180:183], 0
	v_mfma_f32_16x16x32_bf16 v[4:7], v[140:143], v[188:191], 0
	v_mfma_f32_16x16x32_bf16 v[0:3], v[156:159], v[188:191], 0
	v_mfma_f32_16x16x32_bf16 v[52:55], v[152:155], v[168:171], v[52:55]
	v_mfma_f32_16x16x32_bf16 v[48:51], v[160:163], v[168:171], v[48:51]
	v_mfma_f32_16x16x32_bf16 v[36:39], v[152:155], v[176:179], v[36:39]
	v_mfma_f32_16x16x32_bf16 v[32:35], v[160:163], v[176:179], v[32:35]
	v_mfma_f32_16x16x32_bf16 v[20:23], v[152:155], v[184:187], v[20:23]
	v_mfma_f32_16x16x32_bf16 v[16:19], v[160:163], v[184:187], v[16:19]
	v_mfma_f32_16x16x32_bf16 v[4:7], v[152:155], v[192:195], v[4:7]
	v_mfma_f32_16x16x32_bf16 v[0:3], v[160:163], v[192:195], v[0:3]
	s_setprio 0
	s_barrier
	s_add_i32 s4, 0, 0x18000
	s_add_i32 s81, 0, 0x1c000
	v_add_u32_e32 v136, s4, v228
	v_add_u32_e32 v160, s81, v228
	ds_read_b128 v[68:71], v136
	ds_read_b128 v[72:75], v136 offset:1024
	ds_read_b128 v[76:79], v136 offset:2048
	ds_read_b128 v[136:139], v136 offset:3072
	ds_read_b128 v[140:143], v160
	ds_read_b128 v[152:155], v160 offset:1024
	ds_read_b128 v[156:159], v160 offset:2048
	ds_read_b128 v[160:163], v160 offset:3072
	s_add_u32 s40, s40, 0x40000
	s_addc_u32 s41, s41, 0
	s_mov_b32 m0, s47
	v_lshl_add_u64 v[216:217], s[40:41], 0, v[206:207]
	ds_read_b128 v[164:167], v232 offset:32768
	ds_read_b128 v[168:171], v232 offset:33792
	ds_read_b128 v[172:175], v232 offset:34816
	ds_read_b128 v[176:179], v232 offset:35840
	ds_read_b128 v[180:183], v232 offset:36864
	ds_read_b128 v[184:187], v232 offset:37888
	ds_read_b128 v[188:191], v232 offset:38912
	ds_read_b128 v[192:195], v232 offset:39936
	global_load_lds_dwordx4 v[216:217], off
	v_lshl_add_u64 v[216:217], s[40:41], 0, v[202:203]
	s_mov_b32 m0, s62
	s_nop 0
	global_load_lds_dwordx4 v[216:217], off
	s_waitcnt vmcnt(8)
	s_waitcnt lgkmcnt(0)
	s_barrier
	s_setprio 1
	s_waitcnt lgkmcnt(0)
	v_mfma_f32_16x16x32_bf16 v[148:151], v[68:71], v[164:167], v[148:151]
	v_mfma_f32_16x16x32_bf16 v[144:147], v[76:79], v[164:167], v[144:147]
	v_mfma_f32_16x16x32_bf16 v[124:127], v[68:71], v[172:175], v[124:127]
	v_mfma_f32_16x16x32_bf16 v[120:123], v[76:79], v[172:175], v[120:123]
	v_mfma_f32_16x16x32_bf16 v[108:111], v[68:71], v[180:183], v[108:111]
	v_mfma_f32_16x16x32_bf16 v[104:107], v[76:79], v[180:183], v[104:107]
	v_mfma_f32_16x16x32_bf16 v[92:95], v[68:71], v[188:191], v[92:95]
	v_mfma_f32_16x16x32_bf16 v[88:91], v[76:79], v[188:191], v[88:91]
	v_mfma_f32_16x16x32_bf16 v[148:151], v[72:75], v[168:171], v[148:151]
	v_mfma_f32_16x16x32_bf16 v[144:147], v[136:139], v[168:171], v[144:147]
	v_mfma_f32_16x16x32_bf16 v[124:127], v[72:75], v[176:179], v[124:127]
	v_mfma_f32_16x16x32_bf16 v[120:123], v[136:139], v[176:179], v[120:123]
	v_mfma_f32_16x16x32_bf16 v[108:111], v[72:75], v[184:187], v[108:111]
	v_mfma_f32_16x16x32_bf16 v[104:107], v[136:139], v[184:187], v[104:107]
	v_mfma_f32_16x16x32_bf16 v[92:95], v[72:75], v[192:195], v[92:95]
	v_mfma_f32_16x16x32_bf16 v[88:91], v[136:139], v[192:195], v[88:91]
	s_setprio 0
	s_setprio 1
	v_mfma_f32_16x16x32_bf16 v[132:135], v[140:143], v[164:167], v[132:135]
	v_mfma_f32_16x16x32_bf16 v[128:131], v[156:159], v[164:167], v[128:131]
	v_mfma_f32_16x16x32_bf16 v[116:119], v[140:143], v[172:175], v[116:119]
	v_mfma_f32_16x16x32_bf16 v[112:115], v[156:159], v[172:175], v[112:115]
	v_mfma_f32_16x16x32_bf16 v[100:103], v[140:143], v[180:183], v[100:103]
	v_mfma_f32_16x16x32_bf16 v[96:99], v[156:159], v[180:183], v[96:99]
	v_mfma_f32_16x16x32_bf16 v[84:87], v[140:143], v[188:191], v[84:87]
	v_mfma_f32_16x16x32_bf16 v[80:83], v[156:159], v[188:191], v[80:83]
	v_mfma_f32_16x16x32_bf16 v[132:135], v[152:155], v[168:171], v[132:135]
	v_mfma_f32_16x16x32_bf16 v[128:131], v[160:163], v[168:171], v[128:131]
	v_mfma_f32_16x16x32_bf16 v[116:119], v[152:155], v[176:179], v[116:119]
	v_mfma_f32_16x16x32_bf16 v[112:115], v[160:163], v[176:179], v[112:115]
	v_mfma_f32_16x16x32_bf16 v[100:103], v[152:155], v[184:187], v[100:103]
	v_mfma_f32_16x16x32_bf16 v[96:99], v[160:163], v[184:187], v[96:99]
	v_mfma_f32_16x16x32_bf16 v[84:87], v[152:155], v[192:195], v[84:87]
	v_mfma_f32_16x16x32_bf16 v[80:83], v[160:163], v[192:195], v[80:83]
	s_setprio 0
	s_barrier
; #define PG8_STAGE(bufoff, gbase, voff) do { _Pragma("unroll") for (int _i = 0; _i < 2; ++_i) \
;         __builtin_amdgcn_global_load_lds((const unsigned*)((const char*)(gbase) + (voff)[_i]), (LAS unsigned*)(lds + (bufoff) + ldsw + _i * 8192), 16, 0, 0); } while (0)
; #define PG8_LDA(dst, b, h) do { _Pragma("unroll") for (int m = 0; m < 4; ++m) _Pragma("unroll") for (int k = 0; k < 2; ++k) dst[m][k] = *(const LAS bf16x8*)(lds + PG8_SA(b, h) + aoff + m * 2048 + k * 1024); } while (0)
; #define PG8_MMA(ai, bj, At, Bt) do { __builtin_amdgcn_s_setprio(1); _Pragma("unroll") for (int m = 0; m < 4; ++m) _Pragma("unroll") for (int n = 0; n < 2; ++n) _Pragma("unroll") for (int k = 0; k < 2; ++k) \
;         acc[ai][bj][m][n] = __builtin_amdgcn_mfma_f32_16x16x32_bf16(Bt[n][k], At[m][k], acc[ai][bj][m][n], 0, 0, 0); __builtin_amdgcn_s_setprio(0); } while (0)
; #define PG8_WAIT_V(n) asm volatile("s_waitcnt vmcnt(" #n ")" ::: "memory")
; #define PG8_WAIT_L(n) asm volatile("s_waitcnt lgkmcnt(" #n ")" ::: "memory")
; #define PG8_BAR __builtin_amdgcn_s_barrier()
; #define PG8_SCHED __builtin_amdgcn_sched_barrier(0)
; template <class Epi, bool ALIGN_EPI = true, bool SP2 = true>
; __device__ __forceinline__ void gemm_phase(LAS unsigned char* lds, const Gemm g, const StaticOrder& S, const Epi& E) {
;     ...
;             PG8_LDA(At, 1, 1); PG8_STAGE(PG8_SB(1, 0), b3, voffB); PG8_STAGE(PG8_SB(1, 1), b3 + hstepB, voffB); PG8_STAGE(PG8_SA(1, 0), a3, voffA);
;             PG8_WAIT_V(8); PG8_WAIT_L(0); PG8_BAR; PG8_MMA(1, 0, At, B0); PG8_MMA(1, 1, At, B1); PG8_BAR; PG8_SCHED;
	s_add_i32 s4, s4, s38
	v_lshl_add_u64 v[196:197], v[196:197], 0, s[10:11]
	s_mov_b32 m0, s4
	ds_read_b128 v[164:167], v232 offset:49152
	ds_read_b128 v[168:171], v232 offset:50176
	ds_read_b128 v[172:175], v232 offset:51200
	ds_read_b128 v[176:179], v232 offset:52224
	ds_read_b128 v[180:183], v232 offset:53248
	ds_read_b128 v[184:187], v232 offset:54272
	ds_read_b128 v[188:191], v232 offset:55296
	ds_read_b128 v[192:195], v232 offset:56320
	global_load_lds_dwordx4 v[196:197], off
	s_add_i32 m0, s4, 0x2000
	s_add_u32 s36, s36, 0x40080
	v_lshl_add_u64 v[196:197], v[198:199], 0, s[10:11]
	s_addc_u32 s37, s37, 0
	s_add_i32 s4, s81, s38
	global_load_lds_dwordx4 v[196:197], off
	v_lshl_add_u64 v[196:197], s[36:37], 0, v[204:205]
	s_mov_b32 m0, s4
	s_nop 0
	global_load_lds_dwordx4 v[196:197], off
	v_lshl_add_u64 v[196:197], s[36:37], 0, v[200:201]
	s_add_i32 m0, s4, 0x2000
	s_nop 0
	global_load_lds_dwordx4 v[196:197], off
	v_lshl_add_u64 v[196:197], s[28:29], 0, v[206:207]
	s_mov_b32 m0, s65
	s_nop 0
	global_load_lds_dwordx4 v[196:197], off
	v_lshl_add_u64 v[196:197], s[28:29], 0, v[202:203]
	s_mov_b32 m0, s66
	s_nop 0
	global_load_lds_dwordx4 v[196:197], off
	s_waitcnt vmcnt(8)
	s_waitcnt lgkmcnt(0)
	s_barrier
	s_setprio 1
	s_waitcnt lgkmcnt(0)
	v_mfma_f32_16x16x32_bf16 v[60:63], v[68:71], v[164:167], v[60:63]
	v_mfma_f32_16x16x32_bf16 v[56:59], v[76:79], v[164:167], v[56:59]
	v_mfma_f32_16x16x32_bf16 v[44:47], v[68:71], v[172:175], v[44:47]
	v_mfma_f32_16x16x32_bf16 v[40:43], v[76:79], v[172:175], v[40:43]
	v_mfma_f32_16x16x32_bf16 v[28:31], v[68:71], v[180:183], v[28:31]
	v_mfma_f32_16x16x32_bf16 v[24:27], v[76:79], v[180:183], v[24:27]
	v_mfma_f32_16x16x32_bf16 v[12:15], v[68:71], v[188:191], v[12:15]
	v_mfma_f32_16x16x32_bf16 v[8:11], v[76:79], v[188:191], v[8:11]
	v_mfma_f32_16x16x32_bf16 v[60:63], v[72:75], v[168:171], v[60:63]
	v_mfma_f32_16x16x32_bf16 v[56:59], v[136:139], v[168:171], v[56:59]
	v_mfma_f32_16x16x32_bf16 v[44:47], v[72:75], v[176:179], v[44:47]
	v_mfma_f32_16x16x32_bf16 v[40:43], v[136:139], v[176:179], v[40:43]
	v_mfma_f32_16x16x32_bf16 v[28:31], v[72:75], v[184:187], v[28:31]
	v_mfma_f32_16x16x32_bf16 v[24:27], v[136:139], v[184:187], v[24:27]
	v_mfma_f32_16x16x32_bf16 v[12:15], v[72:75], v[192:195], v[12:15]
	v_mfma_f32_16x16x32_bf16 v[8:11], v[136:139], v[192:195], v[8:11]
	s_setprio 0
	s_setprio 1
	v_mfma_f32_16x16x32_bf16 v[52:55], v[140:143], v[164:167], v[52:55]
	v_mfma_f32_16x16x32_bf16 v[48:51], v[156:159], v[164:167], v[48:51]
	v_mfma_f32_16x16x32_bf16 v[36:39], v[140:143], v[172:175], v[36:39]
	v_mfma_f32_16x16x32_bf16 v[32:35], v[156:159], v[172:175], v[32:35]
	v_mfma_f32_16x16x32_bf16 v[20:23], v[140:143], v[180:183], v[20:23]
	v_mfma_f32_16x16x32_bf16 v[16:19], v[156:159], v[180:183], v[16:19]
	v_mfma_f32_16x16x32_bf16 v[4:7], v[140:143], v[188:191], v[4:7]
	v_mfma_f32_16x16x32_bf16 v[0:3], v[156:159], v[188:191], v[0:3]
	v_mfma_f32_16x16x32_bf16 v[52:55], v[152:155], v[168:171], v[52:55]
	v_mfma_f32_16x16x32_bf16 v[48:51], v[160:163], v[168:171], v[48:51]
	v_mfma_f32_16x16x32_bf16 v[36:39], v[152:155], v[176:179], v[36:39]
	v_mfma_f32_16x16x32_bf16 v[32:35], v[160:163], v[176:179], v[32:35]
	v_mfma_f32_16x16x32_bf16 v[20:23], v[152:155], v[184:187], v[20:23]
	v_mfma_f32_16x16x32_bf16 v[16:19], v[160:163], v[184:187], v[16:19]
	v_mfma_f32_16x16x32_bf16 v[4:7], v[152:155], v[192:195], v[4:7]
	v_mfma_f32_16x16x32_bf16 v[0:3], v[160:163], v[192:195], v[0:3]
	s_setprio 0
	s_barrier
	s_add_u32 s24, s24, 0x100
	s_addc_u32 s25, s25, 0
	s_cmp_gt_u32 s80, 13
	s_mov_b32 s4, s80

; #define PG8_STAGE(bufoff, gbase, voff) do { _Pragma("unroll") for (int _i = 0; _i < 2; ++_i) \
;         __builtin_amdgcn_global_load_lds((const unsigned*)((const char*)(gbase) + (voff)[_i]), (LAS unsigned*)(lds + (bufoff) + ldsw + _i * 8192), 16, 0, 0); } while (0)
; #define PG8_LDA(dst, b, h) do { _Pragma("unroll") for (int m = 0; m < 4; ++m) _Pragma("unroll") for (int k = 0; k < 2; ++k) dst[m][k] = *(const LAS bf16x8*)(lds + PG8_SA(b, h) + aoff + m * 2048 + k * 1024); } while (0)
; #define PG8_LDB(dst, b, h) do { _Pragma("unroll") for (int n = 0; n < 2; ++n) _Pragma("unroll") for (int k = 0; k < 2; ++k) dst[n][k] = *(const LAS bf16x8*)(lds + PG8_SB(b, h) + boff + n * 2048 + k * 1024); } while (0)
; #define PG8_WAIT_V(n) asm volatile("s_waitcnt vmcnt(" #n ")" ::: "memory")
; #define PG8_WAIT_L(n) asm volatile("s_waitcnt lgkmcnt(" #n ")" ::: "memory")
; #define PG8_BAR __builtin_amdgcn_s_barrier()
; template <class Epi, bool ALIGN_EPI = true, bool SP2 = true>
; __device__ __forceinline__ void gemm_phase(LAS unsigned char* lds, const Gemm g, const StaticOrder& S, const Epi& E) {
;     ...
;         for (int t = 0; t < nt; t += 2) {
;             const bool last = (t == nt - 2);
;             const char* a1 = PG8_ATILE(cur.pm, t + 1);
;             const char* a2 = last ? PG8_ATILE(npm, 0) : PG8_ATILE(cur.pm, t + 2);
;             const char* a3 = last ? PG8_ATILE(npm, 1) : PG8_ATILE(cur.pm, t + 3);
;             const char* b2 = last ? nB : cB + (size_t)(t + 2) * kstep;
;             const char* b3 = b2 + kstep;
;             if constexpr (SP2) {
;             PG8_LDB(B0, 0, 0); PG8_LDB(B1, 0, 1); PG8_SCHED; PG8_LDA(At, 0, 0); PG8_STAGE(PG8_SA(1, 1), a1 + hstepA, voffA);
;             PG8_WAIT_V(8); PG8_WAIT_L(0); PG8_BAR; PG8_MMA(0, 0, At, B0); PG8_MMA(0, 1, At, B1); PG8_BAR; PG8_SCHED;
;             PG8_LDA(At, 0, 1); PG8_STAGE(PG8_SB(0, 0), b2, voffB); PG8_STAGE(PG8_SB(0, 1), b2 + hstepB, voffB); PG8_STAGE(PG8_SA(0, 0), a2, voffA);
;             PG8_WAIT_V(8); PG8_WAIT_L(0); PG8_BAR; PG8_MMA(1, 0, At, B0); PG8_MMA(1, 1, At, B1); PG8_BAR; PG8_SCHED;
;     ...
;         for (int a = 0; a < 2; ++a)
; #pragma unroll
;             for (int b = 0; b < 2; ++b)
; #pragma unroll
;                 for (int m = 0; m < 4; ++m)
; #pragma unroll
;                     for (int n = 0; n < 2; ++n) acc[a][b][m][n] = (f32x4){0.f, 0.f, 0.f, 0.f};
.LBB0_1233:
	s_ashr_i32 s13, s12, 31
	s_lshl_b64 s[14:15], s[12:13], 19
	s_add_u32 s14, s35, s14
	s_addc_u32 s15, s36, s15
	s_and_b64 s[18:19], s[0:1], exec
	s_cselect_b32 s13, s15, s21
	s_cselect_b32 s53, s14, s20
	s_ashr_i32 s17, s16, 31
	s_ashr_i32 s23, s22, 31
	s_lshl_b64 s[18:19], s[16:17], 19
	s_lshl_b64 s[22:23], s[22:23], 19
	s_add_u32 s54, s26, s22
	s_addc_u32 s55, s27, s23
	s_add_u32 s56, s42, s22
	s_addc_u32 s57, s43, s23
	s_add_u32 s58, s78, s18
	s_addc_u32 s59, s79, s19
	s_add_u32 s60, s20, 0x100
	v_mov_b32_e32 v0, 0
	v_lshl_add_u64 v[128:129], v[152:153], 0, s[18:19]
	v_lshl_add_u64 v[130:131], v[154:155], 0, s[18:19]
	s_addc_u32 s61, s21, 0
	s_mov_b32 s4, -2
	s_mov_b64 s[20:21], 0
	s_waitcnt vmcnt(0)
	s_add_i32 s62, s4, 2
	s_add_u32 s22, s58, s20
	s_addc_u32 s23, s59, s21
	s_add_u32 s24, s22, 0x16000100
	s_addc_u32 s25, s23, 0
	s_add_u32 s22, s78, s20
	s_addc_u32 s23, s79, s21
	s_add_u32 s28, s22, 0x16000180
	s_addc_u32 s29, s23, 0
	s_add_i32 s4, s4, -11
	ds_read_b128 v[132:135], v171
	ds_read_b128 v[136:139], v171 offset:1024
	ds_read_b128 v[140:143], v171 offset:2048
	ds_read_b128 v[160:163], v171 offset:3072
	ds_read_b128 v[164:167], v172
	ds_read_b128 v[174:177], v172 offset:1024
	ds_read_b128 v[178:181], v172 offset:2048
	ds_read_b128 v[182:185], v172 offset:3072
	s_lshl_b64 s[22:23], s[4:5], 7
	s_add_u32 s4, s26, s22
	s_addc_u32 s22, s27, s23
	s_cmp_lt_u32 s62, 13
	s_cselect_b32 s4, s28, s4
	s_cselect_b32 s22, s29, s22
	s_add_u32 s4, s4, s18
	s_addc_u32 s22, s22, s19
	s_add_u32 s63, s60, s20
	s_addc_u32 s64, s61, s21
	s_cmpk_eq_i32 s20, 0x700
	s_cselect_b32 s29, s55, s25
	s_cselect_b32 s28, s54, s24
	s_cselect_b32 s23, s57, s22
	s_cselect_b32 s22, s56, s4
	s_cselect_b32 s25, s13, s64
	s_cselect_b32 s24, s53, s63
	v_lshl_add_u64 v[218:219], v[128:129], 0, s[20:21]
	s_add_i32 m0, s38, 0xc000
	ds_read_b128 v[186:189], v173
	ds_read_b128 v[190:193], v173 offset:1024
	ds_read_b128 v[194:197], v173 offset:2048
	ds_read_b128 v[198:201], v173 offset:3072
	ds_read_b128 v[202:205], v173 offset:4096
	ds_read_b128 v[206:209], v173 offset:5120
	ds_read_b128 v[210:213], v173 offset:6144
	ds_read_b128 v[214:217], v173 offset:7168
	global_load_lds_dwordx4 v[218:219], off
	v_lshl_add_u64 v[218:219], v[130:131], 0, s[20:21]
	s_add_i32 m0, s38, 0xe000
	s_nop 0
	global_load_lds_dwordx4 v[218:219], off
	s_waitcnt vmcnt(8)
	s_waitcnt lgkmcnt(0)
	s_barrier
	s_setprio 1
	s_waitcnt lgkmcnt(0)
	v_mfma_f32_16x16x32_bf16 v[124:127], v[132:135], v[186:189], 0
	v_mfma_f32_16x16x32_bf16 v[120:123], v[140:143], v[186:189], 0
	v_mfma_f32_16x16x32_bf16 v[116:119], v[132:135], v[194:197], 0
	v_mfma_f32_16x16x32_bf16 v[112:115], v[140:143], v[194:197], 0
	v_mfma_f32_16x16x32_bf16 v[96:99], v[132:135], v[202:205], 0
	v_mfma_f32_16x16x32_bf16 v[88:91], v[140:143], v[202:205], 0
	v_mfma_f32_16x16x32_bf16 v[80:83], v[132:135], v[210:213], 0
	v_mfma_f32_16x16x32_bf16 v[72:75], v[140:143], v[210:213], 0
	v_mfma_f32_16x16x32_bf16 v[124:127], v[136:139], v[190:193], v[124:127]
	v_mfma_f32_16x16x32_bf16 v[120:123], v[160:163], v[190:193], v[120:123]
	v_mfma_f32_16x16x32_bf16 v[116:119], v[136:139], v[198:201], v[116:119]
	v_mfma_f32_16x16x32_bf16 v[112:115], v[160:163], v[198:201], v[112:115]
	v_mfma_f32_16x16x32_bf16 v[96:99], v[136:139], v[206:209], v[96:99]
	v_mfma_f32_16x16x32_bf16 v[88:91], v[160:163], v[206:209], v[88:91]
	v_mfma_f32_16x16x32_bf16 v[80:83], v[136:139], v[214:217], v[80:83]
	v_mfma_f32_16x16x32_bf16 v[72:75], v[160:163], v[214:217], v[72:75]
	s_setprio 0
	s_setprio 1
	v_mfma_f32_16x16x32_bf16 v[108:111], v[164:167], v[186:189], 0
	v_mfma_f32_16x16x32_bf16 v[104:107], v[178:181], v[186:189], 0
	v_mfma_f32_16x16x32_bf16 v[100:103], v[164:167], v[194:197], 0
	v_mfma_f32_16x16x32_bf16 v[92:95], v[178:181], v[194:197], 0
	v_mfma_f32_16x16x32_bf16 v[84:87], v[164:167], v[202:205], 0
	v_mfma_f32_16x16x32_bf16 v[76:79], v[178:181], v[202:205], 0
	v_mfma_f32_16x16x32_bf16 v[68:71], v[164:167], v[210:213], 0
	v_mfma_f32_16x16x32_bf16 v[64:67], v[178:181], v[210:213], 0
	v_mfma_f32_16x16x32_bf16 v[108:111], v[174:177], v[190:193], v[108:111]
	v_mfma_f32_16x16x32_bf16 v[104:107], v[182:185], v[190:193], v[104:107]
	v_mfma_f32_16x16x32_bf16 v[100:103], v[174:177], v[198:201], v[100:103]
	v_mfma_f32_16x16x32_bf16 v[92:95], v[182:185], v[198:201], v[92:95]
	v_mfma_f32_16x16x32_bf16 v[84:87], v[174:177], v[206:209], v[84:87]
	v_mfma_f32_16x16x32_bf16 v[76:79], v[182:185], v[206:209], v[76:79]
	v_mfma_f32_16x16x32_bf16 v[68:71], v[174:177], v[214:217], v[68:71]
	v_mfma_f32_16x16x32_bf16 v[64:67], v[182:185], v[214:217], v[64:67]
	s_setprio 0
	s_barrier
	s_add_i32 s4, s48, s37
	v_lshl_add_u64 v[218:219], s[24:25], 0, v[148:149]
	s_mov_b32 m0, s4
	ds_read_b128 v[186:189], v173 offset:16384
	ds_read_b128 v[190:193], v173 offset:17408
	ds_read_b128 v[194:197], v173 offset:18432
	ds_read_b128 v[198:201], v173 offset:19456
	ds_read_b128 v[202:205], v173 offset:20480
	ds_read_b128 v[206:209], v173 offset:21504
	ds_read_b128 v[210:213], v173 offset:22528
	ds_read_b128 v[214:217], v173 offset:23552
	global_load_lds_dwordx4 v[218:219], off
	s_add_i32 m0, s4, 0x2000
	s_add_u32 s64, s24, 0x40000
	v_lshl_add_u64 v[220:221], s[24:25], 0, v[144:145]
	s_addc_u32 s65, s25, 0
	s_add_i32 s4, s49, s37
	global_load_lds_dwordx4 v[220:221], off
	v_lshl_add_u64 v[222:223], s[64:65], 0, v[148:149]
	s_mov_b32 m0, s4
	s_nop 0
	global_load_lds_dwordx4 v[222:223], off
	v_lshl_add_u64 v[222:223], s[64:65], 0, v[144:145]
	s_add_i32 m0, s4, 0x2000
	s_nop 0
	global_load_lds_dwordx4 v[222:223], off
	v_lshl_add_u64 v[222:223], s[28:29], 0, v[150:151]
	s_mov_b32 m0, s38
	s_nop 0
	global_load_lds_dwordx4 v[222:223], off
	v_lshl_add_u64 v[222:223], s[28:29], 0, v[146:147]
	s_mov_b32 m0, s39
	s_nop 0
	global_load_lds_dwordx4 v[222:223], off
	s_waitcnt vmcnt(8)
	s_waitcnt lgkmcnt(0)
	s_barrier
; #define PG8_STAGE(bufoff, gbase, voff) do { _Pragma("unroll") for (int _i = 0; _i < 2; ++_i) \
;         __builtin_amdgcn_global_load_lds((const unsigned*)((const char*)(gbase) + (voff)[_i]), (LAS unsigned*)(lds + (bufoff) + ldsw + _i * 8192), 16, 0, 0); } while (0)
; #define PG8_LDA(dst, b, h) do { _Pragma("unroll") for (int m = 0; m < 4; ++m) _Pragma("unroll") for (int k = 0; k < 2; ++k) dst[m][k] = *(const LAS bf16x8*)(lds + PG8_SA(b, h) + aoff + m * 2048 + k * 1024); } while (0)
; #define PG8_LDB(dst, b, h) do { _Pragma("unroll") for (int n = 0; n < 2; ++n) _Pragma("unroll") for (int k = 0; k < 2; ++k) dst[n][k] = *(const LAS bf16x8*)(lds + PG8_SB(b, h) + boff + n * 2048 + k * 1024); } while (0)
; #define PG8_MMA(ai, bj, At, Bt) do { __builtin_amdgcn_s_setprio(1); _Pragma("unroll") for (int m = 0; m < 4; ++m) _Pragma("unroll") for (int n = 0; n < 2; ++n) _Pragma("unroll") for (int k = 0; k < 2; ++k) \
;         acc[ai][bj][m][n] = __builtin_amdgcn_mfma_f32_16x16x32_bf16(Bt[n][k], At[m][k], acc[ai][bj][m][n], 0, 0, 0); __builtin_amdgcn_s_setprio(0); } while (0)
; #define PG8_WAIT_V(n) asm volatile("s_waitcnt vmcnt(" #n ")" ::: "memory")
; #define PG8_WAIT_L(n) asm volatile("s_waitcnt lgkmcnt(" #n ")" ::: "memory")
; #define PG8_BAR __builtin_amdgcn_s_barrier()
; #define PG8_SCHED __builtin_amdgcn_sched_barrier(0)
; template <class Epi, bool ALIGN_EPI = true, bool SP2 = true>
; __device__ __forceinline__ void gemm_phase(LAS unsigned char* lds, const Gemm g, const StaticOrder& S, const Epi& E) {
;     ...
;             PG8_WAIT_V(8); PG8_WAIT_L(0); PG8_BAR; PG8_MMA(1, 0, At, B0); PG8_MMA(1, 1, At, B1); PG8_BAR; PG8_SCHED;
;             PG8_LDB(B0, 1, 0); PG8_LDB(B1, 1, 1); PG8_SCHED; PG8_LDA(At, 1, 0); PG8_STAGE(PG8_SA(0, 1), a2 + hstepA, voffA);
;             PG8_WAIT_V(8); PG8_WAIT_L(0); PG8_BAR; PG8_MMA(0, 0, At, B0); PG8_MMA(0, 1, At, B1); PG8_BAR; PG8_SCHED;
	s_setprio 1
	s_waitcnt lgkmcnt(0)
	v_mfma_f32_16x16x32_bf16 v[60:63], v[132:135], v[186:189], 0
	v_mfma_f32_16x16x32_bf16 v[56:59], v[140:143], v[186:189], 0
	v_mfma_f32_16x16x32_bf16 v[48:51], v[132:135], v[194:197], 0
	v_mfma_f32_16x16x32_bf16 v[40:43], v[140:143], v[194:197], 0
	v_mfma_f32_16x16x32_bf16 v[32:35], v[132:135], v[202:205], 0
	v_mfma_f32_16x16x32_bf16 v[24:27], v[140:143], v[202:205], 0
	v_mfma_f32_16x16x32_bf16 v[16:19], v[132:135], v[210:213], 0
	v_mfma_f32_16x16x32_bf16 v[8:11], v[140:143], v[210:213], 0
	v_mfma_f32_16x16x32_bf16 v[60:63], v[136:139], v[190:193], v[60:63]
	v_mfma_f32_16x16x32_bf16 v[56:59], v[160:163], v[190:193], v[56:59]
	v_mfma_f32_16x16x32_bf16 v[48:51], v[136:139], v[198:201], v[48:51]
	v_mfma_f32_16x16x32_bf16 v[40:43], v[160:163], v[198:201], v[40:43]
	v_mfma_f32_16x16x32_bf16 v[32:35], v[136:139], v[206:209], v[32:35]
	v_mfma_f32_16x16x32_bf16 v[24:27], v[160:163], v[206:209], v[24:27]
	v_mfma_f32_16x16x32_bf16 v[16:19], v[136:139], v[214:217], v[16:19]
	v_mfma_f32_16x16x32_bf16 v[8:11], v[160:163], v[214:217], v[8:11]
	s_setprio 0
	s_setprio 1
	v_mfma_f32_16x16x32_bf16 v[52:55], v[164:167], v[186:189], 0
	v_mfma_f32_16x16x32_bf16 v[44:47], v[178:181], v[186:189], 0
	v_mfma_f32_16x16x32_bf16 v[36:39], v[164:167], v[194:197], 0
	v_mfma_f32_16x16x32_bf16 v[28:31], v[178:181], v[194:197], 0
	v_mfma_f32_16x16x32_bf16 v[20:23], v[164:167], v[202:205], 0
	v_mfma_f32_16x16x32_bf16 v[12:15], v[178:181], v[202:205], 0
	v_mfma_f32_16x16x32_bf16 v[4:7], v[164:167], v[210:213], 0
	v_mfma_f32_16x16x32_bf16 v[0:3], v[178:181], v[210:213], 0
	v_mfma_f32_16x16x32_bf16 v[52:55], v[174:177], v[190:193], v[52:55]
	v_mfma_f32_16x16x32_bf16 v[44:47], v[182:185], v[190:193], v[44:47]
	v_mfma_f32_16x16x32_bf16 v[36:39], v[174:177], v[198:201], v[36:39]
	v_mfma_f32_16x16x32_bf16 v[28:31], v[182:185], v[198:201], v[28:31]
	v_mfma_f32_16x16x32_bf16 v[20:23], v[174:177], v[206:209], v[20:23]
	v_mfma_f32_16x16x32_bf16 v[12:15], v[182:185], v[206:209], v[12:15]
	v_mfma_f32_16x16x32_bf16 v[4:7], v[174:177], v[214:217], v[4:7]
	v_mfma_f32_16x16x32_bf16 v[0:3], v[182:185], v[214:217], v[0:3]
	s_setprio 0
	s_barrier
	s_add_i32 s4, 0, 0x18000
	s_add_i32 s63, 0, 0x1c000
	v_add_u32_e32 v160, s4, v169
	v_add_u32_e32 v182, s63, v169
	ds_read_b128 v[132:135], v160
	ds_read_b128 v[136:139], v160 offset:1024
	ds_read_b128 v[140:143], v160 offset:2048
	ds_read_b128 v[160:163], v160 offset:3072
	ds_read_b128 v[164:167], v182
	ds_read_b128 v[174:177], v182 offset:1024
	ds_read_b128 v[178:181], v182 offset:2048
	ds_read_b128 v[182:185], v182 offset:3072
	s_add_u32 s28, s28, 0x40000
	s_addc_u32 s29, s29, 0
	s_mov_b32 m0, s40
	v_lshl_add_u64 v[222:223], s[28:29], 0, v[150:151]
	ds_read_b128 v[186:189], v173 offset:32768
	ds_read_b128 v[190:193], v173 offset:33792
	ds_read_b128 v[194:197], v173 offset:34816
	ds_read_b128 v[198:201], v173 offset:35840
	ds_read_b128 v[202:205], v173 offset:36864
	ds_read_b128 v[206:209], v173 offset:37888
	ds_read_b128 v[210:213], v173 offset:38912
	ds_read_b128 v[214:217], v173 offset:39936
	global_load_lds_dwordx4 v[222:223], off
	v_lshl_add_u64 v[222:223], s[28:29], 0, v[146:147]
	s_mov_b32 m0, s41
	s_nop 0
	global_load_lds_dwordx4 v[222:223], off
	s_waitcnt vmcnt(8)
	s_waitcnt lgkmcnt(0)
	s_barrier
	s_setprio 1
	s_waitcnt lgkmcnt(0)
	v_mfma_f32_16x16x32_bf16 v[124:127], v[132:135], v[186:189], v[124:127]
	v_mfma_f32_16x16x32_bf16 v[120:123], v[140:143], v[186:189], v[120:123]
	v_mfma_f32_16x16x32_bf16 v[116:119], v[132:135], v[194:197], v[116:119]
	v_mfma_f32_16x16x32_bf16 v[112:115], v[140:143], v[194:197], v[112:115]
	v_mfma_f32_16x16x32_bf16 v[96:99], v[132:135], v[202:205], v[96:99]
	v_mfma_f32_16x16x32_bf16 v[88:91], v[140:143], v[202:205], v[88:91]
	v_mfma_f32_16x16x32_bf16 v[80:83], v[132:135], v[210:213], v[80:83]
	v_mfma_f32_16x16x32_bf16 v[72:75], v[140:143], v[210:213], v[72:75]
	v_mfma_f32_16x16x32_bf16 v[124:127], v[136:139], v[190:193], v[124:127]
	v_mfma_f32_16x16x32_bf16 v[120:123], v[160:163], v[190:193], v[120:123]
	v_mfma_f32_16x16x32_bf16 v[116:119], v[136:139], v[198:201], v[116:119]
	v_mfma_f32_16x16x32_bf16 v[112:115], v[160:163], v[198:201], v[112:115]
	v_mfma_f32_16x16x32_bf16 v[96:99], v[136:139], v[206:209], v[96:99]
	v_mfma_f32_16x16x32_bf16 v[88:91], v[160:163], v[206:209], v[88:91]
	v_mfma_f32_16x16x32_bf16 v[80:83], v[136:139], v[214:217], v[80:83]
	v_mfma_f32_16x16x32_bf16 v[72:75], v[160:163], v[214:217], v[72:75]
	s_setprio 0
	s_setprio 1
	v_mfma_f32_16x16x32_bf16 v[108:111], v[164:167], v[186:189], v[108:111]
	v_mfma_f32_16x16x32_bf16 v[104:107], v[178:181], v[186:189], v[104:107]
	v_mfma_f32_16x16x32_bf16 v[100:103], v[164:167], v[194:197], v[100:103]
	v_mfma_f32_16x16x32_bf16 v[92:95], v[178:181], v[194:197], v[92:95]
	v_mfma_f32_16x16x32_bf16 v[84:87], v[164:167], v[202:205], v[84:87]
	v_mfma_f32_16x16x32_bf16 v[76:79], v[178:181], v[202:205], v[76:79]
	v_mfma_f32_16x16x32_bf16 v[68:71], v[164:167], v[210:213], v[68:71]
	v_mfma_f32_16x16x32_bf16 v[64:67], v[178:181], v[210:213], v[64:67]
	v_mfma_f32_16x16x32_bf16 v[108:111], v[174:177], v[190:193], v[108:111]
	v_mfma_f32_16x16x32_bf16 v[104:107], v[182:185], v[190:193], v[104:107]
	v_mfma_f32_16x16x32_bf16 v[100:103], v[174:177], v[198:201], v[100:103]
	v_mfma_f32_16x16x32_bf16 v[92:95], v[182:185], v[198:201], v[92:95]
	v_mfma_f32_16x16x32_bf16 v[84:87], v[174:177], v[206:209], v[84:87]
	v_mfma_f32_16x16x32_bf16 v[76:79], v[182:185], v[206:209], v[76:79]
	v_mfma_f32_16x16x32_bf16 v[68:71], v[174:177], v[214:217], v[68:71]
	v_mfma_f32_16x16x32_bf16 v[64:67], v[182:185], v[214:217], v[64:67]
	s_setprio 0
	s_barrier
; #define PG8_STAGE(bufoff, gbase, voff) do { _Pragma("unroll") for (int _i = 0; _i < 2; ++_i) \
;         __builtin_amdgcn_global_load_lds((const unsigned*)((const char*)(gbase) + (voff)[_i]), (LAS unsigned*)(lds + (bufoff) + ldsw + _i * 8192), 16, 0, 0); } while (0)
; #define PG8_LDA(dst, b, h) do { _Pragma("unroll") for (int m = 0; m < 4; ++m) _Pragma("unroll") for (int k = 0; k < 2; ++k) dst[m][k] = *(const LAS bf16x8*)(lds + PG8_SA(b, h) + aoff + m * 2048 + k * 1024); } while (0)
; #define PG8_MMA(ai, bj, At, Bt) do { __builtin_amdgcn_s_setprio(1); _Pragma("unroll") for (int m = 0; m < 4; ++m) _Pragma("unroll") for (int n = 0; n < 2; ++n) _Pragma("unroll") for (int k = 0; k < 2; ++k) \
;         acc[ai][bj][m][n] = __builtin_amdgcn_mfma_f32_16x16x32_bf16(Bt[n][k], At[m][k], acc[ai][bj][m][n], 0, 0, 0); __builtin_amdgcn_s_setprio(0); } while (0)
; #define PG8_WAIT_V(n) asm volatile("s_waitcnt vmcnt(" #n ")" ::: "memory")
; #define PG8_WAIT_L(n) asm volatile("s_waitcnt lgkmcnt(" #n ")" ::: "memory")
; #define PG8_BAR __builtin_amdgcn_s_barrier()
; #define PG8_SCHED __builtin_amdgcn_sched_barrier(0)
; template <class Epi, bool ALIGN_EPI = true, bool SP2 = true>
; __device__ __forceinline__ void gemm_phase(LAS unsigned char* lds, const Gemm g, const StaticOrder& S, const Epi& E) {
;     ...
;             PG8_LDA(At, 1, 1); PG8_STAGE(PG8_SB(1, 0), b3, voffB); PG8_STAGE(PG8_SB(1, 1), b3 + hstepB, voffB); PG8_STAGE(PG8_SA(1, 0), a3, voffA);
;             PG8_WAIT_V(8); PG8_WAIT_L(0); PG8_BAR; PG8_MMA(1, 0, At, B0); PG8_MMA(1, 1, At, B1); PG8_BAR; PG8_SCHED;
	s_add_i32 s4, s4, s37
	v_lshl_add_u64 v[218:219], v[218:219], 0, s[8:9]
	s_mov_b32 m0, s4
	ds_read_b128 v[186:189], v173 offset:49152
	ds_read_b128 v[190:193], v173 offset:50176
	ds_read_b128 v[194:197], v173 offset:51200
	ds_read_b128 v[198:201], v173 offset:52224
	ds_read_b128 v[202:205], v173 offset:53248
	ds_read_b128 v[206:209], v173 offset:54272
	ds_read_b128 v[210:213], v173 offset:55296
	ds_read_b128 v[214:217], v173 offset:56320
	global_load_lds_dwordx4 v[218:219], off
	s_add_i32 m0, s4, 0x2000
	s_add_u32 s24, s24, 0x40080
	v_lshl_add_u64 v[218:219], v[220:221], 0, s[8:9]
	s_addc_u32 s25, s25, 0
	s_add_i32 s4, s63, s37
	global_load_lds_dwordx4 v[218:219], off
	v_lshl_add_u64 v[218:219], s[24:25], 0, v[148:149]
	s_mov_b32 m0, s4
	s_nop 0
	global_load_lds_dwordx4 v[218:219], off
	v_lshl_add_u64 v[218:219], s[24:25], 0, v[144:145]
	s_add_i32 m0, s4, 0x2000
	s_nop 0
	global_load_lds_dwordx4 v[218:219], off
	v_lshl_add_u64 v[218:219], s[22:23], 0, v[150:151]
	s_mov_b32 m0, s46
	s_nop 0
	global_load_lds_dwordx4 v[218:219], off
	v_lshl_add_u64 v[218:219], s[22:23], 0, v[146:147]
	s_mov_b32 m0, s47
	s_nop 0
	global_load_lds_dwordx4 v[218:219], off
	s_waitcnt vmcnt(8)
	s_waitcnt lgkmcnt(0)
	s_barrier
	s_setprio 1
	s_waitcnt lgkmcnt(0)
	v_mfma_f32_16x16x32_bf16 v[60:63], v[132:135], v[186:189], v[60:63]
	v_mfma_f32_16x16x32_bf16 v[56:59], v[140:143], v[186:189], v[56:59]
	v_mfma_f32_16x16x32_bf16 v[48:51], v[132:135], v[194:197], v[48:51]
	v_mfma_f32_16x16x32_bf16 v[40:43], v[140:143], v[194:197], v[40:43]
	v_mfma_f32_16x16x32_bf16 v[32:35], v[132:135], v[202:205], v[32:35]
	v_mfma_f32_16x16x32_bf16 v[24:27], v[140:143], v[202:205], v[24:27]
	v_mfma_f32_16x16x32_bf16 v[16:19], v[132:135], v[210:213], v[16:19]
	v_mfma_f32_16x16x32_bf16 v[8:11], v[140:143], v[210:213], v[8:11]
	v_mfma_f32_16x16x32_bf16 v[60:63], v[136:139], v[190:193], v[60:63]
	v_mfma_f32_16x16x32_bf16 v[56:59], v[160:163], v[190:193], v[56:59]
	v_mfma_f32_16x16x32_bf16 v[48:51], v[136:139], v[198:201], v[48:51]
	v_mfma_f32_16x16x32_bf16 v[40:43], v[160:163], v[198:201], v[40:43]
	v_mfma_f32_16x16x32_bf16 v[32:35], v[136:139], v[206:209], v[32:35]
	v_mfma_f32_16x16x32_bf16 v[24:27], v[160:163], v[206:209], v[24:27]
	v_mfma_f32_16x16x32_bf16 v[16:19], v[136:139], v[214:217], v[16:19]
	v_mfma_f32_16x16x32_bf16 v[8:11], v[160:163], v[214:217], v[8:11]
	s_setprio 0
	s_setprio 1
	v_mfma_f32_16x16x32_bf16 v[52:55], v[164:167], v[186:189], v[52:55]
	v_mfma_f32_16x16x32_bf16 v[44:47], v[178:181], v[186:189], v[44:47]
	v_mfma_f32_16x16x32_bf16 v[36:39], v[164:167], v[194:197], v[36:39]
	v_mfma_f32_16x16x32_bf16 v[28:31], v[178:181], v[194:197], v[28:31]
	v_mfma_f32_16x16x32_bf16 v[20:23], v[164:167], v[202:205], v[20:23]
	v_mfma_f32_16x16x32_bf16 v[12:15], v[178:181], v[202:205], v[12:15]
	v_mfma_f32_16x16x32_bf16 v[4:7], v[164:167], v[210:213], v[4:7]
	v_mfma_f32_16x16x32_bf16 v[0:3], v[178:181], v[210:213], v[0:3]
	v_mfma_f32_16x16x32_bf16 v[52:55], v[174:177], v[190:193], v[52:55]
	v_mfma_f32_16x16x32_bf16 v[44:47], v[182:185], v[190:193], v[44:47]
	v_mfma_f32_16x16x32_bf16 v[36:39], v[174:177], v[198:201], v[36:39]
	v_mfma_f32_16x16x32_bf16 v[28:31], v[182:185], v[198:201], v[28:31]
	v_mfma_f32_16x16x32_bf16 v[20:23], v[174:177], v[206:209], v[20:23]
	v_mfma_f32_16x16x32_bf16 v[12:15], v[182:185], v[206:209], v[12:15]
	v_mfma_f32_16x16x32_bf16 v[4:7], v[174:177], v[214:217], v[4:7]
	v_mfma_f32_16x16x32_bf16 v[0:3], v[182:185], v[214:217], v[0:3]
	s_setprio 0
	s_barrier
	s_add_u32 s20, s20, 0x100
	s_addc_u32 s21, s21, 0
	s_cmp_gt_u32 s62, 13
	s_mov_b32 s4, s62
